# adds hand-scheduled residual epilogue (24 loads in flight, counted waits) and weights-conversion rows loaded 32 at a time
# speedup vs baseline: 1.0308x; 1.0065x over previous
; __device__ __forceinline__ void weights_phase(const Params& P, LAS float* scr, int lane, int it0, int it1, int w, int nw) {
;     ...
; #pragma unroll 8
;         for (int i = 0; i < 32; ++i) { const int kk = 2 * i + (lane >> 5); scr[kk * 33 + (lane & 31)] = jb.src[(size_t)(k0 + kk) * jb.ld + c0 + (lane & 31)]; }
.LBB0_25:
	s_or_b64 exec, exec, s[4:5]
	v_ashrrev_i32_e32 v21, 31, v20
	v_lshlrev_b32_e32 v18, 6, v2
	v_ashrrev_i32_e32 v3, 31, v1
	s_waitcnt vmcnt(0)
	v_lshl_add_u64 v[4:5], v[20:21], 2, v[4:5]
	v_lshl_add_u64 v[20:21], v[4:5], 0, v[16:17]
	v_mov_b32_e32 v2, v1
	v_mov_b32_e32 v4, v1
	v_mov_b32_e32 v5, v3
	v_or_b32_e32 v1, v9, v18
	v_or_b32_e32 v22, v10, v18
	s_mov_b32 s4, 1
	s_mov_b32 s5, 0
	s_mov_b32 s12, 32
	v_lshlrev_b32_e32 v27, 2, v2
	v_mul_lo_u32 v28, v22, v27
	v_lshlrev_b32_e32 v27, 1, v27
	v_mov_b32_e32 v29, 0
	v_mul_u32_u24_e32 v66, 0x84, v10
	v_add_u32_e32 v66, v66, v14
	v_lshl_add_u64 v[30:31], v[28:29], 0, v[20:21]
	global_load_dword v32, v[30:31], off
	v_add_u32_e32 v28, v28, v27
	v_lshl_add_u64 v[64:65], v[28:29], 0, v[20:21]
	global_load_dword v33, v[64:65], off
	v_add_u32_e32 v28, v28, v27
	v_lshl_add_u64 v[30:31], v[28:29], 0, v[20:21]
	global_load_dword v34, v[30:31], off
	v_add_u32_e32 v28, v28, v27
	v_lshl_add_u64 v[64:65], v[28:29], 0, v[20:21]
	global_load_dword v35, v[64:65], off
	v_add_u32_e32 v28, v28, v27
	v_lshl_add_u64 v[30:31], v[28:29], 0, v[20:21]
	global_load_dword v36, v[30:31], off
	v_add_u32_e32 v28, v28, v27
	v_lshl_add_u64 v[64:65], v[28:29], 0, v[20:21]
	global_load_dword v37, v[64:65], off
	v_add_u32_e32 v28, v28, v27
	v_lshl_add_u64 v[30:31], v[28:29], 0, v[20:21]
	global_load_dword v38, v[30:31], off
	v_add_u32_e32 v28, v28, v27
	v_lshl_add_u64 v[64:65], v[28:29], 0, v[20:21]
	global_load_dword v39, v[64:65], off
	v_add_u32_e32 v28, v28, v27
	v_lshl_add_u64 v[30:31], v[28:29], 0, v[20:21]
	global_load_dword v40, v[30:31], off
	v_add_u32_e32 v28, v28, v27
	v_lshl_add_u64 v[64:65], v[28:29], 0, v[20:21]
	global_load_dword v41, v[64:65], off
	v_add_u32_e32 v28, v28, v27
	v_lshl_add_u64 v[30:31], v[28:29], 0, v[20:21]
	global_load_dword v42, v[30:31], off
	v_add_u32_e32 v28, v28, v27
	v_lshl_add_u64 v[64:65], v[28:29], 0, v[20:21]
	global_load_dword v43, v[64:65], off
	v_add_u32_e32 v28, v28, v27
	v_lshl_add_u64 v[30:31], v[28:29], 0, v[20:21]
	global_load_dword v44, v[30:31], off
	v_add_u32_e32 v28, v28, v27
	v_lshl_add_u64 v[64:65], v[28:29], 0, v[20:21]
	global_load_dword v45, v[64:65], off
	v_add_u32_e32 v28, v28, v27
	v_lshl_add_u64 v[30:31], v[28:29], 0, v[20:21]
	global_load_dword v46, v[30:31], off
	v_add_u32_e32 v28, v28, v27
	v_lshl_add_u64 v[64:65], v[28:29], 0, v[20:21]
	global_load_dword v47, v[64:65], off
	v_add_u32_e32 v28, v28, v27
	v_lshl_add_u64 v[30:31], v[28:29], 0, v[20:21]
	global_load_dword v48, v[30:31], off
	v_add_u32_e32 v28, v28, v27
	v_lshl_add_u64 v[64:65], v[28:29], 0, v[20:21]
	global_load_dword v49, v[64:65], off
	v_add_u32_e32 v28, v28, v27
	v_lshl_add_u64 v[30:31], v[28:29], 0, v[20:21]
	global_load_dword v50, v[30:31], off
	v_add_u32_e32 v28, v28, v27
	v_lshl_add_u64 v[64:65], v[28:29], 0, v[20:21]
	global_load_dword v51, v[64:65], off
	v_add_u32_e32 v28, v28, v27
	v_lshl_add_u64 v[30:31], v[28:29], 0, v[20:21]
	global_load_dword v52, v[30:31], off
	v_add_u32_e32 v28, v28, v27
	v_lshl_add_u64 v[64:65], v[28:29], 0, v[20:21]
	global_load_dword v53, v[64:65], off
	v_add_u32_e32 v28, v28, v27
	v_lshl_add_u64 v[30:31], v[28:29], 0, v[20:21]
	global_load_dword v54, v[30:31], off
	v_add_u32_e32 v28, v28, v27
	v_lshl_add_u64 v[64:65], v[28:29], 0, v[20:21]
	global_load_dword v55, v[64:65], off
	v_add_u32_e32 v28, v28, v27
	v_lshl_add_u64 v[30:31], v[28:29], 0, v[20:21]
	global_load_dword v56, v[30:31], off
	v_add_u32_e32 v28, v28, v27
	v_lshl_add_u64 v[64:65], v[28:29], 0, v[20:21]
	global_load_dword v57, v[64:65], off
	v_add_u32_e32 v28, v28, v27
	v_lshl_add_u64 v[30:31], v[28:29], 0, v[20:21]
	global_load_dword v58, v[30:31], off
	v_add_u32_e32 v28, v28, v27
	v_lshl_add_u64 v[64:65], v[28:29], 0, v[20:21]
	global_load_dword v59, v[64:65], off
	v_add_u32_e32 v28, v28, v27
	v_lshl_add_u64 v[30:31], v[28:29], 0, v[20:21]
	global_load_dword v60, v[30:31], off
	v_add_u32_e32 v28, v28, v27
	v_lshl_add_u64 v[64:65], v[28:29], 0, v[20:21]
	global_load_dword v61, v[64:65], off
	v_add_u32_e32 v28, v28, v27
	v_lshl_add_u64 v[30:31], v[28:29], 0, v[20:21]
	global_load_dword v62, v[30:31], off
	v_add_u32_e32 v28, v28, v27
	v_lshl_add_u64 v[64:65], v[28:29], 0, v[20:21]
	global_load_dword v63, v[64:65], off
	s_waitcnt vmcnt(31)
; #define LAS __attribute__((address_space(3)))
; __device__ __forceinline__ void weights_phase(const Params& P, LAS float* scr, int lane, int it0, int it1, int w, int nw) {
;     ...
;         for (int i = 0; i < 32; ++i) { const int kk = 2 * i + (lane >> 5); scr[kk * 33 + (lane & 31)] = jb.src[(size_t)(k0 + kk) * jb.ld + c0 + (lane & 31)]; }
;         asm volatile("s_waitcnt lgkmcnt(0)" ::: "memory");
;         const int c = lane & 7;
; #pragma unroll
;         for (int j = 0; j < 4; ++j) { const int n = (lane >> 3) + 8 * j; const LAS float* s = scr + (8 * c) * 33 + n;
;             u32x4 o; o.x = cvt_pk_bf16(s[0 * 33], s[1 * 33]); o.y = cvt_pk_bf16(s[2 * 33], s[3 * 33]); o.z = cvt_pk_bf16(s[4 * 33], s[5 * 33]); o.w = cvt_pk_bf16(s[6 * 33], s[7 * 33]);
;             *(u32x4*)(jb.dst + (size_t)(n0 + n) * jb.K + k0 + 8 * c) = o; }
;         asm volatile("s_waitcnt lgkmcnt(0)" ::: "memory");
	ds_write_b32 v66, v32
	s_waitcnt vmcnt(30)
	ds_write_b32 v66, v33 offset:264
	s_waitcnt vmcnt(29)
	ds_write_b32 v66, v34 offset:528
	s_waitcnt vmcnt(28)
	ds_write_b32 v66, v35 offset:792
	s_waitcnt vmcnt(27)
	ds_write_b32 v66, v36 offset:1056
	s_waitcnt vmcnt(26)
	ds_write_b32 v66, v37 offset:1320
	s_waitcnt vmcnt(25)
	ds_write_b32 v66, v38 offset:1584
	s_waitcnt vmcnt(24)
	ds_write_b32 v66, v39 offset:1848
	s_waitcnt vmcnt(23)
	ds_write_b32 v66, v40 offset:2112
	s_waitcnt vmcnt(22)
	ds_write_b32 v66, v41 offset:2376
	s_waitcnt vmcnt(21)
	ds_write_b32 v66, v42 offset:2640
	s_waitcnt vmcnt(20)
	ds_write_b32 v66, v43 offset:2904
	s_waitcnt vmcnt(19)
	ds_write_b32 v66, v44 offset:3168
	s_waitcnt vmcnt(18)
	ds_write_b32 v66, v45 offset:3432
	s_waitcnt vmcnt(17)
	ds_write_b32 v66, v46 offset:3696
	s_waitcnt vmcnt(16)
	ds_write_b32 v66, v47 offset:3960
	s_waitcnt vmcnt(15)
	ds_write_b32 v66, v48 offset:4224
	s_waitcnt vmcnt(14)
	ds_write_b32 v66, v49 offset:4488
	s_waitcnt vmcnt(13)
	ds_write_b32 v66, v50 offset:4752
	s_waitcnt vmcnt(12)
	ds_write_b32 v66, v51 offset:5016
	s_waitcnt vmcnt(11)
	ds_write_b32 v66, v52 offset:5280
	s_waitcnt vmcnt(10)
	ds_write_b32 v66, v53 offset:5544
	s_waitcnt vmcnt(9)
	ds_write_b32 v66, v54 offset:5808
	s_waitcnt vmcnt(8)
	ds_write_b32 v66, v55 offset:6072
	s_waitcnt vmcnt(7)
	ds_write_b32 v66, v56 offset:6336
	s_waitcnt vmcnt(6)
	ds_write_b32 v66, v57 offset:6600
	s_waitcnt vmcnt(5)
	ds_write_b32 v66, v58 offset:6864
	s_waitcnt vmcnt(4)
	ds_write_b32 v66, v59 offset:7128
	s_waitcnt vmcnt(3)
	ds_write_b32 v66, v60 offset:7392
	s_waitcnt vmcnt(2)
	ds_write_b32 v66, v61 offset:7656
	s_waitcnt vmcnt(1)
	ds_write_b32 v66, v62 offset:7920
	s_waitcnt vmcnt(0)
	ds_write_b32 v66, v63 offset:8184
	s_waitcnt lgkmcnt(0)
	v_ashrrev_i32_e32 v19, 31, v18
	v_lshl_add_u64 v[2:3], v[18:19], 1, v[6:7]
	ds_read2_b32 v[6:7], v15 offset0:33 offset1:41
	ds_read2_b32 v[18:19], v15 offset1:8
	ds_read2_b32 v[20:21], v15 offset0:66 offset1:74
	ds_read2_b32 v[28:29], v15 offset0:99 offset1:107
	ds_read2_b32 v[30:31], v15 offset0:132 offset1:140
	ds_read2_b32 v[32:33], v15 offset0:165 offset1:173
	ds_read2_b32 v[34:35], v15 offset0:198 offset1:206
	ds_read2_b32 v[36:37], v15 offset0:231 offset1:239
	v_or_b32_e32 v1, v26, v11
	v_lshl_add_u64 v[38:39], v[2:3], 0, v[12:13]
	v_mad_i64_i32 v[40:41], s[4:5], v1, v0, 0
	s_waitcnt lgkmcnt(6)
	v_cvt_pk_bf16_f32 v2, v18, v6
	s_waitcnt lgkmcnt(4)
	v_cvt_pk_bf16_f32 v3, v20, v28
	s_waitcnt lgkmcnt(2)
	v_cvt_pk_bf16_f32 v4, v30, v32
	s_waitcnt lgkmcnt(0)
	v_cvt_pk_bf16_f32 v5, v34, v36
	v_lshl_add_u64 v[40:41], v[40:41], 1, v[38:39]
	global_store_dwordx4 v[40:41], v[2:5], off
	v_or_b32_e32 v1, v26, v23
	v_add_u32_e32 v8, s62, v8
	v_cvt_pk_bf16_f32 v2, v19, v7
	v_cvt_pk_bf16_f32 v3, v21, v29
	v_cvt_pk_bf16_f32 v4, v31, v33
	v_cvt_pk_bf16_f32 v5, v35, v37
	ds_read2_b32 v[18:19], v15 offset0:16 offset1:24
	ds_read2_b32 v[20:21], v15 offset0:49 offset1:57
	ds_read2_b32 v[28:29], v15 offset0:82 offset1:90
	ds_read2_b32 v[30:31], v15 offset0:115 offset1:123
	ds_read2_b32 v[32:33], v15 offset0:148 offset1:156
	ds_read2_b32 v[34:35], v15 offset0:181 offset1:189
	ds_read2_b32 v[36:37], v15 offset0:214 offset1:222
	ds_read2_b32 v[40:41], v15 offset0:247 offset1:255
	v_mad_i64_i32 v[6:7], s[4:5], v1, v0, 0
	v_lshl_add_u64 v[6:7], v[6:7], 1, v[38:39]
	v_or_b32_e32 v1, v26, v24
	global_store_dwordx4 v[6:7], v[2:5], off
	v_mad_i64_i32 v[6:7], s[4:5], v1, v0, 0
	v_or_b32_e32 v1, v26, v25
	s_waitcnt lgkmcnt(6)
	v_cvt_pk_bf16_f32 v2, v18, v20
	s_waitcnt lgkmcnt(4)
	v_cvt_pk_bf16_f32 v3, v28, v30
	s_waitcnt lgkmcnt(2)
	v_cvt_pk_bf16_f32 v4, v32, v34
	s_waitcnt lgkmcnt(0)
	v_cvt_pk_bf16_f32 v5, v36, v40
	v_lshl_add_u64 v[6:7], v[6:7], 1, v[38:39]
	v_mad_i64_i32 v[0:1], s[4:5], v1, v0, 0
	global_store_dwordx4 v[6:7], v[2:5], off
	v_lshl_add_u64 v[0:1], v[0:1], 1, v[38:39]
	v_cmp_le_i32_e32 vcc, s3, v8
	v_cvt_pk_bf16_f32 v2, v19, v21
	v_cvt_pk_bf16_f32 v3, v29, v31
	v_cvt_pk_bf16_f32 v4, v33, v35
	v_cvt_pk_bf16_f32 v5, v37, v41
	global_store_dwordx4 v[0:1], v[2:5], off
	s_waitcnt lgkmcnt(0)
	s_or_b64 s[10:11], vcc, s[10:11]
	s_andn2_b64 exec, exec, s[10:11]
	s_cbranch_execnz .LBB0_17
	s_branch .LBB0_30

; #define PG8_STAGE(bufoff, gbase, voff) do { _Pragma("unroll") for (int _i = 0; _i < 2; ++_i) \
;         __builtin_amdgcn_global_load_lds((const unsigned*)((const char*)(gbase) + (voff)[_i]), (LAS unsigned*)(lds + (bufoff) + ldsw + _i * 8192), 16, 0, 0); } while (0)
; #define PG8_LDA(dst, b, h) do { _Pragma("unroll") for (int m = 0; m < 4; ++m) _Pragma("unroll") for (int k = 0; k < 2; ++k) dst[m][k] = *(const LAS bf16x8*)(lds + PG8_SA(b, h) + aoff + m * 2048 + k * 1024); } while (0)
; #define PG8_LDB(dst, b, h) do { _Pragma("unroll") for (int n = 0; n < 2; ++n) _Pragma("unroll") for (int k = 0; k < 2; ++k) dst[n][k] = *(const LAS bf16x8*)(lds + PG8_SB(b, h) + boff + n * 2048 + k * 1024); } while (0)
; #define PG8_MMA(ai, bj, At, Bt) do { __builtin_amdgcn_s_setprio(1); _Pragma("unroll") for (int m = 0; m < 4; ++m) _Pragma("unroll") for (int n = 0; n < 2; ++n) _Pragma("unroll") for (int k = 0; k < 2; ++k) \
;         acc[ai][bj][m][n] = __builtin_amdgcn_mfma_f32_16x16x32_bf16(Bt[n][k], At[m][k], acc[ai][bj][m][n], 0, 0, 0); __builtin_amdgcn_s_setprio(0); } while (0)
; #define PG8_WAIT_V(n) asm volatile("s_waitcnt vmcnt(" #n ")" ::: "memory")
; #define PG8_WAIT_L(n) asm volatile("s_waitcnt lgkmcnt(" #n ")" ::: "memory")
; #define PG8_BAR __builtin_amdgcn_s_barrier()
; #define PG8_SCHED __builtin_amdgcn_sched_barrier(0)
; template <class Epi>
; __device__ __forceinline__ void gemm_phase(LAS unsigned char* lds, const Gemm g, const StaticOrder& S, const Epi& E) {
;     ...
;             PG8_LDB(B0, 0, 0); PG8_SCHED; PG8_LDA(At, 0, 0); PG8_STAGE(PG8_SA(1, 1), a1 + hstepA, voffA);
;             PG8_WAIT_L(8); PG8_BAR; PG8_WAIT_L(0); PG8_MMA(0, 0, At, B0); PG8_BAR; PG8_SCHED;
;             PG8_LDB(B1, 0, 1); PG8_STAGE(PG8_SB(0, 0), b2, voffB);
;             PG8_BAR; PG8_WAIT_L(0); PG8_MMA(0, 1, At, B1); PG8_BAR;
;             PG8_LDA(At, 0, 1); PG8_STAGE(PG8_SA(0, 0), a2, voffA);
;             PG8_BAR; PG8_WAIT_L(0); PG8_MMA(1, 0, At, B0); PG8_BAR; PG8_SCHED;
;             PG8_STAGE(PG8_SB(0, 1), b2 + hstepB, voffB);
;             PG8_WAIT_V(6); PG8_BAR; PG8_MMA(1, 1, At, B1); PG8_BAR;
.LBB0_411:
	ds_read_b128 v[140:143], v149
	ds_read_b128 v[152:155], v149 offset:1024
	ds_read_b128 v[156:159], v149 offset:2048
	ds_read_b128 v[160:163], v149 offset:3072
	s_add_u32 s28, s26, 0x100
	s_addc_u32 s29, s27, 0
	s_cmp_eq_u32 s68, 40
	s_cselect_b32 s35, s11, s29
	s_cselect_b32 s34, s10, s28
	s_cselect_b32 s31, s13, s63
	s_cselect_b32 s30, s12, s49
	v_lshl_add_u64 v[144:145], s[26:27], 0, v[132:133]
	s_add_i32 m0, s36, 0xc000
	ds_read_b128 v[164:167], v150
	ds_read_b128 v[168:171], v150 offset:1024
	ds_read_b128 v[172:175], v150 offset:2048
	ds_read_b128 v[176:179], v150 offset:3072
	ds_read_b128 v[180:183], v150 offset:4096
	ds_read_b128 v[184:187], v150 offset:5120
	ds_read_b128 v[188:191], v150 offset:6144
	ds_read_b128 v[192:195], v150 offset:7168
	global_load_lds_dwordx4 v[144:145], off
	v_lshl_add_u64 v[144:145], s[26:27], 0, v[134:135]
	s_add_i32 m0, s36, 0xe000
	s_nop 0
	global_load_lds_dwordx4 v[144:145], off
	ds_read_b128 v[196:199], v151
	ds_read_b128 v[200:203], v151 offset:1024
	ds_read_b128 v[204:207], v151 offset:2048
	ds_read_b128 v[208:211], v151 offset:3072
	s_waitcnt lgkmcnt(0)
	s_barrier
	s_setprio 1
	v_mfma_f32_16x16x32_bf16 v[124:127], v[140:143], v[164:167], v[124:127]
	v_mfma_f32_16x16x32_bf16 v[120:123], v[156:159], v[164:167], v[120:123]
	v_mfma_f32_16x16x32_bf16 v[112:115], v[140:143], v[172:175], v[112:115]
	v_mfma_f32_16x16x32_bf16 v[104:107], v[156:159], v[172:175], v[104:107]
	v_mfma_f32_16x16x32_bf16 v[92:95], v[140:143], v[180:183], v[92:95]
	v_mfma_f32_16x16x32_bf16 v[88:91], v[156:159], v[180:183], v[88:91]
	v_mfma_f32_16x16x32_bf16 v[80:83], v[140:143], v[188:191], v[80:83]
	v_mfma_f32_16x16x32_bf16 v[72:75], v[156:159], v[188:191], v[72:75]
	v_mfma_f32_16x16x32_bf16 v[124:127], v[152:155], v[168:171], v[124:127]
	v_mfma_f32_16x16x32_bf16 v[120:123], v[160:163], v[168:171], v[120:123]
	v_mfma_f32_16x16x32_bf16 v[112:115], v[152:155], v[176:179], v[112:115]
	v_mfma_f32_16x16x32_bf16 v[104:107], v[160:163], v[176:179], v[104:107]
	v_mfma_f32_16x16x32_bf16 v[92:95], v[152:155], v[184:187], v[92:95]
	v_mfma_f32_16x16x32_bf16 v[88:91], v[160:163], v[184:187], v[88:91]
	v_mfma_f32_16x16x32_bf16 v[80:83], v[152:155], v[192:195], v[80:83]
	v_mfma_f32_16x16x32_bf16 v[72:75], v[160:163], v[192:195], v[72:75]
	v_mfma_f32_16x16x32_bf16 v[116:119], v[196:199], v[164:167], v[116:119]
	v_mfma_f32_16x16x32_bf16 v[108:111], v[204:207], v[164:167], v[108:111]
	v_mfma_f32_16x16x32_bf16 v[100:103], v[196:199], v[172:175], v[100:103]
	v_mfma_f32_16x16x32_bf16 v[96:99], v[204:207], v[172:175], v[96:99]
	v_mfma_f32_16x16x32_bf16 v[84:87], v[196:199], v[180:183], v[84:87]
	v_mfma_f32_16x16x32_bf16 v[76:79], v[204:207], v[180:183], v[76:79]
	v_mfma_f32_16x16x32_bf16 v[68:71], v[196:199], v[188:191], v[68:71]
	v_mfma_f32_16x16x32_bf16 v[64:67], v[204:207], v[188:191], v[64:67]
	v_mfma_f32_16x16x32_bf16 v[116:119], v[200:203], v[168:171], v[116:119]
	v_mfma_f32_16x16x32_bf16 v[108:111], v[208:211], v[168:171], v[108:111]
	v_mfma_f32_16x16x32_bf16 v[100:103], v[200:203], v[176:179], v[100:103]
	v_mfma_f32_16x16x32_bf16 v[96:99], v[208:211], v[176:179], v[96:99]
	v_mfma_f32_16x16x32_bf16 v[84:87], v[200:203], v[184:187], v[84:87]
	v_mfma_f32_16x16x32_bf16 v[76:79], v[208:211], v[184:187], v[76:79]
	v_mfma_f32_16x16x32_bf16 v[68:71], v[200:203], v[192:195], v[68:71]
	v_mfma_f32_16x16x32_bf16 v[64:67], v[208:211], v[192:195], v[64:67]
	s_setprio 0
	s_barrier
	s_nop 1
	ds_read_b128 v[164:167], v150 offset:16384
	ds_read_b128 v[168:171], v150 offset:17408
	ds_read_b128 v[172:175], v150 offset:18432
	ds_read_b128 v[176:179], v150 offset:19456
	ds_read_b128 v[180:183], v150 offset:20480
	ds_read_b128 v[184:187], v150 offset:21504
	ds_read_b128 v[188:191], v150 offset:22528
	ds_read_b128 v[192:195], v150 offset:23552
	s_add_i32 s26, s43, s7
	v_lshl_add_u64 v[144:145], s[30:31], 0, v[128:129]
	s_mov_b32 m0, s26
	s_nop 0
	global_load_lds_dwordx4 v[144:145], off
	v_lshl_add_u64 v[212:213], s[30:31], 0, v[130:131]
	s_add_i32 m0, s26, 0x2000
	s_nop 0
	global_load_lds_dwordx4 v[212:213], off
	s_mov_b32 m0, s36
	v_lshl_add_u64 v[214:215], s[34:35], 0, v[128:129]
	global_load_lds_dwordx4 v[214:215], off
	v_lshl_add_u64 v[216:217], s[34:35], 0, v[130:131]
	s_mov_b32 m0, s37
	s_nop 0
	global_load_lds_dwordx4 v[216:217], off
	s_add_u32 s26, s30, 0xb0000
	s_addc_u32 s27, s31, 0
	s_add_i32 s69, s44, s7
	v_lshl_add_u64 v[254:255], s[26:27], 0, v[128:129]
	s_mov_b32 m0, s69
	s_nop 0
	global_load_lds_dwordx4 v[254:255], off
	v_lshl_add_u64 v[254:255], s[26:27], 0, v[130:131]
	s_add_i32 m0, s69, 0x2000
	s_nop 0
	global_load_lds_dwordx4 v[254:255], off
	s_waitcnt vmcnt(6)
	s_waitcnt lgkmcnt(0)
	s_barrier
; #define PG8_STAGE(bufoff, gbase, voff) do { _Pragma("unroll") for (int _i = 0; _i < 2; ++_i) \
;         __builtin_amdgcn_global_load_lds((const unsigned*)((const char*)(gbase) + (voff)[_i]), (LAS unsigned*)(lds + (bufoff) + ldsw + _i * 8192), 16, 0, 0); } while (0)
; #define PG8_LDA(dst, b, h) do { _Pragma("unroll") for (int m = 0; m < 4; ++m) _Pragma("unroll") for (int k = 0; k < 2; ++k) dst[m][k] = *(const LAS bf16x8*)(lds + PG8_SA(b, h) + aoff + m * 2048 + k * 1024); } while (0)
; #define PG8_LDB(dst, b, h) do { _Pragma("unroll") for (int n = 0; n < 2; ++n) _Pragma("unroll") for (int k = 0; k < 2; ++k) dst[n][k] = *(const LAS bf16x8*)(lds + PG8_SB(b, h) + boff + n * 2048 + k * 1024); } while (0)
; #define PG8_MMA(ai, bj, At, Bt) do { __builtin_amdgcn_s_setprio(1); _Pragma("unroll") for (int m = 0; m < 4; ++m) _Pragma("unroll") for (int n = 0; n < 2; ++n) _Pragma("unroll") for (int k = 0; k < 2; ++k) \
;         acc[ai][bj][m][n] = __builtin_amdgcn_mfma_f32_16x16x32_bf16(Bt[n][k], At[m][k], acc[ai][bj][m][n], 0, 0, 0); __builtin_amdgcn_s_setprio(0); } while (0)
; #define PG8_WAIT_V(n) asm volatile("s_waitcnt vmcnt(" #n ")" ::: "memory")
; #define PG8_WAIT_L(n) asm volatile("s_waitcnt lgkmcnt(" #n ")" ::: "memory")
; #define PG8_BAR __builtin_amdgcn_s_barrier()
; #define PG8_SCHED __builtin_amdgcn_sched_barrier(0)
; template <class Epi>
; __device__ __forceinline__ void gemm_phase(LAS unsigned char* lds, const Gemm g, const StaticOrder& S, const Epi& E) {
;     ...
;             PG8_WAIT_V(6); PG8_BAR; PG8_MMA(1, 1, At, B1); PG8_BAR;
;             PG8_LDB(B0, 1, 0); PG8_SCHED; PG8_LDA(At, 1, 0); PG8_STAGE(PG8_SA(0, 1), a2 + hstepA, voffA);
;             PG8_WAIT_L(8); PG8_BAR; PG8_WAIT_L(0); PG8_MMA(0, 0, At, B0); PG8_BAR; PG8_SCHED;
;             PG8_LDB(B1, 1, 1); PG8_STAGE(PG8_SB(1, 0), b3, voffB);
;             PG8_BAR; PG8_WAIT_L(0); PG8_MMA(0, 1, At, B1); PG8_BAR;
	s_setprio 1
	v_mfma_f32_16x16x32_bf16 v[60:63], v[140:143], v[164:167], v[60:63]
	v_mfma_f32_16x16x32_bf16 v[56:59], v[156:159], v[164:167], v[56:59]
	v_mfma_f32_16x16x32_bf16 v[48:51], v[140:143], v[172:175], v[48:51]
	v_mfma_f32_16x16x32_bf16 v[40:43], v[156:159], v[172:175], v[40:43]
	v_mfma_f32_16x16x32_bf16 v[28:31], v[140:143], v[180:183], v[28:31]
	v_mfma_f32_16x16x32_bf16 v[24:27], v[156:159], v[180:183], v[24:27]
	v_mfma_f32_16x16x32_bf16 v[16:19], v[140:143], v[188:191], v[16:19]
	v_mfma_f32_16x16x32_bf16 v[8:11], v[156:159], v[188:191], v[8:11]
	v_mfma_f32_16x16x32_bf16 v[60:63], v[152:155], v[168:171], v[60:63]
	v_mfma_f32_16x16x32_bf16 v[56:59], v[160:163], v[168:171], v[56:59]
	v_mfma_f32_16x16x32_bf16 v[48:51], v[152:155], v[176:179], v[48:51]
	v_mfma_f32_16x16x32_bf16 v[40:43], v[160:163], v[176:179], v[40:43]
	v_mfma_f32_16x16x32_bf16 v[28:31], v[152:155], v[184:187], v[28:31]
	v_mfma_f32_16x16x32_bf16 v[24:27], v[160:163], v[184:187], v[24:27]
	v_mfma_f32_16x16x32_bf16 v[16:19], v[152:155], v[192:195], v[16:19]
	v_mfma_f32_16x16x32_bf16 v[8:11], v[160:163], v[192:195], v[8:11]
	v_mfma_f32_16x16x32_bf16 v[52:55], v[196:199], v[164:167], v[52:55]
	v_mfma_f32_16x16x32_bf16 v[44:47], v[204:207], v[164:167], v[44:47]
	v_mfma_f32_16x16x32_bf16 v[36:39], v[196:199], v[172:175], v[36:39]
	v_mfma_f32_16x16x32_bf16 v[32:35], v[204:207], v[172:175], v[32:35]
	v_mfma_f32_16x16x32_bf16 v[20:23], v[196:199], v[180:183], v[20:23]
	v_mfma_f32_16x16x32_bf16 v[12:15], v[204:207], v[180:183], v[12:15]
	v_mfma_f32_16x16x32_bf16 v[4:7], v[196:199], v[188:191], v[4:7]
	v_mfma_f32_16x16x32_bf16 v[0:3], v[204:207], v[188:191], v[0:3]
	v_mfma_f32_16x16x32_bf16 v[52:55], v[200:203], v[168:171], v[52:55]
	v_mfma_f32_16x16x32_bf16 v[44:47], v[208:211], v[168:171], v[44:47]
	v_mfma_f32_16x16x32_bf16 v[36:39], v[200:203], v[176:179], v[36:39]
	v_mfma_f32_16x16x32_bf16 v[32:35], v[208:211], v[176:179], v[32:35]
	v_mfma_f32_16x16x32_bf16 v[20:23], v[200:203], v[184:187], v[20:23]
	v_mfma_f32_16x16x32_bf16 v[12:15], v[208:211], v[184:187], v[12:15]
	v_mfma_f32_16x16x32_bf16 v[4:7], v[200:203], v[192:195], v[4:7]
	v_mfma_f32_16x16x32_bf16 v[0:3], v[208:211], v[192:195], v[0:3]
	s_setprio 0
	s_add_i32 s69, 0, 0x18000
	v_add_u32_e32 v160, s69, v147
	s_barrier
	ds_read_b128 v[140:143], v160
	ds_read_b128 v[152:155], v160 offset:1024
	ds_read_b128 v[156:159], v160 offset:2048
	ds_read_b128 v[160:163], v160 offset:3072
	s_add_u32 s26, s34, 0xb0000
	s_addc_u32 s27, s35, 0
	s_mov_b32 m0, s38
	v_lshl_add_u64 v[196:197], s[26:27], 0, v[128:129]
	ds_read_b128 v[164:167], v150 offset:32768
	ds_read_b128 v[168:171], v150 offset:33792
	ds_read_b128 v[172:175], v150 offset:34816
	ds_read_b128 v[176:179], v150 offset:35840
	ds_read_b128 v[180:183], v150 offset:36864
	ds_read_b128 v[184:187], v150 offset:37888
	ds_read_b128 v[188:191], v150 offset:38912
	ds_read_b128 v[192:195], v150 offset:39936
	global_load_lds_dwordx4 v[196:197], off
	v_lshl_add_u64 v[196:197], s[26:27], 0, v[130:131]
	s_mov_b32 m0, s39
	s_nop 0
	global_load_lds_dwordx4 v[196:197], off
	s_add_i32 s34, 0, 0x1c000
	v_add_u32_e32 v208, s34, v147
	ds_read_b128 v[196:199], v208
	ds_read_b128 v[200:203], v208 offset:1024
	ds_read_b128 v[204:207], v208 offset:2048
	ds_read_b128 v[208:211], v208 offset:3072
	s_waitcnt lgkmcnt(0)
	s_barrier
	s_setprio 1
	v_mfma_f32_16x16x32_bf16 v[124:127], v[140:143], v[164:167], v[124:127]
	v_mfma_f32_16x16x32_bf16 v[120:123], v[156:159], v[164:167], v[120:123]
	v_mfma_f32_16x16x32_bf16 v[112:115], v[140:143], v[172:175], v[112:115]
	v_mfma_f32_16x16x32_bf16 v[104:107], v[156:159], v[172:175], v[104:107]
	v_mfma_f32_16x16x32_bf16 v[92:95], v[140:143], v[180:183], v[92:95]
	v_mfma_f32_16x16x32_bf16 v[88:91], v[156:159], v[180:183], v[88:91]
	v_mfma_f32_16x16x32_bf16 v[80:83], v[140:143], v[188:191], v[80:83]
	v_mfma_f32_16x16x32_bf16 v[72:75], v[156:159], v[188:191], v[72:75]
	v_mfma_f32_16x16x32_bf16 v[124:127], v[152:155], v[168:171], v[124:127]
	v_mfma_f32_16x16x32_bf16 v[120:123], v[160:163], v[168:171], v[120:123]
	v_mfma_f32_16x16x32_bf16 v[112:115], v[152:155], v[176:179], v[112:115]
	v_mfma_f32_16x16x32_bf16 v[104:107], v[160:163], v[176:179], v[104:107]
	v_mfma_f32_16x16x32_bf16 v[92:95], v[152:155], v[184:187], v[92:95]
	v_mfma_f32_16x16x32_bf16 v[88:91], v[160:163], v[184:187], v[88:91]
	v_mfma_f32_16x16x32_bf16 v[80:83], v[152:155], v[192:195], v[80:83]
	v_mfma_f32_16x16x32_bf16 v[72:75], v[160:163], v[192:195], v[72:75]
	v_mfma_f32_16x16x32_bf16 v[116:119], v[196:199], v[164:167], v[116:119]
	v_mfma_f32_16x16x32_bf16 v[108:111], v[204:207], v[164:167], v[108:111]
	v_mfma_f32_16x16x32_bf16 v[100:103], v[196:199], v[172:175], v[100:103]
	v_mfma_f32_16x16x32_bf16 v[96:99], v[204:207], v[172:175], v[96:99]
	v_mfma_f32_16x16x32_bf16 v[84:87], v[196:199], v[180:183], v[84:87]
	v_mfma_f32_16x16x32_bf16 v[76:79], v[204:207], v[180:183], v[76:79]
	v_mfma_f32_16x16x32_bf16 v[68:71], v[196:199], v[188:191], v[68:71]
	v_mfma_f32_16x16x32_bf16 v[64:67], v[204:207], v[188:191], v[64:67]
	v_mfma_f32_16x16x32_bf16 v[116:119], v[200:203], v[168:171], v[116:119]
	v_mfma_f32_16x16x32_bf16 v[108:111], v[208:211], v[168:171], v[108:111]
	v_mfma_f32_16x16x32_bf16 v[100:103], v[200:203], v[176:179], v[100:103]
	v_mfma_f32_16x16x32_bf16 v[96:99], v[208:211], v[176:179], v[96:99]
	v_mfma_f32_16x16x32_bf16 v[84:87], v[200:203], v[184:187], v[84:87]
	v_mfma_f32_16x16x32_bf16 v[76:79], v[208:211], v[184:187], v[76:79]
	v_mfma_f32_16x16x32_bf16 v[68:71], v[200:203], v[192:195], v[68:71]
	v_mfma_f32_16x16x32_bf16 v[64:67], v[208:211], v[192:195], v[64:67]
	s_setprio 0
	s_barrier
; #define PG8_STAGE(bufoff, gbase, voff) do { _Pragma("unroll") for (int _i = 0; _i < 2; ++_i) \
;         __builtin_amdgcn_global_load_lds((const unsigned*)((const char*)(gbase) + (voff)[_i]), (LAS unsigned*)(lds + (bufoff) + ldsw + _i * 8192), 16, 0, 0); } while (0)
; #define PG8_WAIT_V(n) asm volatile("s_waitcnt vmcnt(" #n ")" ::: "memory")
; #define PG8_WAIT_L(n) asm volatile("s_waitcnt lgkmcnt(" #n ")" ::: "memory")
; #define PG8_BAR __builtin_amdgcn_s_barrier()
; template <class Epi>
; __device__ __forceinline__ void gemm_phase(LAS unsigned char* lds, const Gemm g, const StaticOrder& S, const Epi& E) {
;     ...
;             PG8_LDA(At, 1, 1); PG8_STAGE(PG8_SA(1, 0), a3, voffA);
;             PG8_BAR; PG8_WAIT_L(0); PG8_MMA(1, 0, At, B0); PG8_BAR; PG8_SCHED;
;             PG8_STAGE(PG8_SB(1, 1), b3 + hstepB, voffB);
;             PG8_WAIT_V(6); PG8_BAR; PG8_MMA(1, 1, At, B1); PG8_BAR;
;     __device__ __forceinline__ void operator()(AccRef acc, const Unit& u, int wr, int wc, int fr, int fq) const {
;         const int row0 = u.pm * 256 + wr * 64 + fr, col0 = u.pn * 256 + wc * 32 + 4 * fq;
;         f32x4 sv[2][2], bv[2][2];
; #pragma unroll
;         for (int bj = 0; bj < 2; ++bj)
; #pragma unroll
;             for (int n = 0; n < 2; ++n) {
;                 sv[bj][n] = scale ? *(const f32x4*)(scale + col0 + bj * 128 + n * 16) : (f32x4){1.f, 1.f, 1.f, 1.f};
;                 bv[bj][n] = bias ? *(const f32x4*)(bias + col0 + bj * 128 + n * 16) : (f32x4){0.f, 0.f, 0.f, 0.f}; }
; #pragma unroll
;         for (int ai = 0; ai < 2; ++ai)
; #pragma unroll
;             for (int mh = 0; mh < 2; ++mh) {
;                 f32x4 bs[2][2][2];
; #pragma unroll
;                 for (int m = 0; m < 2; ++m)
; #pragma unroll
;                     for (int bj = 0; bj < 2; ++bj)
; #pragma unroll
;                         for (int n = 0; n < 2; ++n) bs[m][bj][n] = *(const f32x4*)(base + (size_t)(row0 + ai * 128 + (2 * mh + m) * 16) * D + col0 + bj * 128 + n * 16);
; #pragma unroll
;                 for (int m = 0; m < 2; ++m)
; #pragma unroll
;                     for (int bj = 0; bj < 2; ++bj)
; #pragma unroll
;                         for (int n = 0; n < 2; ++n) *(f32x4*)(out + (size_t)(row0 + ai * 128 + (2 * mh + m) * 16) * D + col0 + bj * 128 + n * 16) = bs[m][bj][n] + sv[bj][n] * (acc[ai][bj][2 * mh + m][n] + bv[bj][n]);
;                 asm volatile("" ::: "memory"); }
	s_nop 1
	ds_read_b128 v[164:167], v150 offset:49152
	ds_read_b128 v[168:171], v150 offset:50176
	ds_read_b128 v[172:175], v150 offset:51200
	ds_read_b128 v[176:179], v150 offset:52224
	ds_read_b128 v[180:183], v150 offset:53248
	ds_read_b128 v[184:187], v150 offset:54272
	ds_read_b128 v[188:191], v150 offset:55296
	ds_read_b128 v[192:195], v150 offset:56320
	s_add_i32 s26, s69, s7
	v_lshl_add_u64 v[254:255], v[144:145], 0, s[16:17]
	s_mov_b32 m0, s26
	s_nop 0
	global_load_lds_dwordx4 v[254:255], off
	v_lshl_add_u64 v[254:255], v[212:213], 0, s[16:17]
	s_add_i32 m0, s26, 0x2000
	s_nop 0
	global_load_lds_dwordx4 v[254:255], off
	s_mov_b32 m0, s41
	v_lshl_add_u64 v[254:255], v[214:215], 0, s[16:17]
	global_load_lds_dwordx4 v[254:255], off
	v_lshl_add_u64 v[144:145], v[216:217], 0, s[16:17]
	s_mov_b32 m0, s42
	s_nop 0
	global_load_lds_dwordx4 v[144:145], off
	s_add_u32 s26, s30, 0xb0080
	s_addc_u32 s27, s31, 0
	s_add_i32 s30, s34, s7
	v_lshl_add_u64 v[254:255], s[26:27], 0, v[128:129]
	s_mov_b32 m0, s30
	s_nop 0
	global_load_lds_dwordx4 v[254:255], off
	v_lshl_add_u64 v[254:255], s[26:27], 0, v[130:131]
	s_add_i32 m0, s30, 0x2000
	s_nop 0
	global_load_lds_dwordx4 v[254:255], off
	s_waitcnt vmcnt(6)
	s_waitcnt lgkmcnt(0)
	s_barrier
	s_setprio 1
	v_mfma_f32_16x16x32_bf16 v[60:63], v[140:143], v[164:167], v[60:63]
	v_mfma_f32_16x16x32_bf16 v[56:59], v[156:159], v[164:167], v[56:59]
	v_mfma_f32_16x16x32_bf16 v[48:51], v[140:143], v[172:175], v[48:51]
	v_mfma_f32_16x16x32_bf16 v[40:43], v[156:159], v[172:175], v[40:43]
	v_mfma_f32_16x16x32_bf16 v[28:31], v[140:143], v[180:183], v[28:31]
	v_mfma_f32_16x16x32_bf16 v[24:27], v[156:159], v[180:183], v[24:27]
	v_mfma_f32_16x16x32_bf16 v[16:19], v[140:143], v[188:191], v[16:19]
	v_mfma_f32_16x16x32_bf16 v[8:11], v[156:159], v[188:191], v[8:11]
	v_mfma_f32_16x16x32_bf16 v[60:63], v[152:155], v[168:171], v[60:63]
	v_mfma_f32_16x16x32_bf16 v[56:59], v[160:163], v[168:171], v[56:59]
	v_mfma_f32_16x16x32_bf16 v[48:51], v[152:155], v[176:179], v[48:51]
	v_mfma_f32_16x16x32_bf16 v[40:43], v[160:163], v[176:179], v[40:43]
	v_mfma_f32_16x16x32_bf16 v[28:31], v[152:155], v[184:187], v[28:31]
	v_mfma_f32_16x16x32_bf16 v[24:27], v[160:163], v[184:187], v[24:27]
	v_mfma_f32_16x16x32_bf16 v[16:19], v[152:155], v[192:195], v[16:19]
	v_mfma_f32_16x16x32_bf16 v[8:11], v[160:163], v[192:195], v[8:11]
	v_mfma_f32_16x16x32_bf16 v[52:55], v[196:199], v[164:167], v[52:55]
	v_mfma_f32_16x16x32_bf16 v[44:47], v[204:207], v[164:167], v[44:47]
	v_mfma_f32_16x16x32_bf16 v[36:39], v[196:199], v[172:175], v[36:39]
	v_mfma_f32_16x16x32_bf16 v[32:35], v[204:207], v[172:175], v[32:35]
	v_mfma_f32_16x16x32_bf16 v[20:23], v[196:199], v[180:183], v[20:23]
	v_mfma_f32_16x16x32_bf16 v[12:15], v[204:207], v[180:183], v[12:15]
	v_mfma_f32_16x16x32_bf16 v[4:7], v[196:199], v[188:191], v[4:7]
	v_mfma_f32_16x16x32_bf16 v[0:3], v[204:207], v[188:191], v[0:3]
	v_mfma_f32_16x16x32_bf16 v[52:55], v[200:203], v[168:171], v[52:55]
	v_mfma_f32_16x16x32_bf16 v[44:47], v[208:211], v[168:171], v[44:47]
	v_mfma_f32_16x16x32_bf16 v[36:39], v[200:203], v[176:179], v[36:39]
	v_mfma_f32_16x16x32_bf16 v[32:35], v[208:211], v[176:179], v[32:35]
	v_mfma_f32_16x16x32_bf16 v[20:23], v[200:203], v[184:187], v[20:23]
	v_mfma_f32_16x16x32_bf16 v[12:15], v[208:211], v[184:187], v[12:15]
	v_mfma_f32_16x16x32_bf16 v[4:7], v[200:203], v[192:195], v[4:7]
	v_mfma_f32_16x16x32_bf16 v[0:3], v[208:211], v[192:195], v[0:3]
	s_setprio 0
	s_add_i32 s68, s68, 2
	s_add_u32 s49, s49, 0x100
	s_addc_u32 s63, s63, 0
	s_cmp_gt_u32 s68, 41
	s_mov_b64 s[26:27], s[28:29]
	s_barrier
	s_cbranch_scc0 .LBB0_411
	v_lshl_or_b32 v144, s47, 8, v148
	v_lshl_add_u32 v145, s48, 8, v146
	v_lshlrev_b32_e32 v144, 2, v144
	v_lshl_add_u32 v145, v145, 12, v144
	v_add_u32_e32 v216, 0x10000, v145
	v_add_u32_e32 v217, 0x20000, v145
	v_add_u32_e32 v218, 0x30000, v145
	v_add_u32_e32 v232, 0x80000, v145
	v_add_u32_e32 v233, 0x90000, v145
	v_add_u32_e32 v235, 0xa0000, v145
	v_add_u32_e32 v253, 0xb0000, v145
	s_and_b64 vcc, exec, s[8:9]
	s_mov_b32 s47, s45
	s_mov_b32 s48, s46
	s_mov_b64 s[28:29], s[12:13]
	s_mov_b64 s[26:27], s[10:11]
	global_load_dwordx4 v[140:143], v145, s[52:53]
	global_load_dwordx4 v[152:155], v145, s[52:53] offset:64
	global_load_dwordx4 v[156:159], v145, s[52:53] offset:512
	global_load_dwordx4 v[160:163], v145, s[52:53] offset:576
	global_load_dwordx4 v[164:167], v216, s[52:53]
	global_load_dwordx4 v[168:171], v216, s[52:53] offset:64
	global_load_dwordx4 v[172:175], v216, s[52:53] offset:512
	global_load_dwordx4 v[176:179], v216, s[52:53] offset:576
	global_load_dwordx4 v[180:183], v217, s[52:53]
	global_load_dwordx4 v[184:187], v217, s[52:53] offset:64
	global_load_dwordx4 v[188:191], v217, s[52:53] offset:512
	global_load_dwordx4 v[192:195], v217, s[52:53] offset:576
	global_load_dwordx4 v[196:199], v218, s[52:53]
	global_load_dwordx4 v[200:203], v218, s[52:53] offset:64
	global_load_dwordx4 v[204:207], v218, s[52:53] offset:512
	global_load_dwordx4 v[208:211], v218, s[52:53] offset:576
	global_load_dwordx4 v[212:215], v232, s[52:53]
	global_load_dwordx4 v[220:223], v232, s[52:53] offset:64
	global_load_dwordx4 v[224:227], v232, s[52:53] offset:512
	global_load_dwordx4 v[228:231], v232, s[52:53] offset:576
	global_load_dwordx4 v[236:239], v233, s[52:53]
	global_load_dwordx4 v[240:243], v233, s[52:53] offset:64
	global_load_dwordx4 v[244:247], v233, s[52:53] offset:512
	global_load_dwordx4 v[248:251], v233, s[52:53] offset:576
	v_pk_add_f32 v[124:125], v[124:125], 0 op_sel_hi:[1,0]
	v_pk_add_f32 v[126:127], v[126:127], 0 op_sel_hi:[1,0]
	v_pk_add_f32 v[120:121], v[120:121], 0 op_sel_hi:[1,0]
;     __device__ __forceinline__ void operator()(AccRef acc, const Unit& u, int wr, int wc, int fr, int fq) const {
;     ...
;         for (int ai = 0; ai < 2; ++ai)
; #pragma unroll
;             for (int mh = 0; mh < 2; ++mh) {
;                 f32x4 bs[2][2][2];
; #pragma unroll
;                 for (int m = 0; m < 2; ++m)
; #pragma unroll
;                     for (int bj = 0; bj < 2; ++bj)
; #pragma unroll
;                         for (int n = 0; n < 2; ++n) bs[m][bj][n] = *(const f32x4*)(base + (size_t)(row0 + ai * 128 + (2 * mh + m) * 16) * D + col0 + bj * 128 + n * 16);
; #pragma unroll
;                 for (int m = 0; m < 2; ++m)
; #pragma unroll
;                     for (int bj = 0; bj < 2; ++bj)
; #pragma unroll
;                         for (int n = 0; n < 2; ++n) *(f32x4*)(out + (size_t)(row0 + ai * 128 + (2 * mh + m) * 16) * D + col0 + bj * 128 + n * 16) = bs[m][bj][n] + sv[bj][n] * (acc[ai][bj][2 * mh + m][n] + bv[bj][n]);
;                 asm volatile("" ::: "memory"); }
	v_pk_add_f32 v[122:123], v[122:123], 0 op_sel_hi:[1,0]
	v_pk_add_f32 v[116:117], v[116:117], 0 op_sel_hi:[1,0]
	v_pk_add_f32 v[118:119], v[118:119], 0 op_sel_hi:[1,0]
	v_pk_add_f32 v[108:109], v[108:109], 0 op_sel_hi:[1,0]
	v_pk_add_f32 v[110:111], v[110:111], 0 op_sel_hi:[1,0]
	v_pk_add_f32 v[112:113], v[112:113], 0 op_sel_hi:[1,0]
	v_pk_add_f32 v[114:115], v[114:115], 0 op_sel_hi:[1,0]
	v_pk_add_f32 v[104:105], v[104:105], 0 op_sel_hi:[1,0]
	v_pk_add_f32 v[106:107], v[106:107], 0 op_sel_hi:[1,0]
	v_pk_add_f32 v[100:101], v[100:101], 0 op_sel_hi:[1,0]
	v_pk_add_f32 v[102:103], v[102:103], 0 op_sel_hi:[1,0]
	v_pk_add_f32 v[96:97], v[96:97], 0 op_sel_hi:[1,0]
	v_pk_add_f32 v[98:99], v[98:99], 0 op_sel_hi:[1,0]
	v_pk_add_f32 v[92:93], v[92:93], 0 op_sel_hi:[1,0]
	v_pk_add_f32 v[94:95], v[94:95], 0 op_sel_hi:[1,0]
	v_pk_add_f32 v[88:89], v[88:89], 0 op_sel_hi:[1,0]
	v_pk_add_f32 v[90:91], v[90:91], 0 op_sel_hi:[1,0]
	v_pk_add_f32 v[84:85], v[84:85], 0 op_sel_hi:[1,0]
	v_pk_add_f32 v[86:87], v[86:87], 0 op_sel_hi:[1,0]
	v_pk_add_f32 v[76:77], v[76:77], 0 op_sel_hi:[1,0]
	v_pk_add_f32 v[78:79], v[78:79], 0 op_sel_hi:[1,0]
	v_pk_add_f32 v[80:81], v[80:81], 0 op_sel_hi:[1,0]
	v_pk_add_f32 v[82:83], v[82:83], 0 op_sel_hi:[1,0]
	v_pk_add_f32 v[72:73], v[72:73], 0 op_sel_hi:[1,0]
	v_pk_add_f32 v[74:75], v[74:75], 0 op_sel_hi:[1,0]
	v_pk_add_f32 v[68:69], v[68:69], 0 op_sel_hi:[1,0]
	v_pk_add_f32 v[70:71], v[70:71], 0 op_sel_hi:[1,0]
	v_pk_add_f32 v[64:65], v[64:65], 0 op_sel_hi:[1,0]
	v_pk_add_f32 v[66:67], v[66:67], 0 op_sel_hi:[1,0]
	v_pk_add_f32 v[60:61], v[60:61], 0 op_sel_hi:[1,0]
	v_pk_add_f32 v[62:63], v[62:63], 0 op_sel_hi:[1,0]
	v_pk_add_f32 v[56:57], v[56:57], 0 op_sel_hi:[1,0]
	v_pk_add_f32 v[58:59], v[58:59], 0 op_sel_hi:[1,0]
	v_pk_add_f32 v[52:53], v[52:53], 0 op_sel_hi:[1,0]
	v_pk_add_f32 v[54:55], v[54:55], 0 op_sel_hi:[1,0]
	v_pk_add_f32 v[44:45], v[44:45], 0 op_sel_hi:[1,0]
	v_pk_add_f32 v[46:47], v[46:47], 0 op_sel_hi:[1,0]
	v_pk_add_f32 v[48:49], v[48:49], 0 op_sel_hi:[1,0]
	v_pk_add_f32 v[50:51], v[50:51], 0 op_sel_hi:[1,0]
	v_pk_add_f32 v[40:41], v[40:41], 0 op_sel_hi:[1,0]
	v_pk_add_f32 v[42:43], v[42:43], 0 op_sel_hi:[1,0]
	v_pk_add_f32 v[36:37], v[36:37], 0 op_sel_hi:[1,0]
	v_pk_add_f32 v[38:39], v[38:39], 0 op_sel_hi:[1,0]
	v_pk_add_f32 v[32:33], v[32:33], 0 op_sel_hi:[1,0]
	v_pk_add_f32 v[34:35], v[34:35], 0 op_sel_hi:[1,0]
	v_pk_add_f32 v[28:29], v[28:29], 0 op_sel_hi:[1,0]
	v_pk_add_f32 v[30:31], v[30:31], 0 op_sel_hi:[1,0]
	v_pk_add_f32 v[24:25], v[24:25], 0 op_sel_hi:[1,0]
	v_pk_add_f32 v[26:27], v[26:27], 0 op_sel_hi:[1,0]
	v_pk_add_f32 v[20:21], v[20:21], 0 op_sel_hi:[1,0]
	v_pk_add_f32 v[22:23], v[22:23], 0 op_sel_hi:[1,0]
	v_pk_add_f32 v[12:13], v[12:13], 0 op_sel_hi:[1,0]
	v_pk_add_f32 v[14:15], v[14:15], 0 op_sel_hi:[1,0]
	v_pk_add_f32 v[16:17], v[16:17], 0 op_sel_hi:[1,0]
	v_pk_add_f32 v[18:19], v[18:19], 0 op_sel_hi:[1,0]
	v_pk_add_f32 v[8:9], v[8:9], 0 op_sel_hi:[1,0]
	v_pk_add_f32 v[10:11], v[10:11], 0 op_sel_hi:[1,0]
	v_pk_add_f32 v[4:5], v[4:5], 0 op_sel_hi:[1,0]
	v_pk_add_f32 v[6:7], v[6:7], 0 op_sel_hi:[1,0]
	v_pk_add_f32 v[0:1], v[0:1], 0 op_sel_hi:[1,0]
	v_pk_add_f32 v[2:3], v[2:3], 0 op_sel_hi:[1,0]
	s_waitcnt vmcnt(16)
	v_pk_add_f32 v[124:125], v[124:125], v[140:141]
	v_pk_add_f32 v[126:127], v[126:127], v[142:143]
	v_pk_add_f32 v[120:121], v[120:121], v[152:153]
	v_pk_add_f32 v[122:123], v[122:123], v[154:155]
	v_pk_add_f32 v[116:117], v[116:117], v[156:157]
	v_pk_add_f32 v[118:119], v[118:119], v[158:159]
	v_pk_add_f32 v[108:109], v[108:109], v[160:161]
	v_pk_add_f32 v[110:111], v[110:111], v[162:163]
	v_pk_add_f32 v[112:113], v[112:113], v[164:165]
	v_pk_add_f32 v[114:115], v[114:115], v[166:167]
	v_pk_add_f32 v[104:105], v[104:105], v[168:169]
	v_pk_add_f32 v[106:107], v[106:107], v[170:171]
	v_pk_add_f32 v[100:101], v[100:101], v[172:173]
	v_pk_add_f32 v[102:103], v[102:103], v[174:175]
	v_pk_add_f32 v[96:97], v[96:97], v[176:177]
	v_pk_add_f32 v[98:99], v[98:99], v[178:179]
	global_store_dwordx4 v145, v[124:127], s[52:53]
	global_store_dwordx4 v145, v[120:123], s[52:53] offset:64
	global_store_dwordx4 v145, v[116:119], s[52:53] offset:512
	global_store_dwordx4 v145, v[108:111], s[52:53] offset:576
	global_store_dwordx4 v216, v[112:115], s[52:53]
	global_store_dwordx4 v216, v[104:107], s[52:53] offset:64
	global_store_dwordx4 v216, v[100:103], s[52:53] offset:512
	global_store_dwordx4 v216, v[96:99], s[52:53] offset:576
	global_load_dwordx4 v[140:143], v235, s[52:53]
	global_load_dwordx4 v[152:155], v235, s[52:53] offset:64
	global_load_dwordx4 v[156:159], v235, s[52:53] offset:512
	global_load_dwordx4 v[160:163], v235, s[52:53] offset:576
	global_load_dwordx4 v[164:167], v253, s[52:53]
	global_load_dwordx4 v[168:171], v253, s[52:53] offset:64
	global_load_dwordx4 v[172:175], v253, s[52:53] offset:512
	global_load_dwordx4 v[176:179], v253, s[52:53] offset:576
	s_waitcnt vmcnt(24)
;     __device__ __forceinline__ void operator()(AccRef acc, const Unit& u, int wr, int wc, int fr, int fq) const {
;     ...
;                         for (int n = 0; n < 2; ++n) bs[m][bj][n] = *(const f32x4*)(base + (size_t)(row0 + ai * 128 + (2 * mh + m) * 16) * D + col0 + bj * 128 + n * 16);
; #pragma unroll
;                 for (int m = 0; m < 2; ++m)
; #pragma unroll
;                     for (int bj = 0; bj < 2; ++bj)
; #pragma unroll
;                         for (int n = 0; n < 2; ++n) *(f32x4*)(out + (size_t)(row0 + ai * 128 + (2 * mh + m) * 16) * D + col0 + bj * 128 + n * 16) = bs[m][bj][n] + sv[bj][n] * (acc[ai][bj][2 * mh + m][n] + bv[bj][n]);
;                 asm volatile("" ::: "memory"); }
	v_pk_add_f32 v[92:93], v[92:93], v[180:181]
	v_pk_add_f32 v[94:95], v[94:95], v[182:183]
	v_pk_add_f32 v[88:89], v[88:89], v[184:185]
	v_pk_add_f32 v[90:91], v[90:91], v[186:187]
	v_pk_add_f32 v[84:85], v[84:85], v[188:189]
	v_pk_add_f32 v[86:87], v[86:87], v[190:191]
	v_pk_add_f32 v[76:77], v[76:77], v[192:193]
	v_pk_add_f32 v[78:79], v[78:79], v[194:195]
	v_pk_add_f32 v[80:81], v[80:81], v[196:197]
	v_pk_add_f32 v[82:83], v[82:83], v[198:199]
	v_pk_add_f32 v[72:73], v[72:73], v[200:201]
	v_pk_add_f32 v[74:75], v[74:75], v[202:203]
	v_pk_add_f32 v[68:69], v[68:69], v[204:205]
	v_pk_add_f32 v[70:71], v[70:71], v[206:207]
	v_pk_add_f32 v[64:65], v[64:65], v[208:209]
	v_pk_add_f32 v[66:67], v[66:67], v[210:211]
	global_store_dwordx4 v217, v[92:95], s[52:53]
	global_store_dwordx4 v217, v[88:91], s[52:53] offset:64
	global_store_dwordx4 v217, v[84:87], s[52:53] offset:512
	global_store_dwordx4 v217, v[76:79], s[52:53] offset:576
	global_store_dwordx4 v218, v[80:83], s[52:53]
	global_store_dwordx4 v218, v[72:75], s[52:53] offset:64
	global_store_dwordx4 v218, v[68:71], s[52:53] offset:512
	global_store_dwordx4 v218, v[64:67], s[52:53] offset:576
	s_waitcnt vmcnt(24)
	v_pk_add_f32 v[60:61], v[60:61], v[212:213]
	v_pk_add_f32 v[62:63], v[62:63], v[214:215]
	v_pk_add_f32 v[56:57], v[56:57], v[220:221]
	v_pk_add_f32 v[58:59], v[58:59], v[222:223]
	v_pk_add_f32 v[52:53], v[52:53], v[224:225]
	v_pk_add_f32 v[54:55], v[54:55], v[226:227]
	v_pk_add_f32 v[44:45], v[44:45], v[228:229]
	v_pk_add_f32 v[46:47], v[46:47], v[230:231]
	v_pk_add_f32 v[48:49], v[48:49], v[236:237]
	v_pk_add_f32 v[50:51], v[50:51], v[238:239]
	v_pk_add_f32 v[40:41], v[40:41], v[240:241]
	v_pk_add_f32 v[42:43], v[42:43], v[242:243]
	v_pk_add_f32 v[36:37], v[36:37], v[244:245]
	v_pk_add_f32 v[38:39], v[38:39], v[246:247]
	v_pk_add_f32 v[32:33], v[32:33], v[248:249]
	v_pk_add_f32 v[34:35], v[34:35], v[250:251]
	global_store_dwordx4 v232, v[60:63], s[52:53]
	global_store_dwordx4 v232, v[56:59], s[52:53] offset:64
	global_store_dwordx4 v232, v[52:55], s[52:53] offset:512
	global_store_dwordx4 v232, v[44:47], s[52:53] offset:576
	global_store_dwordx4 v233, v[48:51], s[52:53]
	global_store_dwordx4 v233, v[40:43], s[52:53] offset:64
	global_store_dwordx4 v233, v[36:39], s[52:53] offset:512
	global_store_dwordx4 v233, v[32:35], s[52:53] offset:576
	s_waitcnt vmcnt(16)
	v_pk_add_f32 v[28:29], v[28:29], v[140:141]
	v_pk_add_f32 v[30:31], v[30:31], v[142:143]
	v_pk_add_f32 v[24:25], v[24:25], v[152:153]
	v_pk_add_f32 v[26:27], v[26:27], v[154:155]
	v_pk_add_f32 v[20:21], v[20:21], v[156:157]
	v_pk_add_f32 v[22:23], v[22:23], v[158:159]
	v_pk_add_f32 v[12:13], v[12:13], v[160:161]
	v_pk_add_f32 v[14:15], v[14:15], v[162:163]
	v_pk_add_f32 v[16:17], v[16:17], v[164:165]
	v_pk_add_f32 v[18:19], v[18:19], v[166:167]
	v_pk_add_f32 v[8:9], v[8:9], v[168:169]
	v_pk_add_f32 v[10:11], v[10:11], v[170:171]
	v_pk_add_f32 v[4:5], v[4:5], v[172:173]
	v_pk_add_f32 v[6:7], v[6:7], v[174:175]
	v_pk_add_f32 v[0:1], v[0:1], v[176:177]
	v_pk_add_f32 v[2:3], v[2:3], v[178:179]
	global_store_dwordx4 v235, v[28:31], s[52:53]
	global_store_dwordx4 v235, v[24:27], s[52:53] offset:64
	global_store_dwordx4 v235, v[20:23], s[52:53] offset:512
	global_store_dwordx4 v235, v[12:15], s[52:53] offset:576
	global_store_dwordx4 v253, v[16:19], s[52:53]
	global_store_dwordx4 v253, v[8:11], s[52:53] offset:64
	global_store_dwordx4 v253, v[4:7], s[52:53] offset:512
	global_store_dwordx4 v253, v[0:3], s[52:53] offset:576
	s_cbranch_vccz .LBB0_400
	s_waitcnt vmcnt(0)
	s_cmpk_gt_u32 s4, 0xff
	s_cbranch_scc1 .LBB0_415
	s_barrier

; __device__ __forceinline__ void weights_phase(const Params& P, LAS float* scr, int lane, int it0, int it1, int w, int nw) {
;     ...
; #pragma unroll 8
;         for (int i = 0; i < 32; ++i) { const int kk = 2 * i + (lane >> 5); scr[kk * 33 + (lane & 31)] = jb.src[(size_t)(k0 + kk) * jb.ld + c0 + (lane & 31)]; }
.LBB0_565:
	s_or_b64 exec, exec, s[8:9]
	v_ashrrev_i32_e32 v21, 31, v20
	v_lshlrev_b32_e32 v18, 6, v2
	v_ashrrev_i32_e32 v3, 31, v1
	s_waitcnt vmcnt(0)
	v_lshl_add_u64 v[4:5], v[20:21], 2, v[4:5]
	v_lshl_add_u64 v[20:21], v[4:5], 0, v[16:17]
	v_mov_b32_e32 v2, v1
	v_mov_b32_e32 v4, v1
	v_mov_b32_e32 v5, v3
	v_or_b32_e32 v1, v9, v18
	v_or_b32_e32 v22, v10, v18
	s_mov_b32 s8, 1
	s_mov_b32 s9, 0
	s_mov_b32 s13, 32
	v_lshlrev_b32_e32 v27, 2, v2
	v_mul_lo_u32 v28, v22, v27
	v_lshlrev_b32_e32 v27, 1, v27
	v_mov_b32_e32 v29, 0
	v_mul_u32_u24_e32 v66, 0x84, v10
	v_add_u32_e32 v66, v66, v14
	v_lshl_add_u64 v[30:31], v[28:29], 0, v[20:21]
	global_load_dword v32, v[30:31], off
	v_add_u32_e32 v28, v28, v27
	v_lshl_add_u64 v[64:65], v[28:29], 0, v[20:21]
	global_load_dword v33, v[64:65], off
	v_add_u32_e32 v28, v28, v27
	v_lshl_add_u64 v[30:31], v[28:29], 0, v[20:21]
	global_load_dword v34, v[30:31], off
	v_add_u32_e32 v28, v28, v27
	v_lshl_add_u64 v[64:65], v[28:29], 0, v[20:21]
	global_load_dword v35, v[64:65], off
	v_add_u32_e32 v28, v28, v27
	v_lshl_add_u64 v[30:31], v[28:29], 0, v[20:21]
	global_load_dword v36, v[30:31], off
	v_add_u32_e32 v28, v28, v27
	v_lshl_add_u64 v[64:65], v[28:29], 0, v[20:21]
	global_load_dword v37, v[64:65], off
	v_add_u32_e32 v28, v28, v27
	v_lshl_add_u64 v[30:31], v[28:29], 0, v[20:21]
	global_load_dword v38, v[30:31], off
	v_add_u32_e32 v28, v28, v27
	v_lshl_add_u64 v[64:65], v[28:29], 0, v[20:21]
	global_load_dword v39, v[64:65], off
	v_add_u32_e32 v28, v28, v27
	v_lshl_add_u64 v[30:31], v[28:29], 0, v[20:21]
	global_load_dword v40, v[30:31], off
	v_add_u32_e32 v28, v28, v27
	v_lshl_add_u64 v[64:65], v[28:29], 0, v[20:21]
	global_load_dword v41, v[64:65], off
	v_add_u32_e32 v28, v28, v27
	v_lshl_add_u64 v[30:31], v[28:29], 0, v[20:21]
	global_load_dword v42, v[30:31], off
	v_add_u32_e32 v28, v28, v27
	v_lshl_add_u64 v[64:65], v[28:29], 0, v[20:21]
	global_load_dword v43, v[64:65], off
	v_add_u32_e32 v28, v28, v27
	v_lshl_add_u64 v[30:31], v[28:29], 0, v[20:21]
	global_load_dword v44, v[30:31], off
	v_add_u32_e32 v28, v28, v27
	v_lshl_add_u64 v[64:65], v[28:29], 0, v[20:21]
	global_load_dword v45, v[64:65], off
	v_add_u32_e32 v28, v28, v27
	v_lshl_add_u64 v[30:31], v[28:29], 0, v[20:21]
	global_load_dword v46, v[30:31], off
	v_add_u32_e32 v28, v28, v27
	v_lshl_add_u64 v[64:65], v[28:29], 0, v[20:21]
	global_load_dword v47, v[64:65], off
	v_add_u32_e32 v28, v28, v27
	v_lshl_add_u64 v[30:31], v[28:29], 0, v[20:21]
	global_load_dword v48, v[30:31], off
	v_add_u32_e32 v28, v28, v27
	v_lshl_add_u64 v[64:65], v[28:29], 0, v[20:21]
	global_load_dword v49, v[64:65], off
	v_add_u32_e32 v28, v28, v27
	v_lshl_add_u64 v[30:31], v[28:29], 0, v[20:21]
	global_load_dword v50, v[30:31], off
	v_add_u32_e32 v28, v28, v27
	v_lshl_add_u64 v[64:65], v[28:29], 0, v[20:21]
	global_load_dword v51, v[64:65], off
	v_add_u32_e32 v28, v28, v27
	v_lshl_add_u64 v[30:31], v[28:29], 0, v[20:21]
	global_load_dword v52, v[30:31], off
	v_add_u32_e32 v28, v28, v27
	v_lshl_add_u64 v[64:65], v[28:29], 0, v[20:21]
	global_load_dword v53, v[64:65], off
	v_add_u32_e32 v28, v28, v27
	v_lshl_add_u64 v[30:31], v[28:29], 0, v[20:21]
	global_load_dword v54, v[30:31], off
	v_add_u32_e32 v28, v28, v27
	v_lshl_add_u64 v[64:65], v[28:29], 0, v[20:21]
	global_load_dword v55, v[64:65], off
	v_add_u32_e32 v28, v28, v27
	v_lshl_add_u64 v[30:31], v[28:29], 0, v[20:21]
	global_load_dword v56, v[30:31], off
	v_add_u32_e32 v28, v28, v27
	v_lshl_add_u64 v[64:65], v[28:29], 0, v[20:21]
	global_load_dword v57, v[64:65], off
	v_add_u32_e32 v28, v28, v27
	v_lshl_add_u64 v[30:31], v[28:29], 0, v[20:21]
	global_load_dword v58, v[30:31], off
	v_add_u32_e32 v28, v28, v27
	v_lshl_add_u64 v[64:65], v[28:29], 0, v[20:21]
	global_load_dword v59, v[64:65], off
	v_add_u32_e32 v28, v28, v27
	v_lshl_add_u64 v[30:31], v[28:29], 0, v[20:21]
	global_load_dword v60, v[30:31], off
	v_add_u32_e32 v28, v28, v27
	v_lshl_add_u64 v[64:65], v[28:29], 0, v[20:21]
	global_load_dword v61, v[64:65], off
	v_add_u32_e32 v28, v28, v27
	v_lshl_add_u64 v[30:31], v[28:29], 0, v[20:21]
	global_load_dword v62, v[30:31], off
	v_add_u32_e32 v28, v28, v27
	v_lshl_add_u64 v[64:65], v[28:29], 0, v[20:21]
	global_load_dword v63, v[64:65], off
	s_waitcnt vmcnt(31)
; #define LAS __attribute__((address_space(3)))
; __device__ __forceinline__ void weights_phase(const Params& P, LAS float* scr, int lane, int it0, int it1, int w, int nw) {
;     ...
;         for (int i = 0; i < 32; ++i) { const int kk = 2 * i + (lane >> 5); scr[kk * 33 + (lane & 31)] = jb.src[(size_t)(k0 + kk) * jb.ld + c0 + (lane & 31)]; }
;         asm volatile("s_waitcnt lgkmcnt(0)" ::: "memory");
;         const int c = lane & 7;
; #pragma unroll
;         for (int j = 0; j < 4; ++j) { const int n = (lane >> 3) + 8 * j; const LAS float* s = scr + (8 * c) * 33 + n;
;             u32x4 o; o.x = cvt_pk_bf16(s[0 * 33], s[1 * 33]); o.y = cvt_pk_bf16(s[2 * 33], s[3 * 33]); o.z = cvt_pk_bf16(s[4 * 33], s[5 * 33]); o.w = cvt_pk_bf16(s[6 * 33], s[7 * 33]);
;             *(u32x4*)(jb.dst + (size_t)(n0 + n) * jb.K + k0 + 8 * c) = o; }
;         asm volatile("s_waitcnt lgkmcnt(0)" ::: "memory");
	ds_write_b32 v66, v32
	s_waitcnt vmcnt(30)
	ds_write_b32 v66, v33 offset:264
	s_waitcnt vmcnt(29)
	ds_write_b32 v66, v34 offset:528
	s_waitcnt vmcnt(28)
	ds_write_b32 v66, v35 offset:792
	s_waitcnt vmcnt(27)
	ds_write_b32 v66, v36 offset:1056
	s_waitcnt vmcnt(26)
	ds_write_b32 v66, v37 offset:1320
	s_waitcnt vmcnt(25)
	ds_write_b32 v66, v38 offset:1584
	s_waitcnt vmcnt(24)
	ds_write_b32 v66, v39 offset:1848
	s_waitcnt vmcnt(23)
	ds_write_b32 v66, v40 offset:2112
	s_waitcnt vmcnt(22)
	ds_write_b32 v66, v41 offset:2376
	s_waitcnt vmcnt(21)
	ds_write_b32 v66, v42 offset:2640
	s_waitcnt vmcnt(20)
	ds_write_b32 v66, v43 offset:2904
	s_waitcnt vmcnt(19)
	ds_write_b32 v66, v44 offset:3168
	s_waitcnt vmcnt(18)
	ds_write_b32 v66, v45 offset:3432
	s_waitcnt vmcnt(17)
	ds_write_b32 v66, v46 offset:3696
	s_waitcnt vmcnt(16)
	ds_write_b32 v66, v47 offset:3960
	s_waitcnt vmcnt(15)
	ds_write_b32 v66, v48 offset:4224
	s_waitcnt vmcnt(14)
	ds_write_b32 v66, v49 offset:4488
	s_waitcnt vmcnt(13)
	ds_write_b32 v66, v50 offset:4752
	s_waitcnt vmcnt(12)
	ds_write_b32 v66, v51 offset:5016
	s_waitcnt vmcnt(11)
	ds_write_b32 v66, v52 offset:5280
	s_waitcnt vmcnt(10)
	ds_write_b32 v66, v53 offset:5544
	s_waitcnt vmcnt(9)
	ds_write_b32 v66, v54 offset:5808
	s_waitcnt vmcnt(8)
	ds_write_b32 v66, v55 offset:6072
	s_waitcnt vmcnt(7)
	ds_write_b32 v66, v56 offset:6336
	s_waitcnt vmcnt(6)
	ds_write_b32 v66, v57 offset:6600
	s_waitcnt vmcnt(5)
	ds_write_b32 v66, v58 offset:6864
	s_waitcnt vmcnt(4)
	ds_write_b32 v66, v59 offset:7128
	s_waitcnt vmcnt(3)
	ds_write_b32 v66, v60 offset:7392
	s_waitcnt vmcnt(2)
	ds_write_b32 v66, v61 offset:7656
	s_waitcnt vmcnt(1)
	ds_write_b32 v66, v62 offset:7920
	s_waitcnt vmcnt(0)
	ds_write_b32 v66, v63 offset:8184
	s_waitcnt lgkmcnt(0)
	v_ashrrev_i32_e32 v19, 31, v18
	v_lshl_add_u64 v[2:3], v[18:19], 1, v[6:7]
	ds_read2_b32 v[6:7], v15 offset0:33 offset1:41
	ds_read2_b32 v[18:19], v15 offset1:8
	ds_read2_b32 v[20:21], v15 offset0:66 offset1:74
	ds_read2_b32 v[28:29], v15 offset0:99 offset1:107
	ds_read2_b32 v[30:31], v15 offset0:132 offset1:140
	ds_read2_b32 v[32:33], v15 offset0:165 offset1:173
	ds_read2_b32 v[34:35], v15 offset0:198 offset1:206
	ds_read2_b32 v[36:37], v15 offset0:231 offset1:239
	v_or_b32_e32 v1, v26, v11
	v_lshl_add_u64 v[38:39], v[2:3], 0, v[12:13]
	v_mad_i64_i32 v[40:41], s[8:9], v1, v0, 0
	s_waitcnt lgkmcnt(6)
	v_cvt_pk_bf16_f32 v2, v18, v6
	s_waitcnt lgkmcnt(4)
	v_cvt_pk_bf16_f32 v3, v20, v28
	s_waitcnt lgkmcnt(2)
	v_cvt_pk_bf16_f32 v4, v30, v32
	s_waitcnt lgkmcnt(0)
	v_cvt_pk_bf16_f32 v5, v34, v36
	v_lshl_add_u64 v[40:41], v[40:41], 1, v[38:39]
	global_store_dwordx4 v[40:41], v[2:5], off
	v_or_b32_e32 v1, v26, v23
	v_add_u32_e32 v8, s4, v8
	v_cvt_pk_bf16_f32 v2, v19, v7
	v_cvt_pk_bf16_f32 v3, v21, v29
	v_cvt_pk_bf16_f32 v4, v31, v33
	v_cvt_pk_bf16_f32 v5, v35, v37
	ds_read2_b32 v[18:19], v15 offset0:16 offset1:24
	ds_read2_b32 v[20:21], v15 offset0:49 offset1:57
	ds_read2_b32 v[28:29], v15 offset0:82 offset1:90
	ds_read2_b32 v[30:31], v15 offset0:115 offset1:123
	ds_read2_b32 v[32:33], v15 offset0:148 offset1:156
	ds_read2_b32 v[34:35], v15 offset0:181 offset1:189
	ds_read2_b32 v[36:37], v15 offset0:214 offset1:222
	ds_read2_b32 v[40:41], v15 offset0:247 offset1:255
	v_mad_i64_i32 v[6:7], s[8:9], v1, v0, 0
	v_lshl_add_u64 v[6:7], v[6:7], 1, v[38:39]
	v_or_b32_e32 v1, v26, v24
	global_store_dwordx4 v[6:7], v[2:5], off
	v_mad_i64_i32 v[6:7], s[8:9], v1, v0, 0
	v_or_b32_e32 v1, v26, v25
	s_waitcnt lgkmcnt(6)
	v_cvt_pk_bf16_f32 v2, v18, v20
	s_waitcnt lgkmcnt(4)
	v_cvt_pk_bf16_f32 v3, v28, v30
	s_waitcnt lgkmcnt(2)
	v_cvt_pk_bf16_f32 v4, v32, v34
	s_waitcnt lgkmcnt(0)
	v_cvt_pk_bf16_f32 v5, v36, v40
	v_lshl_add_u64 v[6:7], v[6:7], 1, v[38:39]
	v_mad_i64_i32 v[0:1], s[8:9], v1, v0, 0
	global_store_dwordx4 v[6:7], v[2:5], off
	v_lshl_add_u64 v[0:1], v[0:1], 1, v[38:39]
	v_cmp_le_i32_e32 vcc, s12, v8
	v_cvt_pk_bf16_f32 v2, v19, v21
	v_cvt_pk_bf16_f32 v3, v29, v31
	v_cvt_pk_bf16_f32 v4, v33, v35
	v_cvt_pk_bf16_f32 v5, v37, v41
	global_store_dwordx4 v[0:1], v[2:5], off
	s_waitcnt lgkmcnt(0)
	s_or_b64 s[16:17], vcc, s[16:17]
	s_andn2_b64 exec, exec, s[16:17]
	s_cbranch_execnz .LBB0_557
	s_branch .LBB0_570

; #define PG8_STAGE(bufoff, gbase, voff) do { _Pragma("unroll") for (int _i = 0; _i < 2; ++_i) \
;         __builtin_amdgcn_global_load_lds((const unsigned*)((const char*)(gbase) + (voff)[_i]), (LAS unsigned*)(lds + (bufoff) + ldsw + _i * 8192), 16, 0, 0); } while (0)
; #define PG8_LDA(dst, b, h) do { _Pragma("unroll") for (int m = 0; m < 4; ++m) _Pragma("unroll") for (int k = 0; k < 2; ++k) dst[m][k] = *(const LAS bf16x8*)(lds + PG8_SA(b, h) + aoff + m * 2048 + k * 1024); } while (0)
; #define PG8_LDB(dst, b, h) do { _Pragma("unroll") for (int n = 0; n < 2; ++n) _Pragma("unroll") for (int k = 0; k < 2; ++k) dst[n][k] = *(const LAS bf16x8*)(lds + PG8_SB(b, h) + boff + n * 2048 + k * 1024); } while (0)
; #define PG8_MMA(ai, bj, At, Bt) do { __builtin_amdgcn_s_setprio(1); _Pragma("unroll") for (int m = 0; m < 4; ++m) _Pragma("unroll") for (int n = 0; n < 2; ++n) _Pragma("unroll") for (int k = 0; k < 2; ++k) \
;         acc[ai][bj][m][n] = __builtin_amdgcn_mfma_f32_16x16x32_bf16(Bt[n][k], At[m][k], acc[ai][bj][m][n], 0, 0, 0); __builtin_amdgcn_s_setprio(0); } while (0)
; #define PG8_WAIT_V(n) asm volatile("s_waitcnt vmcnt(" #n ")" ::: "memory")
; #define PG8_WAIT_L(n) asm volatile("s_waitcnt lgkmcnt(" #n ")" ::: "memory")
; #define PG8_BAR __builtin_amdgcn_s_barrier()
; #define PG8_SCHED __builtin_amdgcn_sched_barrier(0)
; template <class Epi>
; __device__ __forceinline__ void gemm_phase(LAS unsigned char* lds, const Gemm g, const StaticOrder& S, const Epi& E) {
;     ...
;             PG8_LDB(B0, 0, 0); PG8_SCHED; PG8_LDA(At, 0, 0); PG8_STAGE(PG8_SA(1, 1), a1 + hstepA, voffA);
;             PG8_WAIT_L(8); PG8_BAR; PG8_WAIT_L(0); PG8_MMA(0, 0, At, B0); PG8_BAR; PG8_SCHED;
;             PG8_LDB(B1, 0, 1); PG8_STAGE(PG8_SB(0, 0), b2, voffB);
;             PG8_BAR; PG8_WAIT_L(0); PG8_MMA(0, 1, At, B1); PG8_BAR;
;             PG8_LDA(At, 0, 1); PG8_STAGE(PG8_SA(0, 0), a2, voffA);
;             PG8_BAR; PG8_WAIT_L(0); PG8_MMA(1, 0, At, B0); PG8_BAR; PG8_SCHED;
;             PG8_STAGE(PG8_SB(0, 1), b2 + hstepB, voffB);
;             PG8_WAIT_V(6); PG8_BAR; PG8_MMA(1, 1, At, B1); PG8_BAR;
.LBB0_860:
	ds_read_b128 v[140:143], v149
	ds_read_b128 v[152:155], v149 offset:1024
	ds_read_b128 v[156:159], v149 offset:2048
	ds_read_b128 v[160:163], v149 offset:3072
	s_add_u32 s30, s28, 0x100
	s_addc_u32 s31, s29, 0
	s_cmp_eq_u32 s68, 40
	s_cselect_b32 s37, s13, s31
	s_cselect_b32 s36, s12, s30
	s_cselect_b32 s35, s15, s63
	s_cselect_b32 s34, s14, s49
	v_lshl_add_u64 v[144:145], s[28:29], 0, v[132:133]
	s_add_i32 m0, s8, 0xc000
	ds_read_b128 v[164:167], v150
	ds_read_b128 v[168:171], v150 offset:1024
	ds_read_b128 v[172:175], v150 offset:2048
	ds_read_b128 v[176:179], v150 offset:3072
	ds_read_b128 v[180:183], v150 offset:4096
	ds_read_b128 v[184:187], v150 offset:5120
	ds_read_b128 v[188:191], v150 offset:6144
	ds_read_b128 v[192:195], v150 offset:7168
	global_load_lds_dwordx4 v[144:145], off
	v_lshl_add_u64 v[144:145], s[28:29], 0, v[134:135]
	s_add_i32 m0, s8, 0xe000
	s_nop 0
	global_load_lds_dwordx4 v[144:145], off
	ds_read_b128 v[196:199], v151
	ds_read_b128 v[200:203], v151 offset:1024
	ds_read_b128 v[204:207], v151 offset:2048
	ds_read_b128 v[208:211], v151 offset:3072
	s_waitcnt lgkmcnt(0)
	s_barrier
	s_setprio 1
	v_mfma_f32_16x16x32_bf16 v[124:127], v[140:143], v[164:167], v[124:127]
	v_mfma_f32_16x16x32_bf16 v[120:123], v[156:159], v[164:167], v[120:123]
	v_mfma_f32_16x16x32_bf16 v[112:115], v[140:143], v[172:175], v[112:115]
	v_mfma_f32_16x16x32_bf16 v[104:107], v[156:159], v[172:175], v[104:107]
	v_mfma_f32_16x16x32_bf16 v[92:95], v[140:143], v[180:183], v[92:95]
	v_mfma_f32_16x16x32_bf16 v[88:91], v[156:159], v[180:183], v[88:91]
	v_mfma_f32_16x16x32_bf16 v[80:83], v[140:143], v[188:191], v[80:83]
	v_mfma_f32_16x16x32_bf16 v[72:75], v[156:159], v[188:191], v[72:75]
	v_mfma_f32_16x16x32_bf16 v[124:127], v[152:155], v[168:171], v[124:127]
	v_mfma_f32_16x16x32_bf16 v[120:123], v[160:163], v[168:171], v[120:123]
	v_mfma_f32_16x16x32_bf16 v[112:115], v[152:155], v[176:179], v[112:115]
	v_mfma_f32_16x16x32_bf16 v[104:107], v[160:163], v[176:179], v[104:107]
	v_mfma_f32_16x16x32_bf16 v[92:95], v[152:155], v[184:187], v[92:95]
	v_mfma_f32_16x16x32_bf16 v[88:91], v[160:163], v[184:187], v[88:91]
	v_mfma_f32_16x16x32_bf16 v[80:83], v[152:155], v[192:195], v[80:83]
	v_mfma_f32_16x16x32_bf16 v[72:75], v[160:163], v[192:195], v[72:75]
	v_mfma_f32_16x16x32_bf16 v[116:119], v[196:199], v[164:167], v[116:119]
	v_mfma_f32_16x16x32_bf16 v[108:111], v[204:207], v[164:167], v[108:111]
	v_mfma_f32_16x16x32_bf16 v[100:103], v[196:199], v[172:175], v[100:103]
	v_mfma_f32_16x16x32_bf16 v[96:99], v[204:207], v[172:175], v[96:99]
	v_mfma_f32_16x16x32_bf16 v[84:87], v[196:199], v[180:183], v[84:87]
	v_mfma_f32_16x16x32_bf16 v[76:79], v[204:207], v[180:183], v[76:79]
	v_mfma_f32_16x16x32_bf16 v[68:71], v[196:199], v[188:191], v[68:71]
	v_mfma_f32_16x16x32_bf16 v[64:67], v[204:207], v[188:191], v[64:67]
	v_mfma_f32_16x16x32_bf16 v[116:119], v[200:203], v[168:171], v[116:119]
	v_mfma_f32_16x16x32_bf16 v[108:111], v[208:211], v[168:171], v[108:111]
	v_mfma_f32_16x16x32_bf16 v[100:103], v[200:203], v[176:179], v[100:103]
	v_mfma_f32_16x16x32_bf16 v[96:99], v[208:211], v[176:179], v[96:99]
	v_mfma_f32_16x16x32_bf16 v[84:87], v[200:203], v[184:187], v[84:87]
	v_mfma_f32_16x16x32_bf16 v[76:79], v[208:211], v[184:187], v[76:79]
	v_mfma_f32_16x16x32_bf16 v[68:71], v[200:203], v[192:195], v[68:71]
	v_mfma_f32_16x16x32_bf16 v[64:67], v[208:211], v[192:195], v[64:67]
	s_setprio 0
	s_barrier
	s_nop 1
	ds_read_b128 v[164:167], v150 offset:16384
	ds_read_b128 v[168:171], v150 offset:17408
	ds_read_b128 v[172:175], v150 offset:18432
	ds_read_b128 v[176:179], v150 offset:19456
	ds_read_b128 v[180:183], v150 offset:20480
	ds_read_b128 v[184:187], v150 offset:21504
	ds_read_b128 v[188:191], v150 offset:22528
	ds_read_b128 v[192:195], v150 offset:23552
	s_add_i32 s28, s43, s7
	v_lshl_add_u64 v[144:145], s[34:35], 0, v[128:129]
	s_mov_b32 m0, s28
	s_nop 0
	global_load_lds_dwordx4 v[144:145], off
	v_lshl_add_u64 v[212:213], s[34:35], 0, v[130:131]
	s_add_i32 m0, s28, 0x2000
	s_nop 0
	global_load_lds_dwordx4 v[212:213], off
	s_mov_b32 m0, s8
	v_lshl_add_u64 v[214:215], s[36:37], 0, v[128:129]
	global_load_lds_dwordx4 v[214:215], off
	v_lshl_add_u64 v[216:217], s[36:37], 0, v[130:131]
	s_mov_b32 m0, s9
	s_nop 0
	global_load_lds_dwordx4 v[216:217], off
	s_add_u32 s28, s34, 0xb0000
	s_addc_u32 s29, s35, 0
	s_add_i32 s69, s44, s7
	v_lshl_add_u64 v[254:255], s[28:29], 0, v[128:129]
	s_mov_b32 m0, s69
	s_nop 0
	global_load_lds_dwordx4 v[254:255], off
	v_lshl_add_u64 v[254:255], s[28:29], 0, v[130:131]
	s_add_i32 m0, s69, 0x2000
	s_nop 0
	global_load_lds_dwordx4 v[254:255], off
	s_waitcnt vmcnt(6)
	s_waitcnt lgkmcnt(0)
	s_barrier
; #define PG8_STAGE(bufoff, gbase, voff) do { _Pragma("unroll") for (int _i = 0; _i < 2; ++_i) \
;         __builtin_amdgcn_global_load_lds((const unsigned*)((const char*)(gbase) + (voff)[_i]), (LAS unsigned*)(lds + (bufoff) + ldsw + _i * 8192), 16, 0, 0); } while (0)
; #define PG8_LDA(dst, b, h) do { _Pragma("unroll") for (int m = 0; m < 4; ++m) _Pragma("unroll") for (int k = 0; k < 2; ++k) dst[m][k] = *(const LAS bf16x8*)(lds + PG8_SA(b, h) + aoff + m * 2048 + k * 1024); } while (0)
; #define PG8_LDB(dst, b, h) do { _Pragma("unroll") for (int n = 0; n < 2; ++n) _Pragma("unroll") for (int k = 0; k < 2; ++k) dst[n][k] = *(const LAS bf16x8*)(lds + PG8_SB(b, h) + boff + n * 2048 + k * 1024); } while (0)
; #define PG8_MMA(ai, bj, At, Bt) do { __builtin_amdgcn_s_setprio(1); _Pragma("unroll") for (int m = 0; m < 4; ++m) _Pragma("unroll") for (int n = 0; n < 2; ++n) _Pragma("unroll") for (int k = 0; k < 2; ++k) \
;         acc[ai][bj][m][n] = __builtin_amdgcn_mfma_f32_16x16x32_bf16(Bt[n][k], At[m][k], acc[ai][bj][m][n], 0, 0, 0); __builtin_amdgcn_s_setprio(0); } while (0)
; #define PG8_WAIT_V(n) asm volatile("s_waitcnt vmcnt(" #n ")" ::: "memory")
; #define PG8_WAIT_L(n) asm volatile("s_waitcnt lgkmcnt(" #n ")" ::: "memory")
; #define PG8_BAR __builtin_amdgcn_s_barrier()
; #define PG8_SCHED __builtin_amdgcn_sched_barrier(0)
; template <class Epi>
; __device__ __forceinline__ void gemm_phase(LAS unsigned char* lds, const Gemm g, const StaticOrder& S, const Epi& E) {
;     ...
;             PG8_WAIT_V(6); PG8_BAR; PG8_MMA(1, 1, At, B1); PG8_BAR;
;             PG8_LDB(B0, 1, 0); PG8_SCHED; PG8_LDA(At, 1, 0); PG8_STAGE(PG8_SA(0, 1), a2 + hstepA, voffA);
;             PG8_WAIT_L(8); PG8_BAR; PG8_WAIT_L(0); PG8_MMA(0, 0, At, B0); PG8_BAR; PG8_SCHED;
;             PG8_LDB(B1, 1, 1); PG8_STAGE(PG8_SB(1, 0), b3, voffB);
;             PG8_BAR; PG8_WAIT_L(0); PG8_MMA(0, 1, At, B1); PG8_BAR;
	s_setprio 1
	v_mfma_f32_16x16x32_bf16 v[60:63], v[140:143], v[164:167], v[60:63]
	v_mfma_f32_16x16x32_bf16 v[56:59], v[156:159], v[164:167], v[56:59]
	v_mfma_f32_16x16x32_bf16 v[48:51], v[140:143], v[172:175], v[48:51]
	v_mfma_f32_16x16x32_bf16 v[40:43], v[156:159], v[172:175], v[40:43]
	v_mfma_f32_16x16x32_bf16 v[28:31], v[140:143], v[180:183], v[28:31]
	v_mfma_f32_16x16x32_bf16 v[24:27], v[156:159], v[180:183], v[24:27]
	v_mfma_f32_16x16x32_bf16 v[16:19], v[140:143], v[188:191], v[16:19]
	v_mfma_f32_16x16x32_bf16 v[8:11], v[156:159], v[188:191], v[8:11]
	v_mfma_f32_16x16x32_bf16 v[60:63], v[152:155], v[168:171], v[60:63]
	v_mfma_f32_16x16x32_bf16 v[56:59], v[160:163], v[168:171], v[56:59]
	v_mfma_f32_16x16x32_bf16 v[48:51], v[152:155], v[176:179], v[48:51]
	v_mfma_f32_16x16x32_bf16 v[40:43], v[160:163], v[176:179], v[40:43]
	v_mfma_f32_16x16x32_bf16 v[28:31], v[152:155], v[184:187], v[28:31]
	v_mfma_f32_16x16x32_bf16 v[24:27], v[160:163], v[184:187], v[24:27]
	v_mfma_f32_16x16x32_bf16 v[16:19], v[152:155], v[192:195], v[16:19]
	v_mfma_f32_16x16x32_bf16 v[8:11], v[160:163], v[192:195], v[8:11]
	v_mfma_f32_16x16x32_bf16 v[52:55], v[196:199], v[164:167], v[52:55]
	v_mfma_f32_16x16x32_bf16 v[44:47], v[204:207], v[164:167], v[44:47]
	v_mfma_f32_16x16x32_bf16 v[36:39], v[196:199], v[172:175], v[36:39]
	v_mfma_f32_16x16x32_bf16 v[32:35], v[204:207], v[172:175], v[32:35]
	v_mfma_f32_16x16x32_bf16 v[20:23], v[196:199], v[180:183], v[20:23]
	v_mfma_f32_16x16x32_bf16 v[12:15], v[204:207], v[180:183], v[12:15]
	v_mfma_f32_16x16x32_bf16 v[4:7], v[196:199], v[188:191], v[4:7]
	v_mfma_f32_16x16x32_bf16 v[0:3], v[204:207], v[188:191], v[0:3]
	v_mfma_f32_16x16x32_bf16 v[52:55], v[200:203], v[168:171], v[52:55]
	v_mfma_f32_16x16x32_bf16 v[44:47], v[208:211], v[168:171], v[44:47]
	v_mfma_f32_16x16x32_bf16 v[36:39], v[200:203], v[176:179], v[36:39]
	v_mfma_f32_16x16x32_bf16 v[32:35], v[208:211], v[176:179], v[32:35]
	v_mfma_f32_16x16x32_bf16 v[20:23], v[200:203], v[184:187], v[20:23]
	v_mfma_f32_16x16x32_bf16 v[12:15], v[208:211], v[184:187], v[12:15]
	v_mfma_f32_16x16x32_bf16 v[4:7], v[200:203], v[192:195], v[4:7]
	v_mfma_f32_16x16x32_bf16 v[0:3], v[208:211], v[192:195], v[0:3]
	s_setprio 0
	s_add_i32 s69, 0, 0x18000
	v_add_u32_e32 v160, s69, v147
	s_barrier
	ds_read_b128 v[140:143], v160
	ds_read_b128 v[152:155], v160 offset:1024
	ds_read_b128 v[156:159], v160 offset:2048
	ds_read_b128 v[160:163], v160 offset:3072
	s_add_u32 s28, s36, 0xb0000
	s_addc_u32 s29, s37, 0
	s_mov_b32 m0, s38
	v_lshl_add_u64 v[196:197], s[28:29], 0, v[128:129]
	ds_read_b128 v[164:167], v150 offset:32768
	ds_read_b128 v[168:171], v150 offset:33792
	ds_read_b128 v[172:175], v150 offset:34816
	ds_read_b128 v[176:179], v150 offset:35840
	ds_read_b128 v[180:183], v150 offset:36864
	ds_read_b128 v[184:187], v150 offset:37888
	ds_read_b128 v[188:191], v150 offset:38912
	ds_read_b128 v[192:195], v150 offset:39936
	global_load_lds_dwordx4 v[196:197], off
	v_lshl_add_u64 v[196:197], s[28:29], 0, v[130:131]
	s_mov_b32 m0, s39
	s_nop 0
	global_load_lds_dwordx4 v[196:197], off
	s_add_i32 s36, 0, 0x1c000
	v_add_u32_e32 v208, s36, v147
	ds_read_b128 v[196:199], v208
	ds_read_b128 v[200:203], v208 offset:1024
	ds_read_b128 v[204:207], v208 offset:2048
	ds_read_b128 v[208:211], v208 offset:3072
	s_waitcnt lgkmcnt(0)
	s_barrier
	s_setprio 1
	v_mfma_f32_16x16x32_bf16 v[124:127], v[140:143], v[164:167], v[124:127]
	v_mfma_f32_16x16x32_bf16 v[120:123], v[156:159], v[164:167], v[120:123]
	v_mfma_f32_16x16x32_bf16 v[112:115], v[140:143], v[172:175], v[112:115]
	v_mfma_f32_16x16x32_bf16 v[104:107], v[156:159], v[172:175], v[104:107]
	v_mfma_f32_16x16x32_bf16 v[92:95], v[140:143], v[180:183], v[92:95]
	v_mfma_f32_16x16x32_bf16 v[88:91], v[156:159], v[180:183], v[88:91]
	v_mfma_f32_16x16x32_bf16 v[80:83], v[140:143], v[188:191], v[80:83]
	v_mfma_f32_16x16x32_bf16 v[72:75], v[156:159], v[188:191], v[72:75]
	v_mfma_f32_16x16x32_bf16 v[124:127], v[152:155], v[168:171], v[124:127]
	v_mfma_f32_16x16x32_bf16 v[120:123], v[160:163], v[168:171], v[120:123]
	v_mfma_f32_16x16x32_bf16 v[112:115], v[152:155], v[176:179], v[112:115]
	v_mfma_f32_16x16x32_bf16 v[104:107], v[160:163], v[176:179], v[104:107]
	v_mfma_f32_16x16x32_bf16 v[92:95], v[152:155], v[184:187], v[92:95]
	v_mfma_f32_16x16x32_bf16 v[88:91], v[160:163], v[184:187], v[88:91]
	v_mfma_f32_16x16x32_bf16 v[80:83], v[152:155], v[192:195], v[80:83]
	v_mfma_f32_16x16x32_bf16 v[72:75], v[160:163], v[192:195], v[72:75]
	v_mfma_f32_16x16x32_bf16 v[116:119], v[196:199], v[164:167], v[116:119]
	v_mfma_f32_16x16x32_bf16 v[108:111], v[204:207], v[164:167], v[108:111]
	v_mfma_f32_16x16x32_bf16 v[100:103], v[196:199], v[172:175], v[100:103]
	v_mfma_f32_16x16x32_bf16 v[96:99], v[204:207], v[172:175], v[96:99]
	v_mfma_f32_16x16x32_bf16 v[84:87], v[196:199], v[180:183], v[84:87]
	v_mfma_f32_16x16x32_bf16 v[76:79], v[204:207], v[180:183], v[76:79]
	v_mfma_f32_16x16x32_bf16 v[68:71], v[196:199], v[188:191], v[68:71]
	v_mfma_f32_16x16x32_bf16 v[64:67], v[204:207], v[188:191], v[64:67]
	v_mfma_f32_16x16x32_bf16 v[116:119], v[200:203], v[168:171], v[116:119]
	v_mfma_f32_16x16x32_bf16 v[108:111], v[208:211], v[168:171], v[108:111]
	v_mfma_f32_16x16x32_bf16 v[100:103], v[200:203], v[176:179], v[100:103]
	v_mfma_f32_16x16x32_bf16 v[96:99], v[208:211], v[176:179], v[96:99]
	v_mfma_f32_16x16x32_bf16 v[84:87], v[200:203], v[184:187], v[84:87]
	v_mfma_f32_16x16x32_bf16 v[76:79], v[208:211], v[184:187], v[76:79]
	v_mfma_f32_16x16x32_bf16 v[68:71], v[200:203], v[192:195], v[68:71]
	v_mfma_f32_16x16x32_bf16 v[64:67], v[208:211], v[192:195], v[64:67]
	s_setprio 0
	s_barrier
; #define PG8_STAGE(bufoff, gbase, voff) do { _Pragma("unroll") for (int _i = 0; _i < 2; ++_i) \
;         __builtin_amdgcn_global_load_lds((const unsigned*)((const char*)(gbase) + (voff)[_i]), (LAS unsigned*)(lds + (bufoff) + ldsw + _i * 8192), 16, 0, 0); } while (0)
; #define PG8_WAIT_V(n) asm volatile("s_waitcnt vmcnt(" #n ")" ::: "memory")
; #define PG8_WAIT_L(n) asm volatile("s_waitcnt lgkmcnt(" #n ")" ::: "memory")
; #define PG8_BAR __builtin_amdgcn_s_barrier()
; template <class Epi>
; __device__ __forceinline__ void gemm_phase(LAS unsigned char* lds, const Gemm g, const StaticOrder& S, const Epi& E) {
;     ...
;             PG8_LDA(At, 1, 1); PG8_STAGE(PG8_SA(1, 0), a3, voffA);
;             PG8_BAR; PG8_WAIT_L(0); PG8_MMA(1, 0, At, B0); PG8_BAR; PG8_SCHED;
;             PG8_STAGE(PG8_SB(1, 1), b3 + hstepB, voffB);
;             PG8_WAIT_V(6); PG8_BAR; PG8_MMA(1, 1, At, B1); PG8_BAR;
;     __device__ __forceinline__ void operator()(AccRef acc, const Unit& u, int wr, int wc, int fr, int fq) const {
;         const int row0 = u.pm * 256 + wr * 64 + fr, col0 = u.pn * 256 + wc * 32 + 4 * fq;
;         f32x4 sv[2][2], bv[2][2];
; #pragma unroll
;         for (int bj = 0; bj < 2; ++bj)
; #pragma unroll
;             for (int n = 0; n < 2; ++n) {
;                 sv[bj][n] = scale ? *(const f32x4*)(scale + col0 + bj * 128 + n * 16) : (f32x4){1.f, 1.f, 1.f, 1.f};
;                 bv[bj][n] = bias ? *(const f32x4*)(bias + col0 + bj * 128 + n * 16) : (f32x4){0.f, 0.f, 0.f, 0.f}; }
; #pragma unroll
;         for (int ai = 0; ai < 2; ++ai)
; #pragma unroll
;             for (int mh = 0; mh < 2; ++mh) {
;                 f32x4 bs[2][2][2];
; #pragma unroll
;                 for (int m = 0; m < 2; ++m)
; #pragma unroll
;                     for (int bj = 0; bj < 2; ++bj)
; #pragma unroll
;                         for (int n = 0; n < 2; ++n) bs[m][bj][n] = *(const f32x4*)(base + (size_t)(row0 + ai * 128 + (2 * mh + m) * 16) * D + col0 + bj * 128 + n * 16);
; #pragma unroll
;                 for (int m = 0; m < 2; ++m)
; #pragma unroll
;                     for (int bj = 0; bj < 2; ++bj)
; #pragma unroll
;                         for (int n = 0; n < 2; ++n) *(f32x4*)(out + (size_t)(row0 + ai * 128 + (2 * mh + m) * 16) * D + col0 + bj * 128 + n * 16) = bs[m][bj][n] + sv[bj][n] * (acc[ai][bj][2 * mh + m][n] + bv[bj][n]);
;                 asm volatile("" ::: "memory"); }
	s_nop 1
	ds_read_b128 v[164:167], v150 offset:49152
	ds_read_b128 v[168:171], v150 offset:50176
	ds_read_b128 v[172:175], v150 offset:51200
	ds_read_b128 v[176:179], v150 offset:52224
	ds_read_b128 v[180:183], v150 offset:53248
	ds_read_b128 v[184:187], v150 offset:54272
	ds_read_b128 v[188:191], v150 offset:55296
	ds_read_b128 v[192:195], v150 offset:56320
	s_add_i32 s28, s69, s7
	v_lshl_add_u64 v[254:255], v[144:145], 0, s[20:21]
	s_mov_b32 m0, s28
	s_nop 0
	global_load_lds_dwordx4 v[254:255], off
	v_lshl_add_u64 v[254:255], v[212:213], 0, s[20:21]
	s_add_i32 m0, s28, 0x2000
	s_nop 0
	global_load_lds_dwordx4 v[254:255], off
	s_mov_b32 m0, s41
	v_lshl_add_u64 v[254:255], v[214:215], 0, s[20:21]
	global_load_lds_dwordx4 v[254:255], off
	v_lshl_add_u64 v[144:145], v[216:217], 0, s[20:21]
	s_mov_b32 m0, s42
	s_nop 0
	global_load_lds_dwordx4 v[144:145], off
	s_add_u32 s28, s34, 0xb0080
	s_addc_u32 s29, s35, 0
	s_add_i32 s34, s36, s7
	v_lshl_add_u64 v[254:255], s[28:29], 0, v[128:129]
	s_mov_b32 m0, s34
	s_nop 0
	global_load_lds_dwordx4 v[254:255], off
	v_lshl_add_u64 v[254:255], s[28:29], 0, v[130:131]
	s_add_i32 m0, s34, 0x2000
	s_nop 0
	global_load_lds_dwordx4 v[254:255], off
	s_waitcnt vmcnt(6)
	s_waitcnt lgkmcnt(0)
	s_barrier
	s_setprio 1
	v_mfma_f32_16x16x32_bf16 v[60:63], v[140:143], v[164:167], v[60:63]
	v_mfma_f32_16x16x32_bf16 v[56:59], v[156:159], v[164:167], v[56:59]
	v_mfma_f32_16x16x32_bf16 v[48:51], v[140:143], v[172:175], v[48:51]
	v_mfma_f32_16x16x32_bf16 v[40:43], v[156:159], v[172:175], v[40:43]
	v_mfma_f32_16x16x32_bf16 v[28:31], v[140:143], v[180:183], v[28:31]
	v_mfma_f32_16x16x32_bf16 v[24:27], v[156:159], v[180:183], v[24:27]
	v_mfma_f32_16x16x32_bf16 v[16:19], v[140:143], v[188:191], v[16:19]
	v_mfma_f32_16x16x32_bf16 v[8:11], v[156:159], v[188:191], v[8:11]
	v_mfma_f32_16x16x32_bf16 v[60:63], v[152:155], v[168:171], v[60:63]
	v_mfma_f32_16x16x32_bf16 v[56:59], v[160:163], v[168:171], v[56:59]
	v_mfma_f32_16x16x32_bf16 v[48:51], v[152:155], v[176:179], v[48:51]
	v_mfma_f32_16x16x32_bf16 v[40:43], v[160:163], v[176:179], v[40:43]
	v_mfma_f32_16x16x32_bf16 v[28:31], v[152:155], v[184:187], v[28:31]
	v_mfma_f32_16x16x32_bf16 v[24:27], v[160:163], v[184:187], v[24:27]
	v_mfma_f32_16x16x32_bf16 v[16:19], v[152:155], v[192:195], v[16:19]
	v_mfma_f32_16x16x32_bf16 v[8:11], v[160:163], v[192:195], v[8:11]
	v_mfma_f32_16x16x32_bf16 v[52:55], v[196:199], v[164:167], v[52:55]
	v_mfma_f32_16x16x32_bf16 v[44:47], v[204:207], v[164:167], v[44:47]
	v_mfma_f32_16x16x32_bf16 v[36:39], v[196:199], v[172:175], v[36:39]
	v_mfma_f32_16x16x32_bf16 v[32:35], v[204:207], v[172:175], v[32:35]
	v_mfma_f32_16x16x32_bf16 v[20:23], v[196:199], v[180:183], v[20:23]
	v_mfma_f32_16x16x32_bf16 v[12:15], v[204:207], v[180:183], v[12:15]
	v_mfma_f32_16x16x32_bf16 v[4:7], v[196:199], v[188:191], v[4:7]
	v_mfma_f32_16x16x32_bf16 v[0:3], v[204:207], v[188:191], v[0:3]
	v_mfma_f32_16x16x32_bf16 v[52:55], v[200:203], v[168:171], v[52:55]
	v_mfma_f32_16x16x32_bf16 v[44:47], v[208:211], v[168:171], v[44:47]
	v_mfma_f32_16x16x32_bf16 v[36:39], v[200:203], v[176:179], v[36:39]
	v_mfma_f32_16x16x32_bf16 v[32:35], v[208:211], v[176:179], v[32:35]
	v_mfma_f32_16x16x32_bf16 v[20:23], v[200:203], v[184:187], v[20:23]
	v_mfma_f32_16x16x32_bf16 v[12:15], v[208:211], v[184:187], v[12:15]
	v_mfma_f32_16x16x32_bf16 v[4:7], v[200:203], v[192:195], v[4:7]
	v_mfma_f32_16x16x32_bf16 v[0:3], v[208:211], v[192:195], v[0:3]
	s_setprio 0
	s_add_i32 s68, s68, 2
	s_add_u32 s49, s49, 0x100
	s_addc_u32 s63, s63, 0
	s_cmp_gt_u32 s68, 41
	s_mov_b64 s[28:29], s[30:31]
	s_barrier
	s_cbranch_scc0 .LBB0_860
	v_lshl_or_b32 v144, s47, 8, v148
	v_lshl_add_u32 v145, s48, 8, v146
	v_lshlrev_b32_e32 v144, 2, v144
	v_lshl_add_u32 v145, v145, 12, v144
	v_add_u32_e32 v216, 0x10000, v145
	v_add_u32_e32 v217, 0x20000, v145
	v_add_u32_e32 v218, 0x30000, v145
	v_add_u32_e32 v232, 0x80000, v145
	v_add_u32_e32 v233, 0x90000, v145
	v_add_u32_e32 v235, 0xa0000, v145
	v_add_u32_e32 v253, 0xb0000, v145
	s_and_b64 vcc, exec, s[10:11]
	s_mov_b32 s47, s45
	s_mov_b32 s48, s46
	s_mov_b64 s[30:31], s[14:15]
	s_mov_b64 s[28:29], s[12:13]
	global_load_dwordx4 v[140:143], v145, s[52:53]
	global_load_dwordx4 v[152:155], v145, s[52:53] offset:64
	global_load_dwordx4 v[156:159], v145, s[52:53] offset:512
	global_load_dwordx4 v[160:163], v145, s[52:53] offset:576
	global_load_dwordx4 v[164:167], v216, s[52:53]
	global_load_dwordx4 v[168:171], v216, s[52:53] offset:64
	global_load_dwordx4 v[172:175], v216, s[52:53] offset:512
	global_load_dwordx4 v[176:179], v216, s[52:53] offset:576
	global_load_dwordx4 v[180:183], v217, s[52:53]
	global_load_dwordx4 v[184:187], v217, s[52:53] offset:64
	global_load_dwordx4 v[188:191], v217, s[52:53] offset:512
	global_load_dwordx4 v[192:195], v217, s[52:53] offset:576
	global_load_dwordx4 v[196:199], v218, s[52:53]
	global_load_dwordx4 v[200:203], v218, s[52:53] offset:64
	global_load_dwordx4 v[204:207], v218, s[52:53] offset:512
	global_load_dwordx4 v[208:211], v218, s[52:53] offset:576
	global_load_dwordx4 v[212:215], v232, s[52:53]
	global_load_dwordx4 v[220:223], v232, s[52:53] offset:64
	global_load_dwordx4 v[224:227], v232, s[52:53] offset:512
	global_load_dwordx4 v[228:231], v232, s[52:53] offset:576
	global_load_dwordx4 v[236:239], v233, s[52:53]
	global_load_dwordx4 v[240:243], v233, s[52:53] offset:64
	global_load_dwordx4 v[244:247], v233, s[52:53] offset:512
	global_load_dwordx4 v[248:251], v233, s[52:53] offset:576
	v_pk_add_f32 v[124:125], v[124:125], 0 op_sel_hi:[1,0]
	v_pk_add_f32 v[126:127], v[126:127], 0 op_sel_hi:[1,0]
	v_pk_add_f32 v[120:121], v[120:121], 0 op_sel_hi:[1,0]
;     __device__ __forceinline__ void operator()(AccRef acc, const Unit& u, int wr, int wc, int fr, int fq) const {
;     ...
;         for (int ai = 0; ai < 2; ++ai)
; #pragma unroll
;             for (int mh = 0; mh < 2; ++mh) {
;                 f32x4 bs[2][2][2];
; #pragma unroll
;                 for (int m = 0; m < 2; ++m)
; #pragma unroll
;                     for (int bj = 0; bj < 2; ++bj)
; #pragma unroll
;                         for (int n = 0; n < 2; ++n) bs[m][bj][n] = *(const f32x4*)(base + (size_t)(row0 + ai * 128 + (2 * mh + m) * 16) * D + col0 + bj * 128 + n * 16);
; #pragma unroll
;                 for (int m = 0; m < 2; ++m)
; #pragma unroll
;                     for (int bj = 0; bj < 2; ++bj)
; #pragma unroll
;                         for (int n = 0; n < 2; ++n) *(f32x4*)(out + (size_t)(row0 + ai * 128 + (2 * mh + m) * 16) * D + col0 + bj * 128 + n * 16) = bs[m][bj][n] + sv[bj][n] * (acc[ai][bj][2 * mh + m][n] + bv[bj][n]);
;                 asm volatile("" ::: "memory"); }
	v_pk_add_f32 v[122:123], v[122:123], 0 op_sel_hi:[1,0]
	v_pk_add_f32 v[116:117], v[116:117], 0 op_sel_hi:[1,0]
	v_pk_add_f32 v[118:119], v[118:119], 0 op_sel_hi:[1,0]
	v_pk_add_f32 v[108:109], v[108:109], 0 op_sel_hi:[1,0]
	v_pk_add_f32 v[110:111], v[110:111], 0 op_sel_hi:[1,0]
	v_pk_add_f32 v[112:113], v[112:113], 0 op_sel_hi:[1,0]
	v_pk_add_f32 v[114:115], v[114:115], 0 op_sel_hi:[1,0]
	v_pk_add_f32 v[104:105], v[104:105], 0 op_sel_hi:[1,0]
	v_pk_add_f32 v[106:107], v[106:107], 0 op_sel_hi:[1,0]
	v_pk_add_f32 v[100:101], v[100:101], 0 op_sel_hi:[1,0]
	v_pk_add_f32 v[102:103], v[102:103], 0 op_sel_hi:[1,0]
	v_pk_add_f32 v[96:97], v[96:97], 0 op_sel_hi:[1,0]
	v_pk_add_f32 v[98:99], v[98:99], 0 op_sel_hi:[1,0]
	v_pk_add_f32 v[92:93], v[92:93], 0 op_sel_hi:[1,0]
	v_pk_add_f32 v[94:95], v[94:95], 0 op_sel_hi:[1,0]
	v_pk_add_f32 v[88:89], v[88:89], 0 op_sel_hi:[1,0]
	v_pk_add_f32 v[90:91], v[90:91], 0 op_sel_hi:[1,0]
	v_pk_add_f32 v[84:85], v[84:85], 0 op_sel_hi:[1,0]
	v_pk_add_f32 v[86:87], v[86:87], 0 op_sel_hi:[1,0]
	v_pk_add_f32 v[76:77], v[76:77], 0 op_sel_hi:[1,0]
	v_pk_add_f32 v[78:79], v[78:79], 0 op_sel_hi:[1,0]
	v_pk_add_f32 v[80:81], v[80:81], 0 op_sel_hi:[1,0]
	v_pk_add_f32 v[82:83], v[82:83], 0 op_sel_hi:[1,0]
	v_pk_add_f32 v[72:73], v[72:73], 0 op_sel_hi:[1,0]
	v_pk_add_f32 v[74:75], v[74:75], 0 op_sel_hi:[1,0]
	v_pk_add_f32 v[68:69], v[68:69], 0 op_sel_hi:[1,0]
	v_pk_add_f32 v[70:71], v[70:71], 0 op_sel_hi:[1,0]
	v_pk_add_f32 v[64:65], v[64:65], 0 op_sel_hi:[1,0]
	v_pk_add_f32 v[66:67], v[66:67], 0 op_sel_hi:[1,0]
	v_pk_add_f32 v[60:61], v[60:61], 0 op_sel_hi:[1,0]
	v_pk_add_f32 v[62:63], v[62:63], 0 op_sel_hi:[1,0]
	v_pk_add_f32 v[56:57], v[56:57], 0 op_sel_hi:[1,0]
	v_pk_add_f32 v[58:59], v[58:59], 0 op_sel_hi:[1,0]
	v_pk_add_f32 v[52:53], v[52:53], 0 op_sel_hi:[1,0]
	v_pk_add_f32 v[54:55], v[54:55], 0 op_sel_hi:[1,0]
	v_pk_add_f32 v[44:45], v[44:45], 0 op_sel_hi:[1,0]
	v_pk_add_f32 v[46:47], v[46:47], 0 op_sel_hi:[1,0]
	v_pk_add_f32 v[48:49], v[48:49], 0 op_sel_hi:[1,0]
	v_pk_add_f32 v[50:51], v[50:51], 0 op_sel_hi:[1,0]
	v_pk_add_f32 v[40:41], v[40:41], 0 op_sel_hi:[1,0]
	v_pk_add_f32 v[42:43], v[42:43], 0 op_sel_hi:[1,0]
	v_pk_add_f32 v[36:37], v[36:37], 0 op_sel_hi:[1,0]
	v_pk_add_f32 v[38:39], v[38:39], 0 op_sel_hi:[1,0]
	v_pk_add_f32 v[32:33], v[32:33], 0 op_sel_hi:[1,0]
	v_pk_add_f32 v[34:35], v[34:35], 0 op_sel_hi:[1,0]
	v_pk_add_f32 v[28:29], v[28:29], 0 op_sel_hi:[1,0]
	v_pk_add_f32 v[30:31], v[30:31], 0 op_sel_hi:[1,0]
	v_pk_add_f32 v[24:25], v[24:25], 0 op_sel_hi:[1,0]
	v_pk_add_f32 v[26:27], v[26:27], 0 op_sel_hi:[1,0]
	v_pk_add_f32 v[20:21], v[20:21], 0 op_sel_hi:[1,0]
	v_pk_add_f32 v[22:23], v[22:23], 0 op_sel_hi:[1,0]
	v_pk_add_f32 v[12:13], v[12:13], 0 op_sel_hi:[1,0]
	v_pk_add_f32 v[14:15], v[14:15], 0 op_sel_hi:[1,0]
	v_pk_add_f32 v[16:17], v[16:17], 0 op_sel_hi:[1,0]
	v_pk_add_f32 v[18:19], v[18:19], 0 op_sel_hi:[1,0]
	v_pk_add_f32 v[8:9], v[8:9], 0 op_sel_hi:[1,0]
	v_pk_add_f32 v[10:11], v[10:11], 0 op_sel_hi:[1,0]
	v_pk_add_f32 v[4:5], v[4:5], 0 op_sel_hi:[1,0]
	v_pk_add_f32 v[6:7], v[6:7], 0 op_sel_hi:[1,0]
	v_pk_add_f32 v[0:1], v[0:1], 0 op_sel_hi:[1,0]
	v_pk_add_f32 v[2:3], v[2:3], 0 op_sel_hi:[1,0]
	s_waitcnt vmcnt(16)
	v_pk_add_f32 v[124:125], v[124:125], v[140:141]
	v_pk_add_f32 v[126:127], v[126:127], v[142:143]
	v_pk_add_f32 v[120:121], v[120:121], v[152:153]
	v_pk_add_f32 v[122:123], v[122:123], v[154:155]
	v_pk_add_f32 v[116:117], v[116:117], v[156:157]
	v_pk_add_f32 v[118:119], v[118:119], v[158:159]
	v_pk_add_f32 v[108:109], v[108:109], v[160:161]
	v_pk_add_f32 v[110:111], v[110:111], v[162:163]
	v_pk_add_f32 v[112:113], v[112:113], v[164:165]
	v_pk_add_f32 v[114:115], v[114:115], v[166:167]
	v_pk_add_f32 v[104:105], v[104:105], v[168:169]
	v_pk_add_f32 v[106:107], v[106:107], v[170:171]
	v_pk_add_f32 v[100:101], v[100:101], v[172:173]
	v_pk_add_f32 v[102:103], v[102:103], v[174:175]
	v_pk_add_f32 v[96:97], v[96:97], v[176:177]
	v_pk_add_f32 v[98:99], v[98:99], v[178:179]
	global_store_dwordx4 v145, v[124:127], s[52:53]
	global_store_dwordx4 v145, v[120:123], s[52:53] offset:64
	global_store_dwordx4 v145, v[116:119], s[52:53] offset:512
	global_store_dwordx4 v145, v[108:111], s[52:53] offset:576
	global_store_dwordx4 v216, v[112:115], s[52:53]
	global_store_dwordx4 v216, v[104:107], s[52:53] offset:64
	global_store_dwordx4 v216, v[100:103], s[52:53] offset:512
	global_store_dwordx4 v216, v[96:99], s[52:53] offset:576
	global_load_dwordx4 v[140:143], v235, s[52:53]
	global_load_dwordx4 v[152:155], v235, s[52:53] offset:64
	global_load_dwordx4 v[156:159], v235, s[52:53] offset:512
	global_load_dwordx4 v[160:163], v235, s[52:53] offset:576
	global_load_dwordx4 v[164:167], v253, s[52:53]
	global_load_dwordx4 v[168:171], v253, s[52:53] offset:64
	global_load_dwordx4 v[172:175], v253, s[52:53] offset:512
	global_load_dwordx4 v[176:179], v253, s[52:53] offset:576
	s_waitcnt vmcnt(24)
;     __device__ __forceinline__ void operator()(AccRef acc, const Unit& u, int wr, int wc, int fr, int fq) const {
;     ...
;                         for (int n = 0; n < 2; ++n) bs[m][bj][n] = *(const f32x4*)(base + (size_t)(row0 + ai * 128 + (2 * mh + m) * 16) * D + col0 + bj * 128 + n * 16);
; #pragma unroll
;                 for (int m = 0; m < 2; ++m)
; #pragma unroll
;                     for (int bj = 0; bj < 2; ++bj)
; #pragma unroll
;                         for (int n = 0; n < 2; ++n) *(f32x4*)(out + (size_t)(row0 + ai * 128 + (2 * mh + m) * 16) * D + col0 + bj * 128 + n * 16) = bs[m][bj][n] + sv[bj][n] * (acc[ai][bj][2 * mh + m][n] + bv[bj][n]);
;                 asm volatile("" ::: "memory"); }
	v_pk_add_f32 v[92:93], v[92:93], v[180:181]
	v_pk_add_f32 v[94:95], v[94:95], v[182:183]
	v_pk_add_f32 v[88:89], v[88:89], v[184:185]
	v_pk_add_f32 v[90:91], v[90:91], v[186:187]
	v_pk_add_f32 v[84:85], v[84:85], v[188:189]
	v_pk_add_f32 v[86:87], v[86:87], v[190:191]
	v_pk_add_f32 v[76:77], v[76:77], v[192:193]
	v_pk_add_f32 v[78:79], v[78:79], v[194:195]
	v_pk_add_f32 v[80:81], v[80:81], v[196:197]
	v_pk_add_f32 v[82:83], v[82:83], v[198:199]
	v_pk_add_f32 v[72:73], v[72:73], v[200:201]
	v_pk_add_f32 v[74:75], v[74:75], v[202:203]
	v_pk_add_f32 v[68:69], v[68:69], v[204:205]
	v_pk_add_f32 v[70:71], v[70:71], v[206:207]
	v_pk_add_f32 v[64:65], v[64:65], v[208:209]
	v_pk_add_f32 v[66:67], v[66:67], v[210:211]
	global_store_dwordx4 v217, v[92:95], s[52:53]
	global_store_dwordx4 v217, v[88:91], s[52:53] offset:64
	global_store_dwordx4 v217, v[84:87], s[52:53] offset:512
	global_store_dwordx4 v217, v[76:79], s[52:53] offset:576
	global_store_dwordx4 v218, v[80:83], s[52:53]
	global_store_dwordx4 v218, v[72:75], s[52:53] offset:64
	global_store_dwordx4 v218, v[68:71], s[52:53] offset:512
	global_store_dwordx4 v218, v[64:67], s[52:53] offset:576
	s_waitcnt vmcnt(24)
	v_pk_add_f32 v[60:61], v[60:61], v[212:213]
	v_pk_add_f32 v[62:63], v[62:63], v[214:215]
	v_pk_add_f32 v[56:57], v[56:57], v[220:221]
	v_pk_add_f32 v[58:59], v[58:59], v[222:223]
	v_pk_add_f32 v[52:53], v[52:53], v[224:225]
	v_pk_add_f32 v[54:55], v[54:55], v[226:227]
	v_pk_add_f32 v[44:45], v[44:45], v[228:229]
	v_pk_add_f32 v[46:47], v[46:47], v[230:231]
	v_pk_add_f32 v[48:49], v[48:49], v[236:237]
	v_pk_add_f32 v[50:51], v[50:51], v[238:239]
	v_pk_add_f32 v[40:41], v[40:41], v[240:241]
	v_pk_add_f32 v[42:43], v[42:43], v[242:243]
	v_pk_add_f32 v[36:37], v[36:37], v[244:245]
	v_pk_add_f32 v[38:39], v[38:39], v[246:247]
	v_pk_add_f32 v[32:33], v[32:33], v[248:249]
	v_pk_add_f32 v[34:35], v[34:35], v[250:251]
	global_store_dwordx4 v232, v[60:63], s[52:53]
	global_store_dwordx4 v232, v[56:59], s[52:53] offset:64
	global_store_dwordx4 v232, v[52:55], s[52:53] offset:512
	global_store_dwordx4 v232, v[44:47], s[52:53] offset:576
	global_store_dwordx4 v233, v[48:51], s[52:53]
	global_store_dwordx4 v233, v[40:43], s[52:53] offset:64
	global_store_dwordx4 v233, v[36:39], s[52:53] offset:512
	global_store_dwordx4 v233, v[32:35], s[52:53] offset:576
	s_waitcnt vmcnt(16)
	v_pk_add_f32 v[28:29], v[28:29], v[140:141]
	v_pk_add_f32 v[30:31], v[30:31], v[142:143]
	v_pk_add_f32 v[24:25], v[24:25], v[152:153]
	v_pk_add_f32 v[26:27], v[26:27], v[154:155]
	v_pk_add_f32 v[20:21], v[20:21], v[156:157]
	v_pk_add_f32 v[22:23], v[22:23], v[158:159]
	v_pk_add_f32 v[12:13], v[12:13], v[160:161]
	v_pk_add_f32 v[14:15], v[14:15], v[162:163]
	v_pk_add_f32 v[16:17], v[16:17], v[164:165]
	v_pk_add_f32 v[18:19], v[18:19], v[166:167]
	v_pk_add_f32 v[8:9], v[8:9], v[168:169]
	v_pk_add_f32 v[10:11], v[10:11], v[170:171]
	v_pk_add_f32 v[4:5], v[4:5], v[172:173]
	v_pk_add_f32 v[6:7], v[6:7], v[174:175]
	v_pk_add_f32 v[0:1], v[0:1], v[176:177]
	v_pk_add_f32 v[2:3], v[2:3], v[178:179]
	global_store_dwordx4 v235, v[28:31], s[52:53]
	global_store_dwordx4 v235, v[24:27], s[52:53] offset:64
	global_store_dwordx4 v235, v[20:23], s[52:53] offset:512
	global_store_dwordx4 v235, v[12:15], s[52:53] offset:576
	global_store_dwordx4 v253, v[16:19], s[52:53]
	global_store_dwordx4 v253, v[8:11], s[52:53] offset:64
	global_store_dwordx4 v253, v[4:7], s[52:53] offset:512
	global_store_dwordx4 v253, v[0:3], s[52:53] offset:576
	s_cbranch_vccz .LBB0_849
	s_waitcnt vmcnt(0)
	s_cmpk_gt_u32 s4, 0xff
	s_cbranch_scc1 .LBB0_864
	s_barrier

; #define PG8_STAGE(bufoff, gbase, voff) do { _Pragma("unroll") for (int _i = 0; _i < 2; ++_i) \
;         __builtin_amdgcn_global_load_lds((const unsigned*)((const char*)(gbase) + (voff)[_i]), (LAS unsigned*)(lds + (bufoff) + ldsw + _i * 8192), 16, 0, 0); } while (0)
; #define PG8_LDA(dst, b, h) do { _Pragma("unroll") for (int m = 0; m < 4; ++m) _Pragma("unroll") for (int k = 0; k < 2; ++k) dst[m][k] = *(const LAS bf16x8*)(lds + PG8_SA(b, h) + aoff + m * 2048 + k * 1024); } while (0)
; #define PG8_LDB(dst, b, h) do { _Pragma("unroll") for (int n = 0; n < 2; ++n) _Pragma("unroll") for (int k = 0; k < 2; ++k) dst[n][k] = *(const LAS bf16x8*)(lds + PG8_SB(b, h) + boff + n * 2048 + k * 1024); } while (0)
; #define PG8_MMA(ai, bj, At, Bt) do { __builtin_amdgcn_s_setprio(1); _Pragma("unroll") for (int m = 0; m < 4; ++m) _Pragma("unroll") for (int n = 0; n < 2; ++n) _Pragma("unroll") for (int k = 0; k < 2; ++k) \
;         acc[ai][bj][m][n] = __builtin_amdgcn_mfma_f32_16x16x32_bf16(Bt[n][k], At[m][k], acc[ai][bj][m][n], 0, 0, 0); __builtin_amdgcn_s_setprio(0); } while (0)
; #define PG8_WAIT_V(n) asm volatile("s_waitcnt vmcnt(" #n ")" ::: "memory")
; #define PG8_WAIT_L(n) asm volatile("s_waitcnt lgkmcnt(" #n ")" ::: "memory")
; #define PG8_BAR __builtin_amdgcn_s_barrier()
; #define PG8_SCHED __builtin_amdgcn_sched_barrier(0)
; template <class Epi>
; __device__ __forceinline__ void gemm_phase(LAS unsigned char* lds, const Gemm g, const StaticOrder& S, const Epi& E) {
;     ...
;             PG8_LDB(B0, 0, 0); PG8_SCHED; PG8_LDA(At, 0, 0); PG8_STAGE(PG8_SA(1, 1), a1 + hstepA, voffA);
;             PG8_WAIT_L(8); PG8_BAR; PG8_WAIT_L(0); PG8_MMA(0, 0, At, B0); PG8_BAR; PG8_SCHED;
;             PG8_LDB(B1, 0, 1); PG8_STAGE(PG8_SB(0, 0), b2, voffB);
;             PG8_BAR; PG8_WAIT_L(0); PG8_MMA(0, 1, At, B1); PG8_BAR;
;             PG8_LDA(At, 0, 1); PG8_STAGE(PG8_SA(0, 0), a2, voffA);
;             PG8_BAR; PG8_WAIT_L(0); PG8_MMA(1, 0, At, B0); PG8_BAR; PG8_SCHED;
;             PG8_STAGE(PG8_SB(0, 1), b2 + hstepB, voffB);
;             PG8_WAIT_V(6); PG8_BAR; PG8_MMA(1, 1, At, B1); PG8_BAR;
.LBB0_1239:
	ds_read_b128 v[140:143], v149
	ds_read_b128 v[152:155], v149 offset:1024
	ds_read_b128 v[156:159], v149 offset:2048
	ds_read_b128 v[160:163], v149 offset:3072
	s_add_u32 s40, s38, 0xfffc0080
	s_addc_u32 s41, s39, -1
	s_cmp_eq_u32 s76, 12
	s_cselect_b32 s43, s29, s41
	s_cselect_b32 s42, s72, s40
	s_cselect_b32 s41, s27, s75
	s_cselect_b32 s40, s73, s74
	v_lshl_add_u64 v[144:145], s[38:39], 0, v[132:133]
	s_add_i32 m0, s8, 0xc000
	ds_read_b128 v[164:167], v150
	ds_read_b128 v[168:171], v150 offset:1024
	ds_read_b128 v[172:175], v150 offset:2048
	ds_read_b128 v[176:179], v150 offset:3072
	ds_read_b128 v[180:183], v150 offset:4096
	ds_read_b128 v[184:187], v150 offset:5120
	ds_read_b128 v[188:191], v150 offset:6144
	ds_read_b128 v[192:195], v150 offset:7168
	global_load_lds_dwordx4 v[144:145], off
	v_lshl_add_u64 v[144:145], s[38:39], 0, v[134:135]
	s_add_i32 m0, s8, 0xe000
	s_nop 0
	global_load_lds_dwordx4 v[144:145], off
	ds_read_b128 v[196:199], v151
	ds_read_b128 v[200:203], v151 offset:1024
	ds_read_b128 v[204:207], v151 offset:2048
	ds_read_b128 v[208:211], v151 offset:3072
	s_waitcnt lgkmcnt(0)
	s_barrier
	s_setprio 1
	v_mfma_f32_16x16x32_bf16 v[124:127], v[140:143], v[164:167], v[124:127]
	v_mfma_f32_16x16x32_bf16 v[120:123], v[156:159], v[164:167], v[120:123]
	v_mfma_f32_16x16x32_bf16 v[112:115], v[140:143], v[172:175], v[112:115]
	v_mfma_f32_16x16x32_bf16 v[104:107], v[156:159], v[172:175], v[104:107]
	v_mfma_f32_16x16x32_bf16 v[92:95], v[140:143], v[180:183], v[92:95]
	v_mfma_f32_16x16x32_bf16 v[88:91], v[156:159], v[180:183], v[88:91]
	v_mfma_f32_16x16x32_bf16 v[80:83], v[140:143], v[188:191], v[80:83]
	v_mfma_f32_16x16x32_bf16 v[72:75], v[156:159], v[188:191], v[72:75]
	v_mfma_f32_16x16x32_bf16 v[124:127], v[152:155], v[168:171], v[124:127]
	v_mfma_f32_16x16x32_bf16 v[120:123], v[160:163], v[168:171], v[120:123]
	v_mfma_f32_16x16x32_bf16 v[112:115], v[152:155], v[176:179], v[112:115]
	v_mfma_f32_16x16x32_bf16 v[104:107], v[160:163], v[176:179], v[104:107]
	v_mfma_f32_16x16x32_bf16 v[92:95], v[152:155], v[184:187], v[92:95]
	v_mfma_f32_16x16x32_bf16 v[88:91], v[160:163], v[184:187], v[88:91]
	v_mfma_f32_16x16x32_bf16 v[80:83], v[152:155], v[192:195], v[80:83]
	v_mfma_f32_16x16x32_bf16 v[72:75], v[160:163], v[192:195], v[72:75]
	v_mfma_f32_16x16x32_bf16 v[116:119], v[196:199], v[164:167], v[116:119]
	v_mfma_f32_16x16x32_bf16 v[108:111], v[204:207], v[164:167], v[108:111]
	v_mfma_f32_16x16x32_bf16 v[100:103], v[196:199], v[172:175], v[100:103]
	v_mfma_f32_16x16x32_bf16 v[96:99], v[204:207], v[172:175], v[96:99]
	v_mfma_f32_16x16x32_bf16 v[84:87], v[196:199], v[180:183], v[84:87]
	v_mfma_f32_16x16x32_bf16 v[76:79], v[204:207], v[180:183], v[76:79]
	v_mfma_f32_16x16x32_bf16 v[68:71], v[196:199], v[188:191], v[68:71]
	v_mfma_f32_16x16x32_bf16 v[64:67], v[204:207], v[188:191], v[64:67]
	v_mfma_f32_16x16x32_bf16 v[116:119], v[200:203], v[168:171], v[116:119]
	v_mfma_f32_16x16x32_bf16 v[108:111], v[208:211], v[168:171], v[108:111]
	v_mfma_f32_16x16x32_bf16 v[100:103], v[200:203], v[176:179], v[100:103]
	v_mfma_f32_16x16x32_bf16 v[96:99], v[208:211], v[176:179], v[96:99]
	v_mfma_f32_16x16x32_bf16 v[84:87], v[200:203], v[184:187], v[84:87]
	v_mfma_f32_16x16x32_bf16 v[76:79], v[208:211], v[184:187], v[76:79]
	v_mfma_f32_16x16x32_bf16 v[68:71], v[200:203], v[192:195], v[68:71]
	v_mfma_f32_16x16x32_bf16 v[64:67], v[208:211], v[192:195], v[64:67]
	s_setprio 0
	s_barrier
	s_nop 1
	ds_read_b128 v[164:167], v150 offset:16384
	ds_read_b128 v[168:171], v150 offset:17408
	ds_read_b128 v[172:175], v150 offset:18432
	ds_read_b128 v[176:179], v150 offset:19456
	ds_read_b128 v[180:183], v150 offset:20480
	ds_read_b128 v[184:187], v150 offset:21504
	ds_read_b128 v[188:191], v150 offset:22528
	ds_read_b128 v[192:195], v150 offset:23552
	s_add_i32 s77, s48, s7
	v_lshl_add_u64 v[144:145], s[40:41], 0, v[128:129]
	s_mov_b32 m0, s77
	s_nop 0
	global_load_lds_dwordx4 v[144:145], off
	v_lshl_add_u64 v[212:213], s[40:41], 0, v[130:131]
	s_add_i32 m0, s77, 0x2000
	s_nop 0
	global_load_lds_dwordx4 v[212:213], off
	s_mov_b32 m0, s8
	v_lshl_add_u64 v[214:215], s[42:43], 0, v[128:129]
	global_load_lds_dwordx4 v[214:215], off
	v_lshl_add_u64 v[216:217], s[42:43], 0, v[130:131]
	s_mov_b32 m0, s9
	s_nop 0
	global_load_lds_dwordx4 v[216:217], off
	s_add_u32 s78, s40, 0x40000
	s_addc_u32 s79, s41, 0
	s_add_i32 s77, s49, s7
	v_lshl_add_u64 v[254:255], s[78:79], 0, v[128:129]
	s_mov_b32 m0, s77
	s_nop 0
	global_load_lds_dwordx4 v[254:255], off
	v_lshl_add_u64 v[254:255], s[78:79], 0, v[130:131]
	s_add_i32 m0, s77, 0x2000
	s_nop 0
	global_load_lds_dwordx4 v[254:255], off
	s_waitcnt vmcnt(6)
	s_waitcnt lgkmcnt(0)
	s_barrier
; #define PG8_STAGE(bufoff, gbase, voff) do { _Pragma("unroll") for (int _i = 0; _i < 2; ++_i) \
;         __builtin_amdgcn_global_load_lds((const unsigned*)((const char*)(gbase) + (voff)[_i]), (LAS unsigned*)(lds + (bufoff) + ldsw + _i * 8192), 16, 0, 0); } while (0)
; #define PG8_LDA(dst, b, h) do { _Pragma("unroll") for (int m = 0; m < 4; ++m) _Pragma("unroll") for (int k = 0; k < 2; ++k) dst[m][k] = *(const LAS bf16x8*)(lds + PG8_SA(b, h) + aoff + m * 2048 + k * 1024); } while (0)
; #define PG8_LDB(dst, b, h) do { _Pragma("unroll") for (int n = 0; n < 2; ++n) _Pragma("unroll") for (int k = 0; k < 2; ++k) dst[n][k] = *(const LAS bf16x8*)(lds + PG8_SB(b, h) + boff + n * 2048 + k * 1024); } while (0)
; #define PG8_MMA(ai, bj, At, Bt) do { __builtin_amdgcn_s_setprio(1); _Pragma("unroll") for (int m = 0; m < 4; ++m) _Pragma("unroll") for (int n = 0; n < 2; ++n) _Pragma("unroll") for (int k = 0; k < 2; ++k) \
;         acc[ai][bj][m][n] = __builtin_amdgcn_mfma_f32_16x16x32_bf16(Bt[n][k], At[m][k], acc[ai][bj][m][n], 0, 0, 0); __builtin_amdgcn_s_setprio(0); } while (0)
; #define PG8_WAIT_V(n) asm volatile("s_waitcnt vmcnt(" #n ")" ::: "memory")
; #define PG8_WAIT_L(n) asm volatile("s_waitcnt lgkmcnt(" #n ")" ::: "memory")
; #define PG8_BAR __builtin_amdgcn_s_barrier()
; #define PG8_SCHED __builtin_amdgcn_sched_barrier(0)
; template <class Epi>
; __device__ __forceinline__ void gemm_phase(LAS unsigned char* lds, const Gemm g, const StaticOrder& S, const Epi& E) {
;     ...
;             PG8_WAIT_V(6); PG8_BAR; PG8_MMA(1, 1, At, B1); PG8_BAR;
;             PG8_LDB(B0, 1, 0); PG8_SCHED; PG8_LDA(At, 1, 0); PG8_STAGE(PG8_SA(0, 1), a2 + hstepA, voffA);
;             PG8_WAIT_L(8); PG8_BAR; PG8_WAIT_L(0); PG8_MMA(0, 0, At, B0); PG8_BAR; PG8_SCHED;
;             PG8_LDB(B1, 1, 1); PG8_STAGE(PG8_SB(1, 0), b3, voffB);
;             PG8_BAR; PG8_WAIT_L(0); PG8_MMA(0, 1, At, B1); PG8_BAR;
	s_setprio 1
	v_mfma_f32_16x16x32_bf16 v[60:63], v[140:143], v[164:167], v[60:63]
	v_mfma_f32_16x16x32_bf16 v[56:59], v[156:159], v[164:167], v[56:59]
	v_mfma_f32_16x16x32_bf16 v[48:51], v[140:143], v[172:175], v[48:51]
	v_mfma_f32_16x16x32_bf16 v[40:43], v[156:159], v[172:175], v[40:43]
	v_mfma_f32_16x16x32_bf16 v[28:31], v[140:143], v[180:183], v[28:31]
	v_mfma_f32_16x16x32_bf16 v[24:27], v[156:159], v[180:183], v[24:27]
	v_mfma_f32_16x16x32_bf16 v[16:19], v[140:143], v[188:191], v[16:19]
	v_mfma_f32_16x16x32_bf16 v[8:11], v[156:159], v[188:191], v[8:11]
	v_mfma_f32_16x16x32_bf16 v[60:63], v[152:155], v[168:171], v[60:63]
	v_mfma_f32_16x16x32_bf16 v[56:59], v[160:163], v[168:171], v[56:59]
	v_mfma_f32_16x16x32_bf16 v[48:51], v[152:155], v[176:179], v[48:51]
	v_mfma_f32_16x16x32_bf16 v[40:43], v[160:163], v[176:179], v[40:43]
	v_mfma_f32_16x16x32_bf16 v[28:31], v[152:155], v[184:187], v[28:31]
	v_mfma_f32_16x16x32_bf16 v[24:27], v[160:163], v[184:187], v[24:27]
	v_mfma_f32_16x16x32_bf16 v[16:19], v[152:155], v[192:195], v[16:19]
	v_mfma_f32_16x16x32_bf16 v[8:11], v[160:163], v[192:195], v[8:11]
	v_mfma_f32_16x16x32_bf16 v[52:55], v[196:199], v[164:167], v[52:55]
	v_mfma_f32_16x16x32_bf16 v[44:47], v[204:207], v[164:167], v[44:47]
	v_mfma_f32_16x16x32_bf16 v[36:39], v[196:199], v[172:175], v[36:39]
	v_mfma_f32_16x16x32_bf16 v[32:35], v[204:207], v[172:175], v[32:35]
	v_mfma_f32_16x16x32_bf16 v[20:23], v[196:199], v[180:183], v[20:23]
	v_mfma_f32_16x16x32_bf16 v[12:15], v[204:207], v[180:183], v[12:15]
	v_mfma_f32_16x16x32_bf16 v[4:7], v[196:199], v[188:191], v[4:7]
	v_mfma_f32_16x16x32_bf16 v[0:3], v[204:207], v[188:191], v[0:3]
	v_mfma_f32_16x16x32_bf16 v[52:55], v[200:203], v[168:171], v[52:55]
	v_mfma_f32_16x16x32_bf16 v[44:47], v[208:211], v[168:171], v[44:47]
	v_mfma_f32_16x16x32_bf16 v[36:39], v[200:203], v[176:179], v[36:39]
	v_mfma_f32_16x16x32_bf16 v[32:35], v[208:211], v[176:179], v[32:35]
	v_mfma_f32_16x16x32_bf16 v[20:23], v[200:203], v[184:187], v[20:23]
	v_mfma_f32_16x16x32_bf16 v[12:15], v[208:211], v[184:187], v[12:15]
	v_mfma_f32_16x16x32_bf16 v[4:7], v[200:203], v[192:195], v[4:7]
	v_mfma_f32_16x16x32_bf16 v[0:3], v[208:211], v[192:195], v[0:3]
	s_setprio 0
	s_add_i32 s77, 0, 0x18000
	v_add_u32_e32 v160, s77, v147
	s_barrier
	ds_read_b128 v[140:143], v160
	ds_read_b128 v[152:155], v160 offset:1024
	ds_read_b128 v[156:159], v160 offset:2048
	ds_read_b128 v[160:163], v160 offset:3072
	s_add_u32 s42, s42, 0x40000
	s_addc_u32 s43, s43, 0
	s_mov_b32 m0, s37
	v_lshl_add_u64 v[196:197], s[42:43], 0, v[128:129]
	ds_read_b128 v[164:167], v150 offset:32768
	ds_read_b128 v[168:171], v150 offset:33792
	ds_read_b128 v[172:175], v150 offset:34816
	ds_read_b128 v[176:179], v150 offset:35840
	ds_read_b128 v[180:183], v150 offset:36864
	ds_read_b128 v[184:187], v150 offset:37888
	ds_read_b128 v[188:191], v150 offset:38912
	ds_read_b128 v[192:195], v150 offset:39936
	global_load_lds_dwordx4 v[196:197], off
	v_lshl_add_u64 v[196:197], s[42:43], 0, v[130:131]
	s_mov_b32 m0, s44
	s_nop 0
	global_load_lds_dwordx4 v[196:197], off
	s_add_i32 s42, 0, 0x1c000
	v_add_u32_e32 v208, s42, v147
	ds_read_b128 v[196:199], v208
	ds_read_b128 v[200:203], v208 offset:1024
	ds_read_b128 v[204:207], v208 offset:2048
	ds_read_b128 v[208:211], v208 offset:3072
	s_waitcnt lgkmcnt(0)
	s_barrier
	s_setprio 1
	v_mfma_f32_16x16x32_bf16 v[124:127], v[140:143], v[164:167], v[124:127]
	v_mfma_f32_16x16x32_bf16 v[120:123], v[156:159], v[164:167], v[120:123]
	v_mfma_f32_16x16x32_bf16 v[112:115], v[140:143], v[172:175], v[112:115]
	v_mfma_f32_16x16x32_bf16 v[104:107], v[156:159], v[172:175], v[104:107]
	v_mfma_f32_16x16x32_bf16 v[92:95], v[140:143], v[180:183], v[92:95]
	v_mfma_f32_16x16x32_bf16 v[88:91], v[156:159], v[180:183], v[88:91]
	v_mfma_f32_16x16x32_bf16 v[80:83], v[140:143], v[188:191], v[80:83]
	v_mfma_f32_16x16x32_bf16 v[72:75], v[156:159], v[188:191], v[72:75]
	v_mfma_f32_16x16x32_bf16 v[124:127], v[152:155], v[168:171], v[124:127]
	v_mfma_f32_16x16x32_bf16 v[120:123], v[160:163], v[168:171], v[120:123]
	v_mfma_f32_16x16x32_bf16 v[112:115], v[152:155], v[176:179], v[112:115]
	v_mfma_f32_16x16x32_bf16 v[104:107], v[160:163], v[176:179], v[104:107]
	v_mfma_f32_16x16x32_bf16 v[92:95], v[152:155], v[184:187], v[92:95]
	v_mfma_f32_16x16x32_bf16 v[88:91], v[160:163], v[184:187], v[88:91]
	v_mfma_f32_16x16x32_bf16 v[80:83], v[152:155], v[192:195], v[80:83]
	v_mfma_f32_16x16x32_bf16 v[72:75], v[160:163], v[192:195], v[72:75]
	v_mfma_f32_16x16x32_bf16 v[116:119], v[196:199], v[164:167], v[116:119]
	v_mfma_f32_16x16x32_bf16 v[108:111], v[204:207], v[164:167], v[108:111]
	v_mfma_f32_16x16x32_bf16 v[100:103], v[196:199], v[172:175], v[100:103]
	v_mfma_f32_16x16x32_bf16 v[96:99], v[204:207], v[172:175], v[96:99]
	v_mfma_f32_16x16x32_bf16 v[84:87], v[196:199], v[180:183], v[84:87]
	v_mfma_f32_16x16x32_bf16 v[76:79], v[204:207], v[180:183], v[76:79]
	v_mfma_f32_16x16x32_bf16 v[68:71], v[196:199], v[188:191], v[68:71]
	v_mfma_f32_16x16x32_bf16 v[64:67], v[204:207], v[188:191], v[64:67]
	v_mfma_f32_16x16x32_bf16 v[116:119], v[200:203], v[168:171], v[116:119]
	v_mfma_f32_16x16x32_bf16 v[108:111], v[208:211], v[168:171], v[108:111]
	v_mfma_f32_16x16x32_bf16 v[100:103], v[200:203], v[176:179], v[100:103]
	v_mfma_f32_16x16x32_bf16 v[96:99], v[208:211], v[176:179], v[96:99]
	v_mfma_f32_16x16x32_bf16 v[84:87], v[200:203], v[184:187], v[84:87]
	v_mfma_f32_16x16x32_bf16 v[76:79], v[208:211], v[184:187], v[76:79]
	v_mfma_f32_16x16x32_bf16 v[68:71], v[200:203], v[192:195], v[68:71]
	v_mfma_f32_16x16x32_bf16 v[64:67], v[208:211], v[192:195], v[64:67]
	s_setprio 0
	s_barrier
; #define PG8_STAGE(bufoff, gbase, voff) do { _Pragma("unroll") for (int _i = 0; _i < 2; ++_i) \
;         __builtin_amdgcn_global_load_lds((const unsigned*)((const char*)(gbase) + (voff)[_i]), (LAS unsigned*)(lds + (bufoff) + ldsw + _i * 8192), 16, 0, 0); } while (0)
; #define PG8_WAIT_V(n) asm volatile("s_waitcnt vmcnt(" #n ")" ::: "memory")
; #define PG8_WAIT_L(n) asm volatile("s_waitcnt lgkmcnt(" #n ")" ::: "memory")
; #define PG8_BAR __builtin_amdgcn_s_barrier()
; template <class Epi>
; __device__ __forceinline__ void gemm_phase(LAS unsigned char* lds, const Gemm g, const StaticOrder& S, const Epi& E) {
;     ...
;             PG8_LDA(At, 1, 1); PG8_STAGE(PG8_SA(1, 0), a3, voffA);
;             PG8_BAR; PG8_WAIT_L(0); PG8_MMA(1, 0, At, B0); PG8_BAR; PG8_SCHED;
;             PG8_STAGE(PG8_SB(1, 1), b3 + hstepB, voffB);
;             PG8_WAIT_V(6); PG8_BAR; PG8_MMA(1, 1, At, B1); PG8_BAR;
;     __device__ __forceinline__ void operator()(AccRef acc, const Unit& u, int wr, int wc, int fr, int fq) const {
;         const int row0 = u.pm * 256 + wr * 64 + fr, col0 = u.pn * 256 + wc * 32 + 4 * fq;
;         f32x4 sv[2][2], bv[2][2];
; #pragma unroll
;         for (int bj = 0; bj < 2; ++bj)
; #pragma unroll
;             for (int n = 0; n < 2; ++n) {
;                 sv[bj][n] = scale ? *(const f32x4*)(scale + col0 + bj * 128 + n * 16) : (f32x4){1.f, 1.f, 1.f, 1.f};
;                 bv[bj][n] = bias ? *(const f32x4*)(bias + col0 + bj * 128 + n * 16) : (f32x4){0.f, 0.f, 0.f, 0.f}; }
; #pragma unroll
;         for (int ai = 0; ai < 2; ++ai)
; #pragma unroll
;             for (int mh = 0; mh < 2; ++mh) {
;                 f32x4 bs[2][2][2];
; #pragma unroll
;                 for (int m = 0; m < 2; ++m)
; #pragma unroll
;                     for (int bj = 0; bj < 2; ++bj)
; #pragma unroll
;                         for (int n = 0; n < 2; ++n) bs[m][bj][n] = *(const f32x4*)(base + (size_t)(row0 + ai * 128 + (2 * mh + m) * 16) * D + col0 + bj * 128 + n * 16);
; #pragma unroll
;                 for (int m = 0; m < 2; ++m)
; #pragma unroll
;                     for (int bj = 0; bj < 2; ++bj)
; #pragma unroll
;                         for (int n = 0; n < 2; ++n) *(f32x4*)(out + (size_t)(row0 + ai * 128 + (2 * mh + m) * 16) * D + col0 + bj * 128 + n * 16) = bs[m][bj][n] + sv[bj][n] * (acc[ai][bj][2 * mh + m][n] + bv[bj][n]);
;                 asm volatile("" ::: "memory"); }
	s_nop 1
	ds_read_b128 v[164:167], v150 offset:49152
	ds_read_b128 v[168:171], v150 offset:50176
	ds_read_b128 v[172:175], v150 offset:51200
	ds_read_b128 v[176:179], v150 offset:52224
	ds_read_b128 v[180:183], v150 offset:53248
	ds_read_b128 v[184:187], v150 offset:54272
	ds_read_b128 v[188:191], v150 offset:55296
	ds_read_b128 v[192:195], v150 offset:56320
	s_add_i32 s43, s77, s7
	v_lshl_add_u64 v[254:255], v[144:145], 0, s[12:13]
	s_mov_b32 m0, s43
	s_nop 0
	global_load_lds_dwordx4 v[254:255], off
	v_lshl_add_u64 v[254:255], v[212:213], 0, s[12:13]
	s_add_i32 m0, s43, 0x2000
	s_nop 0
	global_load_lds_dwordx4 v[254:255], off
	s_mov_b32 m0, s46
	v_lshl_add_u64 v[254:255], v[214:215], 0, s[12:13]
	global_load_lds_dwordx4 v[254:255], off
	v_lshl_add_u64 v[144:145], v[216:217], 0, s[12:13]
	s_mov_b32 m0, s47
	s_nop 0
	global_load_lds_dwordx4 v[144:145], off
	s_add_u32 s40, s40, 0x40080
	s_addc_u32 s41, s41, 0
	s_add_i32 s42, s42, s7
	v_lshl_add_u64 v[254:255], s[40:41], 0, v[128:129]
	s_mov_b32 m0, s42
	s_nop 0
	global_load_lds_dwordx4 v[254:255], off
	v_lshl_add_u64 v[254:255], s[40:41], 0, v[130:131]
	s_add_i32 m0, s42, 0x2000
	s_nop 0
	global_load_lds_dwordx4 v[254:255], off
	s_waitcnt vmcnt(6)
	s_waitcnt lgkmcnt(0)
	s_barrier
	s_setprio 1
	v_mfma_f32_16x16x32_bf16 v[60:63], v[140:143], v[164:167], v[60:63]
	v_mfma_f32_16x16x32_bf16 v[56:59], v[156:159], v[164:167], v[56:59]
	v_mfma_f32_16x16x32_bf16 v[48:51], v[140:143], v[172:175], v[48:51]
	v_mfma_f32_16x16x32_bf16 v[40:43], v[156:159], v[172:175], v[40:43]
	v_mfma_f32_16x16x32_bf16 v[28:31], v[140:143], v[180:183], v[28:31]
	v_mfma_f32_16x16x32_bf16 v[24:27], v[156:159], v[180:183], v[24:27]
	v_mfma_f32_16x16x32_bf16 v[16:19], v[140:143], v[188:191], v[16:19]
	v_mfma_f32_16x16x32_bf16 v[8:11], v[156:159], v[188:191], v[8:11]
	v_mfma_f32_16x16x32_bf16 v[60:63], v[152:155], v[168:171], v[60:63]
	v_mfma_f32_16x16x32_bf16 v[56:59], v[160:163], v[168:171], v[56:59]
	v_mfma_f32_16x16x32_bf16 v[48:51], v[152:155], v[176:179], v[48:51]
	v_mfma_f32_16x16x32_bf16 v[40:43], v[160:163], v[176:179], v[40:43]
	v_mfma_f32_16x16x32_bf16 v[28:31], v[152:155], v[184:187], v[28:31]
	v_mfma_f32_16x16x32_bf16 v[24:27], v[160:163], v[184:187], v[24:27]
	v_mfma_f32_16x16x32_bf16 v[16:19], v[152:155], v[192:195], v[16:19]
	v_mfma_f32_16x16x32_bf16 v[8:11], v[160:163], v[192:195], v[8:11]
	v_mfma_f32_16x16x32_bf16 v[52:55], v[196:199], v[164:167], v[52:55]
	v_mfma_f32_16x16x32_bf16 v[44:47], v[204:207], v[164:167], v[44:47]
	v_mfma_f32_16x16x32_bf16 v[36:39], v[196:199], v[172:175], v[36:39]
	v_mfma_f32_16x16x32_bf16 v[32:35], v[204:207], v[172:175], v[32:35]
	v_mfma_f32_16x16x32_bf16 v[20:23], v[196:199], v[180:183], v[20:23]
	v_mfma_f32_16x16x32_bf16 v[12:15], v[204:207], v[180:183], v[12:15]
	v_mfma_f32_16x16x32_bf16 v[4:7], v[196:199], v[188:191], v[4:7]
	v_mfma_f32_16x16x32_bf16 v[0:3], v[204:207], v[188:191], v[0:3]
	v_mfma_f32_16x16x32_bf16 v[52:55], v[200:203], v[168:171], v[52:55]
	v_mfma_f32_16x16x32_bf16 v[44:47], v[208:211], v[168:171], v[44:47]
	v_mfma_f32_16x16x32_bf16 v[36:39], v[200:203], v[176:179], v[36:39]
	v_mfma_f32_16x16x32_bf16 v[32:35], v[208:211], v[176:179], v[32:35]
	v_mfma_f32_16x16x32_bf16 v[20:23], v[200:203], v[184:187], v[20:23]
	v_mfma_f32_16x16x32_bf16 v[12:15], v[208:211], v[184:187], v[12:15]
	v_mfma_f32_16x16x32_bf16 v[4:7], v[200:203], v[192:195], v[4:7]
	v_mfma_f32_16x16x32_bf16 v[0:3], v[208:211], v[192:195], v[0:3]
	s_setprio 0
	s_add_i32 s76, s76, 2
	s_add_u32 s38, s38, 0x100
	s_addc_u32 s39, s39, 0
	s_add_u32 s74, s74, 0x100
	s_addc_u32 s75, s75, 0
	s_cmp_gt_u32 s76, 13
	s_barrier
	s_cbranch_scc0 .LBB0_1239
	v_lshl_or_b32 v144, s63, 8, v148
	v_lshl_add_u32 v145, s36, 8, v146
	v_lshlrev_b32_e32 v144, 2, v144
	v_lshl_add_u32 v145, v145, 12, v144
	v_add_u32_e32 v216, 0x10000, v145
	v_add_u32_e32 v217, 0x20000, v145
	v_add_u32_e32 v218, 0x30000, v145
	v_add_u32_e32 v232, 0x80000, v145
	v_add_u32_e32 v233, 0x90000, v145
	v_add_u32_e32 v235, 0xa0000, v145
	v_add_u32_e32 v253, 0xb0000, v145
	s_and_b64 vcc, exec, s[10:11]
	s_mov_b32 s63, s26
	s_mov_b32 s36, s28
	s_mov_b64 s[40:41], s[34:35]
	s_mov_b64 s[38:39], s[30:31]
	global_load_dwordx4 v[140:143], v145, s[52:53]
	global_load_dwordx4 v[152:155], v145, s[52:53] offset:64
	global_load_dwordx4 v[156:159], v145, s[52:53] offset:512
	global_load_dwordx4 v[160:163], v145, s[52:53] offset:576
	global_load_dwordx4 v[164:167], v216, s[52:53]
	global_load_dwordx4 v[168:171], v216, s[52:53] offset:64
	global_load_dwordx4 v[172:175], v216, s[52:53] offset:512
	global_load_dwordx4 v[176:179], v216, s[52:53] offset:576
	global_load_dwordx4 v[180:183], v217, s[52:53]
	global_load_dwordx4 v[184:187], v217, s[52:53] offset:64
	global_load_dwordx4 v[188:191], v217, s[52:53] offset:512
	global_load_dwordx4 v[192:195], v217, s[52:53] offset:576
	global_load_dwordx4 v[196:199], v218, s[52:53]
	global_load_dwordx4 v[200:203], v218, s[52:53] offset:64
	global_load_dwordx4 v[204:207], v218, s[52:53] offset:512
	global_load_dwordx4 v[208:211], v218, s[52:53] offset:576
	global_load_dwordx4 v[212:215], v232, s[52:53]
	global_load_dwordx4 v[220:223], v232, s[52:53] offset:64
	global_load_dwordx4 v[224:227], v232, s[52:53] offset:512
	global_load_dwordx4 v[228:231], v232, s[52:53] offset:576
	global_load_dwordx4 v[236:239], v233, s[52:53]
	global_load_dwordx4 v[240:243], v233, s[52:53] offset:64
	global_load_dwordx4 v[244:247], v233, s[52:53] offset:512
	global_load_dwordx4 v[248:251], v233, s[52:53] offset:576
	v_pk_add_f32 v[124:125], v[124:125], 0 op_sel_hi:[1,0]
	v_pk_add_f32 v[126:127], v[126:127], 0 op_sel_hi:[1,0]
;     __device__ __forceinline__ void operator()(AccRef acc, const Unit& u, int wr, int wc, int fr, int fq) const {
;     ...
;         for (int ai = 0; ai < 2; ++ai)
; #pragma unroll
;             for (int mh = 0; mh < 2; ++mh) {
;                 f32x4 bs[2][2][2];
; #pragma unroll
;                 for (int m = 0; m < 2; ++m)
; #pragma unroll
;                     for (int bj = 0; bj < 2; ++bj)
; #pragma unroll
;                         for (int n = 0; n < 2; ++n) bs[m][bj][n] = *(const f32x4*)(base + (size_t)(row0 + ai * 128 + (2 * mh + m) * 16) * D + col0 + bj * 128 + n * 16);
; #pragma unroll
;                 for (int m = 0; m < 2; ++m)
; #pragma unroll
;                     for (int bj = 0; bj < 2; ++bj)
; #pragma unroll
;                         for (int n = 0; n < 2; ++n) *(f32x4*)(out + (size_t)(row0 + ai * 128 + (2 * mh + m) * 16) * D + col0 + bj * 128 + n * 16) = bs[m][bj][n] + sv[bj][n] * (acc[ai][bj][2 * mh + m][n] + bv[bj][n]);
;                 asm volatile("" ::: "memory"); }
	v_pk_add_f32 v[120:121], v[120:121], 0 op_sel_hi:[1,0]
	v_pk_add_f32 v[122:123], v[122:123], 0 op_sel_hi:[1,0]
	v_pk_add_f32 v[116:117], v[116:117], 0 op_sel_hi:[1,0]
	v_pk_add_f32 v[118:119], v[118:119], 0 op_sel_hi:[1,0]
	v_pk_add_f32 v[108:109], v[108:109], 0 op_sel_hi:[1,0]
	v_pk_add_f32 v[110:111], v[110:111], 0 op_sel_hi:[1,0]
	v_pk_add_f32 v[112:113], v[112:113], 0 op_sel_hi:[1,0]
	v_pk_add_f32 v[114:115], v[114:115], 0 op_sel_hi:[1,0]
	v_pk_add_f32 v[104:105], v[104:105], 0 op_sel_hi:[1,0]
	v_pk_add_f32 v[106:107], v[106:107], 0 op_sel_hi:[1,0]
	v_pk_add_f32 v[100:101], v[100:101], 0 op_sel_hi:[1,0]
	v_pk_add_f32 v[102:103], v[102:103], 0 op_sel_hi:[1,0]
	v_pk_add_f32 v[96:97], v[96:97], 0 op_sel_hi:[1,0]
	v_pk_add_f32 v[98:99], v[98:99], 0 op_sel_hi:[1,0]
	v_pk_add_f32 v[92:93], v[92:93], 0 op_sel_hi:[1,0]
	v_pk_add_f32 v[94:95], v[94:95], 0 op_sel_hi:[1,0]
	v_pk_add_f32 v[88:89], v[88:89], 0 op_sel_hi:[1,0]
	v_pk_add_f32 v[90:91], v[90:91], 0 op_sel_hi:[1,0]
	v_pk_add_f32 v[84:85], v[84:85], 0 op_sel_hi:[1,0]
	v_pk_add_f32 v[86:87], v[86:87], 0 op_sel_hi:[1,0]
	v_pk_add_f32 v[76:77], v[76:77], 0 op_sel_hi:[1,0]
	v_pk_add_f32 v[78:79], v[78:79], 0 op_sel_hi:[1,0]
	v_pk_add_f32 v[80:81], v[80:81], 0 op_sel_hi:[1,0]
	v_pk_add_f32 v[82:83], v[82:83], 0 op_sel_hi:[1,0]
	v_pk_add_f32 v[72:73], v[72:73], 0 op_sel_hi:[1,0]
	v_pk_add_f32 v[74:75], v[74:75], 0 op_sel_hi:[1,0]
	v_pk_add_f32 v[68:69], v[68:69], 0 op_sel_hi:[1,0]
	v_pk_add_f32 v[70:71], v[70:71], 0 op_sel_hi:[1,0]
	v_pk_add_f32 v[64:65], v[64:65], 0 op_sel_hi:[1,0]
	v_pk_add_f32 v[66:67], v[66:67], 0 op_sel_hi:[1,0]
	v_pk_add_f32 v[60:61], v[60:61], 0 op_sel_hi:[1,0]
	v_pk_add_f32 v[62:63], v[62:63], 0 op_sel_hi:[1,0]
	v_pk_add_f32 v[56:57], v[56:57], 0 op_sel_hi:[1,0]
	v_pk_add_f32 v[58:59], v[58:59], 0 op_sel_hi:[1,0]
	v_pk_add_f32 v[52:53], v[52:53], 0 op_sel_hi:[1,0]
	v_pk_add_f32 v[54:55], v[54:55], 0 op_sel_hi:[1,0]
	v_pk_add_f32 v[44:45], v[44:45], 0 op_sel_hi:[1,0]
	v_pk_add_f32 v[46:47], v[46:47], 0 op_sel_hi:[1,0]
	v_pk_add_f32 v[48:49], v[48:49], 0 op_sel_hi:[1,0]
	v_pk_add_f32 v[50:51], v[50:51], 0 op_sel_hi:[1,0]
	v_pk_add_f32 v[40:41], v[40:41], 0 op_sel_hi:[1,0]
	v_pk_add_f32 v[42:43], v[42:43], 0 op_sel_hi:[1,0]
	v_pk_add_f32 v[36:37], v[36:37], 0 op_sel_hi:[1,0]
	v_pk_add_f32 v[38:39], v[38:39], 0 op_sel_hi:[1,0]
	v_pk_add_f32 v[32:33], v[32:33], 0 op_sel_hi:[1,0]
	v_pk_add_f32 v[34:35], v[34:35], 0 op_sel_hi:[1,0]
	v_pk_add_f32 v[28:29], v[28:29], 0 op_sel_hi:[1,0]
	v_pk_add_f32 v[30:31], v[30:31], 0 op_sel_hi:[1,0]
	v_pk_add_f32 v[24:25], v[24:25], 0 op_sel_hi:[1,0]
	v_pk_add_f32 v[26:27], v[26:27], 0 op_sel_hi:[1,0]
	v_pk_add_f32 v[20:21], v[20:21], 0 op_sel_hi:[1,0]
	v_pk_add_f32 v[22:23], v[22:23], 0 op_sel_hi:[1,0]
	v_pk_add_f32 v[12:13], v[12:13], 0 op_sel_hi:[1,0]
	v_pk_add_f32 v[14:15], v[14:15], 0 op_sel_hi:[1,0]
	v_pk_add_f32 v[16:17], v[16:17], 0 op_sel_hi:[1,0]
	v_pk_add_f32 v[18:19], v[18:19], 0 op_sel_hi:[1,0]
	v_pk_add_f32 v[8:9], v[8:9], 0 op_sel_hi:[1,0]
	v_pk_add_f32 v[10:11], v[10:11], 0 op_sel_hi:[1,0]
	v_pk_add_f32 v[4:5], v[4:5], 0 op_sel_hi:[1,0]
	v_pk_add_f32 v[6:7], v[6:7], 0 op_sel_hi:[1,0]
	v_pk_add_f32 v[0:1], v[0:1], 0 op_sel_hi:[1,0]
	v_pk_add_f32 v[2:3], v[2:3], 0 op_sel_hi:[1,0]
	s_waitcnt vmcnt(16)
	v_pk_add_f32 v[124:125], v[124:125], v[140:141]
	v_pk_add_f32 v[126:127], v[126:127], v[142:143]
	v_pk_add_f32 v[120:121], v[120:121], v[152:153]
	v_pk_add_f32 v[122:123], v[122:123], v[154:155]
	v_pk_add_f32 v[116:117], v[116:117], v[156:157]
	v_pk_add_f32 v[118:119], v[118:119], v[158:159]
	v_pk_add_f32 v[108:109], v[108:109], v[160:161]
	v_pk_add_f32 v[110:111], v[110:111], v[162:163]
	v_pk_add_f32 v[112:113], v[112:113], v[164:165]
	v_pk_add_f32 v[114:115], v[114:115], v[166:167]
	v_pk_add_f32 v[104:105], v[104:105], v[168:169]
	v_pk_add_f32 v[106:107], v[106:107], v[170:171]
	v_pk_add_f32 v[100:101], v[100:101], v[172:173]
	v_pk_add_f32 v[102:103], v[102:103], v[174:175]
	v_pk_add_f32 v[96:97], v[96:97], v[176:177]
	v_pk_add_f32 v[98:99], v[98:99], v[178:179]
	global_store_dwordx4 v145, v[124:127], s[52:53]
	global_store_dwordx4 v145, v[120:123], s[52:53] offset:64
	global_store_dwordx4 v145, v[116:119], s[52:53] offset:512
	global_store_dwordx4 v145, v[108:111], s[52:53] offset:576
	global_store_dwordx4 v216, v[112:115], s[52:53]
	global_store_dwordx4 v216, v[104:107], s[52:53] offset:64
	global_store_dwordx4 v216, v[100:103], s[52:53] offset:512
	global_store_dwordx4 v216, v[96:99], s[52:53] offset:576
	global_load_dwordx4 v[140:143], v235, s[52:53]
	global_load_dwordx4 v[152:155], v235, s[52:53] offset:64
	global_load_dwordx4 v[156:159], v235, s[52:53] offset:512
	global_load_dwordx4 v[160:163], v235, s[52:53] offset:576
	global_load_dwordx4 v[164:167], v253, s[52:53]
	global_load_dwordx4 v[168:171], v253, s[52:53] offset:64
	global_load_dwordx4 v[172:175], v253, s[52:53] offset:512
	global_load_dwordx4 v[176:179], v253, s[52:53] offset:576
	s_waitcnt vmcnt(24)
;     __device__ __forceinline__ void operator()(AccRef acc, const Unit& u, int wr, int wc, int fr, int fq) const {
;     ...
;                         for (int n = 0; n < 2; ++n) bs[m][bj][n] = *(const f32x4*)(base + (size_t)(row0 + ai * 128 + (2 * mh + m) * 16) * D + col0 + bj * 128 + n * 16);
; #pragma unroll
;                 for (int m = 0; m < 2; ++m)
; #pragma unroll
;                     for (int bj = 0; bj < 2; ++bj)
; #pragma unroll
;                         for (int n = 0; n < 2; ++n) *(f32x4*)(out + (size_t)(row0 + ai * 128 + (2 * mh + m) * 16) * D + col0 + bj * 128 + n * 16) = bs[m][bj][n] + sv[bj][n] * (acc[ai][bj][2 * mh + m][n] + bv[bj][n]);
;                 asm volatile("" ::: "memory"); }
	v_pk_add_f32 v[92:93], v[92:93], v[180:181]
	v_pk_add_f32 v[94:95], v[94:95], v[182:183]
	v_pk_add_f32 v[88:89], v[88:89], v[184:185]
	v_pk_add_f32 v[90:91], v[90:91], v[186:187]
	v_pk_add_f32 v[84:85], v[84:85], v[188:189]
	v_pk_add_f32 v[86:87], v[86:87], v[190:191]
	v_pk_add_f32 v[76:77], v[76:77], v[192:193]
	v_pk_add_f32 v[78:79], v[78:79], v[194:195]
	v_pk_add_f32 v[80:81], v[80:81], v[196:197]
	v_pk_add_f32 v[82:83], v[82:83], v[198:199]
	v_pk_add_f32 v[72:73], v[72:73], v[200:201]
	v_pk_add_f32 v[74:75], v[74:75], v[202:203]
	v_pk_add_f32 v[68:69], v[68:69], v[204:205]
	v_pk_add_f32 v[70:71], v[70:71], v[206:207]
	v_pk_add_f32 v[64:65], v[64:65], v[208:209]
	v_pk_add_f32 v[66:67], v[66:67], v[210:211]
	global_store_dwordx4 v217, v[92:95], s[52:53]
	global_store_dwordx4 v217, v[88:91], s[52:53] offset:64
	global_store_dwordx4 v217, v[84:87], s[52:53] offset:512
	global_store_dwordx4 v217, v[76:79], s[52:53] offset:576
	global_store_dwordx4 v218, v[80:83], s[52:53]
	global_store_dwordx4 v218, v[72:75], s[52:53] offset:64
	global_store_dwordx4 v218, v[68:71], s[52:53] offset:512
	global_store_dwordx4 v218, v[64:67], s[52:53] offset:576
	s_waitcnt vmcnt(24)
	v_pk_add_f32 v[60:61], v[60:61], v[212:213]
	v_pk_add_f32 v[62:63], v[62:63], v[214:215]
	v_pk_add_f32 v[56:57], v[56:57], v[220:221]
	v_pk_add_f32 v[58:59], v[58:59], v[222:223]
	v_pk_add_f32 v[52:53], v[52:53], v[224:225]
	v_pk_add_f32 v[54:55], v[54:55], v[226:227]
	v_pk_add_f32 v[44:45], v[44:45], v[228:229]
	v_pk_add_f32 v[46:47], v[46:47], v[230:231]
	v_pk_add_f32 v[48:49], v[48:49], v[236:237]
	v_pk_add_f32 v[50:51], v[50:51], v[238:239]
	v_pk_add_f32 v[40:41], v[40:41], v[240:241]
	v_pk_add_f32 v[42:43], v[42:43], v[242:243]
	v_pk_add_f32 v[36:37], v[36:37], v[244:245]
	v_pk_add_f32 v[38:39], v[38:39], v[246:247]
	v_pk_add_f32 v[32:33], v[32:33], v[248:249]
	v_pk_add_f32 v[34:35], v[34:35], v[250:251]
	global_store_dwordx4 v232, v[60:63], s[52:53]
	global_store_dwordx4 v232, v[56:59], s[52:53] offset:64
	global_store_dwordx4 v232, v[52:55], s[52:53] offset:512
	global_store_dwordx4 v232, v[44:47], s[52:53] offset:576
	global_store_dwordx4 v233, v[48:51], s[52:53]
	global_store_dwordx4 v233, v[40:43], s[52:53] offset:64
	global_store_dwordx4 v233, v[36:39], s[52:53] offset:512
	global_store_dwordx4 v233, v[32:35], s[52:53] offset:576
	s_waitcnt vmcnt(16)
	v_pk_add_f32 v[28:29], v[28:29], v[140:141]
	v_pk_add_f32 v[30:31], v[30:31], v[142:143]
	v_pk_add_f32 v[24:25], v[24:25], v[152:153]
	v_pk_add_f32 v[26:27], v[26:27], v[154:155]
	v_pk_add_f32 v[20:21], v[20:21], v[156:157]
	v_pk_add_f32 v[22:23], v[22:23], v[158:159]
	v_pk_add_f32 v[12:13], v[12:13], v[160:161]
	v_pk_add_f32 v[14:15], v[14:15], v[162:163]
	v_pk_add_f32 v[16:17], v[16:17], v[164:165]
	v_pk_add_f32 v[18:19], v[18:19], v[166:167]
	v_pk_add_f32 v[8:9], v[8:9], v[168:169]
	v_pk_add_f32 v[10:11], v[10:11], v[170:171]
	v_pk_add_f32 v[4:5], v[4:5], v[172:173]
	v_pk_add_f32 v[6:7], v[6:7], v[174:175]
	v_pk_add_f32 v[0:1], v[0:1], v[176:177]
	v_pk_add_f32 v[2:3], v[2:3], v[178:179]
	global_store_dwordx4 v235, v[28:31], s[52:53]
	global_store_dwordx4 v235, v[24:27], s[52:53] offset:64
	global_store_dwordx4 v235, v[20:23], s[52:53] offset:512
	global_store_dwordx4 v235, v[12:15], s[52:53] offset:576
	global_store_dwordx4 v253, v[16:19], s[52:53]
	global_store_dwordx4 v253, v[8:11], s[52:53] offset:64
	global_store_dwordx4 v253, v[4:7], s[52:53] offset:512
	global_store_dwordx4 v253, v[0:3], s[52:53] offset:576
	s_cbranch_vccz .LBB0_1232
	s_waitcnt vmcnt(0)
	s_cmpk_gt_u32 s4, 0xff
	s_cbranch_scc1 .LBB0_1243
	s_barrier

; #define PG8_STAGE(bufoff, gbase, voff) do { _Pragma("unroll") for (int _i = 0; _i < 2; ++_i) \
;         __builtin_amdgcn_global_load_lds((const unsigned*)((const char*)(gbase) + (voff)[_i]), (LAS unsigned*)(lds + (bufoff) + ldsw + _i * 8192), 16, 0, 0); } while (0)
; #define PG8_LDA(dst, b, h) do { _Pragma("unroll") for (int m = 0; m < 4; ++m) _Pragma("unroll") for (int k = 0; k < 2; ++k) dst[m][k] = *(const LAS bf16x8*)(lds + PG8_SA(b, h) + aoff + m * 2048 + k * 1024); } while (0)
; #define PG8_LDB(dst, b, h) do { _Pragma("unroll") for (int n = 0; n < 2; ++n) _Pragma("unroll") for (int k = 0; k < 2; ++k) dst[n][k] = *(const LAS bf16x8*)(lds + PG8_SB(b, h) + boff + n * 2048 + k * 1024); } while (0)
; #define PG8_MMA(ai, bj, At, Bt) do { __builtin_amdgcn_s_setprio(1); _Pragma("unroll") for (int m = 0; m < 4; ++m) _Pragma("unroll") for (int n = 0; n < 2; ++n) _Pragma("unroll") for (int k = 0; k < 2; ++k) \
;         acc[ai][bj][m][n] = __builtin_amdgcn_mfma_f32_16x16x32_bf16(Bt[n][k], At[m][k], acc[ai][bj][m][n], 0, 0, 0); __builtin_amdgcn_s_setprio(0); } while (0)
; #define PG8_WAIT_V(n) asm volatile("s_waitcnt vmcnt(" #n ")" ::: "memory")
; #define PG8_WAIT_L(n) asm volatile("s_waitcnt lgkmcnt(" #n ")" ::: "memory")
; template <class Epi>
; __device__ __forceinline__ void gemm_phase(LAS unsigned char* lds, const Gemm g, const StaticOrder& S, const Epi& E) {
;     ...
;         for (int t = 0; t < nt; t += 2) {
;             const bool last = (t == nt - 2);
;             const char* a1 = cA + (size_t)(t + 1) * kstep;
;             const char* a2 = last ? nA : cA + (size_t)(t + 2) * kstep; const char* b2 = last ? nB : cB + (size_t)(t + 2) * kstep;
;             const char* a3 = a2 + kstep; const char* b3 = b2 + kstep;
;             PG8_LDB(B0, 0, 0); PG8_SCHED; PG8_LDA(At, 0, 0); PG8_STAGE(PG8_SA(1, 1), a1 + hstepA, voffA);
;             PG8_WAIT_L(8); PG8_BAR; PG8_WAIT_L(0); PG8_MMA(0, 0, At, B0); PG8_BAR; PG8_SCHED;
;             PG8_LDB(B1, 0, 1); PG8_STAGE(PG8_SB(0, 0), b2, voffB);
;             PG8_BAR; PG8_WAIT_L(0); PG8_MMA(0, 1, At, B1); PG8_BAR;
;             PG8_LDA(At, 0, 1); PG8_STAGE(PG8_SA(0, 0), a2, voffA);
;             PG8_BAR; PG8_WAIT_L(0); PG8_MMA(1, 0, At, B0); PG8_BAR; PG8_SCHED;
;             PG8_STAGE(PG8_SB(0, 1), b2 + hstepB, voffB);
;             PG8_WAIT_V(6); PG8_BAR; PG8_MMA(1, 1, At, B1); PG8_BAR;
.LBB0_1461:
	ds_read_b128 v[140:143], v149
	ds_read_b128 v[152:155], v149 offset:1024
	ds_read_b128 v[156:159], v149 offset:2048
	ds_read_b128 v[160:163], v149 offset:3072
	s_add_u32 s34, s30, 0x100
	s_addc_u32 s35, s31, 0
	s_cmp_eq_u32 s74, 40
	s_cselect_b32 s39, s13, s35
	s_cselect_b32 s38, s12, s34
	s_cselect_b32 s37, s15, s73
	s_cselect_b32 s36, s14, s72
	v_lshl_add_u64 v[144:145], s[30:31], 0, v[132:133]
	s_add_i32 m0, s8, 0xc000
	ds_read_b128 v[164:167], v150
	ds_read_b128 v[168:171], v150 offset:1024
	ds_read_b128 v[172:175], v150 offset:2048
	ds_read_b128 v[176:179], v150 offset:3072
	ds_read_b128 v[180:183], v150 offset:4096
	ds_read_b128 v[184:187], v150 offset:5120
	ds_read_b128 v[188:191], v150 offset:6144
	ds_read_b128 v[192:195], v150 offset:7168
	global_load_lds_dwordx4 v[144:145], off
	v_lshl_add_u64 v[144:145], s[30:31], 0, v[134:135]
	s_add_i32 m0, s8, 0xe000
	s_nop 0
	global_load_lds_dwordx4 v[144:145], off
	ds_read_b128 v[196:199], v151
	ds_read_b128 v[200:203], v151 offset:1024
	ds_read_b128 v[204:207], v151 offset:2048
	ds_read_b128 v[208:211], v151 offset:3072
	s_waitcnt lgkmcnt(0)
	s_barrier
	s_setprio 1
	v_mfma_f32_16x16x32_bf16 v[124:127], v[140:143], v[164:167], v[124:127]
	v_mfma_f32_16x16x32_bf16 v[120:123], v[156:159], v[164:167], v[120:123]
	v_mfma_f32_16x16x32_bf16 v[112:115], v[140:143], v[172:175], v[112:115]
	v_mfma_f32_16x16x32_bf16 v[104:107], v[156:159], v[172:175], v[104:107]
	v_mfma_f32_16x16x32_bf16 v[92:95], v[140:143], v[180:183], v[92:95]
	v_mfma_f32_16x16x32_bf16 v[88:91], v[156:159], v[180:183], v[88:91]
	v_mfma_f32_16x16x32_bf16 v[80:83], v[140:143], v[188:191], v[80:83]
	v_mfma_f32_16x16x32_bf16 v[72:75], v[156:159], v[188:191], v[72:75]
	v_mfma_f32_16x16x32_bf16 v[124:127], v[152:155], v[168:171], v[124:127]
	v_mfma_f32_16x16x32_bf16 v[120:123], v[160:163], v[168:171], v[120:123]
	v_mfma_f32_16x16x32_bf16 v[112:115], v[152:155], v[176:179], v[112:115]
	v_mfma_f32_16x16x32_bf16 v[104:107], v[160:163], v[176:179], v[104:107]
	v_mfma_f32_16x16x32_bf16 v[92:95], v[152:155], v[184:187], v[92:95]
	v_mfma_f32_16x16x32_bf16 v[88:91], v[160:163], v[184:187], v[88:91]
	v_mfma_f32_16x16x32_bf16 v[80:83], v[152:155], v[192:195], v[80:83]
	v_mfma_f32_16x16x32_bf16 v[72:75], v[160:163], v[192:195], v[72:75]
	v_mfma_f32_16x16x32_bf16 v[116:119], v[196:199], v[164:167], v[116:119]
	v_mfma_f32_16x16x32_bf16 v[108:111], v[204:207], v[164:167], v[108:111]
	v_mfma_f32_16x16x32_bf16 v[100:103], v[196:199], v[172:175], v[100:103]
	v_mfma_f32_16x16x32_bf16 v[96:99], v[204:207], v[172:175], v[96:99]
	v_mfma_f32_16x16x32_bf16 v[84:87], v[196:199], v[180:183], v[84:87]
	v_mfma_f32_16x16x32_bf16 v[76:79], v[204:207], v[180:183], v[76:79]
	v_mfma_f32_16x16x32_bf16 v[68:71], v[196:199], v[188:191], v[68:71]
	v_mfma_f32_16x16x32_bf16 v[64:67], v[204:207], v[188:191], v[64:67]
	v_mfma_f32_16x16x32_bf16 v[116:119], v[200:203], v[168:171], v[116:119]
	v_mfma_f32_16x16x32_bf16 v[108:111], v[208:211], v[168:171], v[108:111]
	v_mfma_f32_16x16x32_bf16 v[100:103], v[200:203], v[176:179], v[100:103]
	v_mfma_f32_16x16x32_bf16 v[96:99], v[208:211], v[176:179], v[96:99]
	v_mfma_f32_16x16x32_bf16 v[84:87], v[200:203], v[184:187], v[84:87]
	v_mfma_f32_16x16x32_bf16 v[76:79], v[208:211], v[184:187], v[76:79]
	v_mfma_f32_16x16x32_bf16 v[68:71], v[200:203], v[192:195], v[68:71]
	v_mfma_f32_16x16x32_bf16 v[64:67], v[208:211], v[192:195], v[64:67]
	s_setprio 0
	s_barrier
	s_nop 1
	ds_read_b128 v[164:167], v150 offset:16384
	ds_read_b128 v[168:171], v150 offset:17408
	ds_read_b128 v[172:175], v150 offset:18432
	ds_read_b128 v[176:179], v150 offset:19456
	ds_read_b128 v[180:183], v150 offset:20480
	ds_read_b128 v[184:187], v150 offset:21504
	ds_read_b128 v[188:191], v150 offset:22528
	ds_read_b128 v[192:195], v150 offset:23552
	s_add_i32 s30, s45, s7
	v_lshl_add_u64 v[144:145], s[36:37], 0, v[128:129]
	s_mov_b32 m0, s30
	s_nop 0
	global_load_lds_dwordx4 v[144:145], off
	v_lshl_add_u64 v[212:213], s[36:37], 0, v[130:131]
	s_add_i32 m0, s30, 0x2000
	s_nop 0
	global_load_lds_dwordx4 v[212:213], off
	s_mov_b32 m0, s8
	v_lshl_add_u64 v[214:215], s[38:39], 0, v[128:129]
	global_load_lds_dwordx4 v[214:215], off
	v_lshl_add_u64 v[216:217], s[38:39], 0, v[130:131]
	s_mov_b32 m0, s9
	s_nop 0
	global_load_lds_dwordx4 v[216:217], off
	s_add_u32 s30, s36, 0xb0000
	s_addc_u32 s31, s37, 0
	s_add_i32 s75, s46, s7
	v_lshl_add_u64 v[254:255], s[30:31], 0, v[128:129]
	s_mov_b32 m0, s75
	s_nop 0
	global_load_lds_dwordx4 v[254:255], off
	v_lshl_add_u64 v[254:255], s[30:31], 0, v[130:131]
	s_add_i32 m0, s75, 0x2000
	s_nop 0
	global_load_lds_dwordx4 v[254:255], off
	s_waitcnt vmcnt(6)
	s_waitcnt lgkmcnt(0)
	s_barrier
; #define PG8_STAGE(bufoff, gbase, voff) do { _Pragma("unroll") for (int _i = 0; _i < 2; ++_i) \
;         __builtin_amdgcn_global_load_lds((const unsigned*)((const char*)(gbase) + (voff)[_i]), (LAS unsigned*)(lds + (bufoff) + ldsw + _i * 8192), 16, 0, 0); } while (0)
; #define PG8_LDA(dst, b, h) do { _Pragma("unroll") for (int m = 0; m < 4; ++m) _Pragma("unroll") for (int k = 0; k < 2; ++k) dst[m][k] = *(const LAS bf16x8*)(lds + PG8_SA(b, h) + aoff + m * 2048 + k * 1024); } while (0)
; #define PG8_LDB(dst, b, h) do { _Pragma("unroll") for (int n = 0; n < 2; ++n) _Pragma("unroll") for (int k = 0; k < 2; ++k) dst[n][k] = *(const LAS bf16x8*)(lds + PG8_SB(b, h) + boff + n * 2048 + k * 1024); } while (0)
; #define PG8_MMA(ai, bj, At, Bt) do { __builtin_amdgcn_s_setprio(1); _Pragma("unroll") for (int m = 0; m < 4; ++m) _Pragma("unroll") for (int n = 0; n < 2; ++n) _Pragma("unroll") for (int k = 0; k < 2; ++k) \
;         acc[ai][bj][m][n] = __builtin_amdgcn_mfma_f32_16x16x32_bf16(Bt[n][k], At[m][k], acc[ai][bj][m][n], 0, 0, 0); __builtin_amdgcn_s_setprio(0); } while (0)
; #define PG8_WAIT_V(n) asm volatile("s_waitcnt vmcnt(" #n ")" ::: "memory")
; #define PG8_WAIT_L(n) asm volatile("s_waitcnt lgkmcnt(" #n ")" ::: "memory")
; #define PG8_BAR __builtin_amdgcn_s_barrier()
; #define PG8_SCHED __builtin_amdgcn_sched_barrier(0)
; template <class Epi>
; __device__ __forceinline__ void gemm_phase(LAS unsigned char* lds, const Gemm g, const StaticOrder& S, const Epi& E) {
;     ...
;             PG8_WAIT_L(8); PG8_BAR; PG8_WAIT_L(0); PG8_MMA(0, 0, At, B0); PG8_BAR; PG8_SCHED;
;             PG8_LDB(B1, 0, 1); PG8_STAGE(PG8_SB(0, 0), b2, voffB);
;             PG8_BAR; PG8_WAIT_L(0); PG8_MMA(0, 1, At, B1); PG8_BAR;
;             PG8_LDA(At, 0, 1); PG8_STAGE(PG8_SA(0, 0), a2, voffA);
;             PG8_BAR; PG8_WAIT_L(0); PG8_MMA(1, 0, At, B0); PG8_BAR; PG8_SCHED;
;             PG8_STAGE(PG8_SB(0, 1), b2 + hstepB, voffB);
;             PG8_WAIT_V(6); PG8_BAR; PG8_MMA(1, 1, At, B1); PG8_BAR;
;             PG8_LDB(B0, 1, 0); PG8_SCHED; PG8_LDA(At, 1, 0); PG8_STAGE(PG8_SA(0, 1), a2 + hstepA, voffA);
;             PG8_WAIT_L(8); PG8_BAR; PG8_WAIT_L(0); PG8_MMA(0, 0, At, B0); PG8_BAR; PG8_SCHED;
;             PG8_LDB(B1, 1, 1); PG8_STAGE(PG8_SB(1, 0), b3, voffB);
;             PG8_BAR; PG8_WAIT_L(0); PG8_MMA(0, 1, At, B1); PG8_BAR;
	s_setprio 1
	v_mfma_f32_16x16x32_bf16 v[60:63], v[140:143], v[164:167], v[60:63]
	v_mfma_f32_16x16x32_bf16 v[56:59], v[156:159], v[164:167], v[56:59]
	v_mfma_f32_16x16x32_bf16 v[48:51], v[140:143], v[172:175], v[48:51]
	v_mfma_f32_16x16x32_bf16 v[40:43], v[156:159], v[172:175], v[40:43]
	v_mfma_f32_16x16x32_bf16 v[28:31], v[140:143], v[180:183], v[28:31]
	v_mfma_f32_16x16x32_bf16 v[24:27], v[156:159], v[180:183], v[24:27]
	v_mfma_f32_16x16x32_bf16 v[16:19], v[140:143], v[188:191], v[16:19]
	v_mfma_f32_16x16x32_bf16 v[8:11], v[156:159], v[188:191], v[8:11]
	v_mfma_f32_16x16x32_bf16 v[60:63], v[152:155], v[168:171], v[60:63]
	v_mfma_f32_16x16x32_bf16 v[56:59], v[160:163], v[168:171], v[56:59]
	v_mfma_f32_16x16x32_bf16 v[48:51], v[152:155], v[176:179], v[48:51]
	v_mfma_f32_16x16x32_bf16 v[40:43], v[160:163], v[176:179], v[40:43]
	v_mfma_f32_16x16x32_bf16 v[28:31], v[152:155], v[184:187], v[28:31]
	v_mfma_f32_16x16x32_bf16 v[24:27], v[160:163], v[184:187], v[24:27]
	v_mfma_f32_16x16x32_bf16 v[16:19], v[152:155], v[192:195], v[16:19]
	v_mfma_f32_16x16x32_bf16 v[8:11], v[160:163], v[192:195], v[8:11]
	v_mfma_f32_16x16x32_bf16 v[52:55], v[196:199], v[164:167], v[52:55]
	v_mfma_f32_16x16x32_bf16 v[44:47], v[204:207], v[164:167], v[44:47]
	v_mfma_f32_16x16x32_bf16 v[36:39], v[196:199], v[172:175], v[36:39]
	v_mfma_f32_16x16x32_bf16 v[32:35], v[204:207], v[172:175], v[32:35]
	v_mfma_f32_16x16x32_bf16 v[20:23], v[196:199], v[180:183], v[20:23]
	v_mfma_f32_16x16x32_bf16 v[12:15], v[204:207], v[180:183], v[12:15]
	v_mfma_f32_16x16x32_bf16 v[4:7], v[196:199], v[188:191], v[4:7]
	v_mfma_f32_16x16x32_bf16 v[0:3], v[204:207], v[188:191], v[0:3]
	v_mfma_f32_16x16x32_bf16 v[52:55], v[200:203], v[168:171], v[52:55]
	v_mfma_f32_16x16x32_bf16 v[44:47], v[208:211], v[168:171], v[44:47]
	v_mfma_f32_16x16x32_bf16 v[36:39], v[200:203], v[176:179], v[36:39]
	v_mfma_f32_16x16x32_bf16 v[32:35], v[208:211], v[176:179], v[32:35]
	v_mfma_f32_16x16x32_bf16 v[20:23], v[200:203], v[184:187], v[20:23]
	v_mfma_f32_16x16x32_bf16 v[12:15], v[208:211], v[184:187], v[12:15]
	v_mfma_f32_16x16x32_bf16 v[4:7], v[200:203], v[192:195], v[4:7]
	v_mfma_f32_16x16x32_bf16 v[0:3], v[208:211], v[192:195], v[0:3]
	s_setprio 0
	s_add_i32 s75, 0, 0x18000
	v_add_u32_e32 v160, s75, v147
	s_barrier
	ds_read_b128 v[140:143], v160
	ds_read_b128 v[152:155], v160 offset:1024
	ds_read_b128 v[156:159], v160 offset:2048
	ds_read_b128 v[160:163], v160 offset:3072
	s_add_u32 s30, s38, 0xb0000
	s_addc_u32 s31, s39, 0
	s_mov_b32 m0, s40
	v_lshl_add_u64 v[196:197], s[30:31], 0, v[128:129]
	ds_read_b128 v[164:167], v150 offset:32768
	ds_read_b128 v[168:171], v150 offset:33792
	ds_read_b128 v[172:175], v150 offset:34816
	ds_read_b128 v[176:179], v150 offset:35840
	ds_read_b128 v[180:183], v150 offset:36864
	ds_read_b128 v[184:187], v150 offset:37888
	ds_read_b128 v[188:191], v150 offset:38912
	ds_read_b128 v[192:195], v150 offset:39936
	global_load_lds_dwordx4 v[196:197], off
	v_lshl_add_u64 v[196:197], s[30:31], 0, v[130:131]
	s_mov_b32 m0, s41
	s_nop 0
	global_load_lds_dwordx4 v[196:197], off
	s_add_i32 s38, 0, 0x1c000
	v_add_u32_e32 v208, s38, v147
	ds_read_b128 v[196:199], v208
	ds_read_b128 v[200:203], v208 offset:1024
	ds_read_b128 v[204:207], v208 offset:2048
	ds_read_b128 v[208:211], v208 offset:3072
	s_waitcnt lgkmcnt(0)
	s_barrier
	s_setprio 1
	v_mfma_f32_16x16x32_bf16 v[124:127], v[140:143], v[164:167], v[124:127]
	v_mfma_f32_16x16x32_bf16 v[120:123], v[156:159], v[164:167], v[120:123]
	v_mfma_f32_16x16x32_bf16 v[112:115], v[140:143], v[172:175], v[112:115]
	v_mfma_f32_16x16x32_bf16 v[104:107], v[156:159], v[172:175], v[104:107]
	v_mfma_f32_16x16x32_bf16 v[92:95], v[140:143], v[180:183], v[92:95]
	v_mfma_f32_16x16x32_bf16 v[88:91], v[156:159], v[180:183], v[88:91]
	v_mfma_f32_16x16x32_bf16 v[80:83], v[140:143], v[188:191], v[80:83]
	v_mfma_f32_16x16x32_bf16 v[72:75], v[156:159], v[188:191], v[72:75]
	v_mfma_f32_16x16x32_bf16 v[124:127], v[152:155], v[168:171], v[124:127]
	v_mfma_f32_16x16x32_bf16 v[120:123], v[160:163], v[168:171], v[120:123]
	v_mfma_f32_16x16x32_bf16 v[112:115], v[152:155], v[176:179], v[112:115]
	v_mfma_f32_16x16x32_bf16 v[104:107], v[160:163], v[176:179], v[104:107]
	v_mfma_f32_16x16x32_bf16 v[92:95], v[152:155], v[184:187], v[92:95]
	v_mfma_f32_16x16x32_bf16 v[88:91], v[160:163], v[184:187], v[88:91]
	v_mfma_f32_16x16x32_bf16 v[80:83], v[152:155], v[192:195], v[80:83]
	v_mfma_f32_16x16x32_bf16 v[72:75], v[160:163], v[192:195], v[72:75]
	v_mfma_f32_16x16x32_bf16 v[116:119], v[196:199], v[164:167], v[116:119]
	v_mfma_f32_16x16x32_bf16 v[108:111], v[204:207], v[164:167], v[108:111]
	v_mfma_f32_16x16x32_bf16 v[100:103], v[196:199], v[172:175], v[100:103]
	v_mfma_f32_16x16x32_bf16 v[96:99], v[204:207], v[172:175], v[96:99]
	v_mfma_f32_16x16x32_bf16 v[84:87], v[196:199], v[180:183], v[84:87]
	v_mfma_f32_16x16x32_bf16 v[76:79], v[204:207], v[180:183], v[76:79]
	v_mfma_f32_16x16x32_bf16 v[68:71], v[196:199], v[188:191], v[68:71]
	v_mfma_f32_16x16x32_bf16 v[64:67], v[204:207], v[188:191], v[64:67]
	v_mfma_f32_16x16x32_bf16 v[116:119], v[200:203], v[168:171], v[116:119]
	v_mfma_f32_16x16x32_bf16 v[108:111], v[208:211], v[168:171], v[108:111]
	v_mfma_f32_16x16x32_bf16 v[100:103], v[200:203], v[176:179], v[100:103]
	v_mfma_f32_16x16x32_bf16 v[96:99], v[208:211], v[176:179], v[96:99]
	v_mfma_f32_16x16x32_bf16 v[84:87], v[200:203], v[184:187], v[84:87]
	v_mfma_f32_16x16x32_bf16 v[76:79], v[208:211], v[184:187], v[76:79]
	v_mfma_f32_16x16x32_bf16 v[68:71], v[200:203], v[192:195], v[68:71]
	v_mfma_f32_16x16x32_bf16 v[64:67], v[208:211], v[192:195], v[64:67]
	s_setprio 0
	s_barrier
; #define PG8_STAGE(bufoff, gbase, voff) do { _Pragma("unroll") for (int _i = 0; _i < 2; ++_i) \
;         __builtin_amdgcn_global_load_lds((const unsigned*)((const char*)(gbase) + (voff)[_i]), (LAS unsigned*)(lds + (bufoff) + ldsw + _i * 8192), 16, 0, 0); } while (0)
; #define PG8_LDA(dst, b, h) do { _Pragma("unroll") for (int m = 0; m < 4; ++m) _Pragma("unroll") for (int k = 0; k < 2; ++k) dst[m][k] = *(const LAS bf16x8*)(lds + PG8_SA(b, h) + aoff + m * 2048 + k * 1024); } while (0)
; #define PG8_BAR __builtin_amdgcn_s_barrier()
; template <class Epi>
; __device__ __forceinline__ void gemm_phase(LAS unsigned char* lds, const Gemm g, const StaticOrder& S, const Epi& E) {
;     ...
;             PG8_LDB(B0, 1, 0); PG8_SCHED; PG8_LDA(At, 1, 0); PG8_STAGE(PG8_SA(0, 1), a2 + hstepA, voffA);
;             PG8_WAIT_L(8); PG8_BAR; PG8_WAIT_L(0); PG8_MMA(0, 0, At, B0); PG8_BAR; PG8_SCHED;
;             PG8_LDB(B1, 1, 1); PG8_STAGE(PG8_SB(1, 0), b3, voffB);
;             PG8_BAR; PG8_WAIT_L(0); PG8_MMA(0, 1, At, B1); PG8_BAR;
;             PG8_LDA(At, 1, 1); PG8_STAGE(PG8_SA(1, 0), a3, voffA);
;             PG8_BAR; PG8_WAIT_L(0); PG8_MMA(1, 0, At, B0); PG8_BAR; PG8_SCHED;
;             PG8_STAGE(PG8_SB(1, 1), b3 + hstepB, voffB);
;             PG8_WAIT_V(6); PG8_BAR; PG8_MMA(1, 1, At, B1); PG8_BAR;
;     __device__ __forceinline__ void operator()(AccRef acc, const Unit& u, int wr, int wc, int fr, int fq) const {
;         const int row0 = u.pm * 256 + wr * 64 + fr, col0 = u.pn * 256 + wc * 32 + 4 * fq;
;         f32x4 sv[2][2], bv[2][2];
; #pragma unroll
;         for (int bj = 0; bj < 2; ++bj)
; #pragma unroll
;             for (int n = 0; n < 2; ++n) {
;                 sv[bj][n] = scale ? *(const f32x4*)(scale + col0 + bj * 128 + n * 16) : (f32x4){1.f, 1.f, 1.f, 1.f};
;                 bv[bj][n] = bias ? *(const f32x4*)(bias + col0 + bj * 128 + n * 16) : (f32x4){0.f, 0.f, 0.f, 0.f}; }
; #pragma unroll
;         for (int ai = 0; ai < 2; ++ai)
; #pragma unroll
;             for (int mh = 0; mh < 2; ++mh) {
;                 f32x4 bs[2][2][2];
; #pragma unroll
;                 for (int m = 0; m < 2; ++m)
; #pragma unroll
;                     for (int bj = 0; bj < 2; ++bj)
; #pragma unroll
;                         for (int n = 0; n < 2; ++n) bs[m][bj][n] = *(const f32x4*)(base + (size_t)(row0 + ai * 128 + (2 * mh + m) * 16) * D + col0 + bj * 128 + n * 16);
	s_nop 1
	ds_read_b128 v[164:167], v150 offset:49152
	ds_read_b128 v[168:171], v150 offset:50176
	ds_read_b128 v[172:175], v150 offset:51200
	ds_read_b128 v[176:179], v150 offset:52224
	ds_read_b128 v[180:183], v150 offset:53248
	ds_read_b128 v[184:187], v150 offset:54272
	ds_read_b128 v[188:191], v150 offset:55296
	ds_read_b128 v[192:195], v150 offset:56320
	s_add_i32 s30, s75, s7
	v_lshl_add_u64 v[254:255], v[144:145], 0, s[22:23]
	s_mov_b32 m0, s30
	s_nop 0
	global_load_lds_dwordx4 v[254:255], off
	v_lshl_add_u64 v[254:255], v[212:213], 0, s[22:23]
	s_add_i32 m0, s30, 0x2000
	s_nop 0
	global_load_lds_dwordx4 v[254:255], off
	s_mov_b32 m0, s43
	v_lshl_add_u64 v[254:255], v[214:215], 0, s[22:23]
	global_load_lds_dwordx4 v[254:255], off
	v_lshl_add_u64 v[144:145], v[216:217], 0, s[22:23]
	s_mov_b32 m0, s44
	s_nop 0
	global_load_lds_dwordx4 v[144:145], off
	s_add_u32 s30, s36, 0xb0080
	s_addc_u32 s31, s37, 0
	s_add_i32 s36, s38, s7
	v_lshl_add_u64 v[254:255], s[30:31], 0, v[128:129]
	s_mov_b32 m0, s36
	s_nop 0
	global_load_lds_dwordx4 v[254:255], off
	v_lshl_add_u64 v[254:255], s[30:31], 0, v[130:131]
	s_add_i32 m0, s36, 0x2000
	s_nop 0
	global_load_lds_dwordx4 v[254:255], off
	s_waitcnt vmcnt(6)
	s_waitcnt lgkmcnt(0)
	s_barrier
	s_setprio 1
	v_mfma_f32_16x16x32_bf16 v[60:63], v[140:143], v[164:167], v[60:63]
	v_mfma_f32_16x16x32_bf16 v[56:59], v[156:159], v[164:167], v[56:59]
	v_mfma_f32_16x16x32_bf16 v[48:51], v[140:143], v[172:175], v[48:51]
	v_mfma_f32_16x16x32_bf16 v[40:43], v[156:159], v[172:175], v[40:43]
	v_mfma_f32_16x16x32_bf16 v[28:31], v[140:143], v[180:183], v[28:31]
	v_mfma_f32_16x16x32_bf16 v[24:27], v[156:159], v[180:183], v[24:27]
	v_mfma_f32_16x16x32_bf16 v[16:19], v[140:143], v[188:191], v[16:19]
	v_mfma_f32_16x16x32_bf16 v[8:11], v[156:159], v[188:191], v[8:11]
	v_mfma_f32_16x16x32_bf16 v[60:63], v[152:155], v[168:171], v[60:63]
	v_mfma_f32_16x16x32_bf16 v[56:59], v[160:163], v[168:171], v[56:59]
	v_mfma_f32_16x16x32_bf16 v[48:51], v[152:155], v[176:179], v[48:51]
	v_mfma_f32_16x16x32_bf16 v[40:43], v[160:163], v[176:179], v[40:43]
	v_mfma_f32_16x16x32_bf16 v[28:31], v[152:155], v[184:187], v[28:31]
	v_mfma_f32_16x16x32_bf16 v[24:27], v[160:163], v[184:187], v[24:27]
	v_mfma_f32_16x16x32_bf16 v[16:19], v[152:155], v[192:195], v[16:19]
	v_mfma_f32_16x16x32_bf16 v[8:11], v[160:163], v[192:195], v[8:11]
	v_mfma_f32_16x16x32_bf16 v[52:55], v[196:199], v[164:167], v[52:55]
	v_mfma_f32_16x16x32_bf16 v[44:47], v[204:207], v[164:167], v[44:47]
	v_mfma_f32_16x16x32_bf16 v[36:39], v[196:199], v[172:175], v[36:39]
	v_mfma_f32_16x16x32_bf16 v[32:35], v[204:207], v[172:175], v[32:35]
	v_mfma_f32_16x16x32_bf16 v[20:23], v[196:199], v[180:183], v[20:23]
	v_mfma_f32_16x16x32_bf16 v[12:15], v[204:207], v[180:183], v[12:15]
	v_mfma_f32_16x16x32_bf16 v[4:7], v[196:199], v[188:191], v[4:7]
	v_mfma_f32_16x16x32_bf16 v[0:3], v[204:207], v[188:191], v[0:3]
	v_mfma_f32_16x16x32_bf16 v[52:55], v[200:203], v[168:171], v[52:55]
	v_mfma_f32_16x16x32_bf16 v[44:47], v[208:211], v[168:171], v[44:47]
	v_mfma_f32_16x16x32_bf16 v[36:39], v[200:203], v[176:179], v[36:39]
	v_mfma_f32_16x16x32_bf16 v[32:35], v[208:211], v[176:179], v[32:35]
	v_mfma_f32_16x16x32_bf16 v[20:23], v[200:203], v[184:187], v[20:23]
	v_mfma_f32_16x16x32_bf16 v[12:15], v[208:211], v[184:187], v[12:15]
	v_mfma_f32_16x16x32_bf16 v[4:7], v[200:203], v[192:195], v[4:7]
	v_mfma_f32_16x16x32_bf16 v[0:3], v[208:211], v[192:195], v[0:3]
	s_setprio 0
	s_add_i32 s74, s74, 2
	s_add_u32 s72, s72, 0x100
	s_addc_u32 s73, s73, 0
	s_cmp_gt_u32 s74, 41
	s_mov_b64 s[30:31], s[34:35]
	s_barrier
	s_cbranch_scc0 .LBB0_1461
	v_lshl_or_b32 v144, s49, 8, v148
	v_lshl_add_u32 v145, s63, 8, v146
	v_lshlrev_b32_e32 v144, 2, v144
	v_lshl_add_u32 v145, v145, 12, v144
	v_add_u32_e32 v216, 0x10000, v145
	v_add_u32_e32 v217, 0x20000, v145
	v_add_u32_e32 v218, 0x30000, v145
	v_add_u32_e32 v232, 0x80000, v145
	v_add_u32_e32 v233, 0x90000, v145
	v_add_u32_e32 v235, 0xa0000, v145
	v_add_u32_e32 v253, 0xb0000, v145
	s_and_b64 vcc, exec, s[10:11]
	s_mov_b32 s49, s47
	s_mov_b32 s63, s48
	s_mov_b64 s[34:35], s[14:15]
	s_mov_b64 s[30:31], s[12:13]
	global_load_dwordx4 v[140:143], v145, s[52:53]
	global_load_dwordx4 v[152:155], v145, s[52:53] offset:64
	global_load_dwordx4 v[156:159], v145, s[52:53] offset:512
	global_load_dwordx4 v[160:163], v145, s[52:53] offset:576
	global_load_dwordx4 v[164:167], v216, s[52:53]
	global_load_dwordx4 v[168:171], v216, s[52:53] offset:64
	global_load_dwordx4 v[172:175], v216, s[52:53] offset:512
	global_load_dwordx4 v[176:179], v216, s[52:53] offset:576
	global_load_dwordx4 v[180:183], v217, s[52:53]
	global_load_dwordx4 v[184:187], v217, s[52:53] offset:64
	global_load_dwordx4 v[188:191], v217, s[52:53] offset:512
	global_load_dwordx4 v[192:195], v217, s[52:53] offset:576
	global_load_dwordx4 v[196:199], v218, s[52:53]
	global_load_dwordx4 v[200:203], v218, s[52:53] offset:64
	global_load_dwordx4 v[204:207], v218, s[52:53] offset:512
	global_load_dwordx4 v[208:211], v218, s[52:53] offset:576
	global_load_dwordx4 v[212:215], v232, s[52:53]
	global_load_dwordx4 v[220:223], v232, s[52:53] offset:64
	global_load_dwordx4 v[224:227], v232, s[52:53] offset:512
	global_load_dwordx4 v[228:231], v232, s[52:53] offset:576
	global_load_dwordx4 v[236:239], v233, s[52:53]
	global_load_dwordx4 v[240:243], v233, s[52:53] offset:64
	global_load_dwordx4 v[244:247], v233, s[52:53] offset:512
	global_load_dwordx4 v[248:251], v233, s[52:53] offset:576
	v_pk_add_f32 v[124:125], v[124:125], 0 op_sel_hi:[1,0]
	v_pk_add_f32 v[126:127], v[126:127], 0 op_sel_hi:[1,0]
	v_pk_add_f32 v[120:121], v[120:121], 0 op_sel_hi:[1,0]
;     __device__ __forceinline__ void operator()(AccRef acc, const Unit& u, int wr, int wc, int fr, int fq) const {
;     ...
;                         for (int n = 0; n < 2; ++n) bs[m][bj][n] = *(const f32x4*)(base + (size_t)(row0 + ai * 128 + (2 * mh + m) * 16) * D + col0 + bj * 128 + n * 16);
; #pragma unroll
;                 for (int m = 0; m < 2; ++m)
; #pragma unroll
;                     for (int bj = 0; bj < 2; ++bj)
; #pragma unroll
;                         for (int n = 0; n < 2; ++n) *(f32x4*)(out + (size_t)(row0 + ai * 128 + (2 * mh + m) * 16) * D + col0 + bj * 128 + n * 16) = bs[m][bj][n] + sv[bj][n] * (acc[ai][bj][2 * mh + m][n] + bv[bj][n]);
;                 asm volatile("" ::: "memory"); }
	v_pk_add_f32 v[122:123], v[122:123], 0 op_sel_hi:[1,0]
	v_pk_add_f32 v[116:117], v[116:117], 0 op_sel_hi:[1,0]
	v_pk_add_f32 v[118:119], v[118:119], 0 op_sel_hi:[1,0]
	v_pk_add_f32 v[108:109], v[108:109], 0 op_sel_hi:[1,0]
	v_pk_add_f32 v[110:111], v[110:111], 0 op_sel_hi:[1,0]
	v_pk_add_f32 v[112:113], v[112:113], 0 op_sel_hi:[1,0]
	v_pk_add_f32 v[114:115], v[114:115], 0 op_sel_hi:[1,0]
	v_pk_add_f32 v[104:105], v[104:105], 0 op_sel_hi:[1,0]
	v_pk_add_f32 v[106:107], v[106:107], 0 op_sel_hi:[1,0]
	v_pk_add_f32 v[100:101], v[100:101], 0 op_sel_hi:[1,0]
	v_pk_add_f32 v[102:103], v[102:103], 0 op_sel_hi:[1,0]
	v_pk_add_f32 v[96:97], v[96:97], 0 op_sel_hi:[1,0]
	v_pk_add_f32 v[98:99], v[98:99], 0 op_sel_hi:[1,0]
	v_pk_add_f32 v[92:93], v[92:93], 0 op_sel_hi:[1,0]
	v_pk_add_f32 v[94:95], v[94:95], 0 op_sel_hi:[1,0]
	v_pk_add_f32 v[88:89], v[88:89], 0 op_sel_hi:[1,0]
	v_pk_add_f32 v[90:91], v[90:91], 0 op_sel_hi:[1,0]
	v_pk_add_f32 v[84:85], v[84:85], 0 op_sel_hi:[1,0]
	v_pk_add_f32 v[86:87], v[86:87], 0 op_sel_hi:[1,0]
	v_pk_add_f32 v[76:77], v[76:77], 0 op_sel_hi:[1,0]
	v_pk_add_f32 v[78:79], v[78:79], 0 op_sel_hi:[1,0]
	v_pk_add_f32 v[80:81], v[80:81], 0 op_sel_hi:[1,0]
	v_pk_add_f32 v[82:83], v[82:83], 0 op_sel_hi:[1,0]
	v_pk_add_f32 v[72:73], v[72:73], 0 op_sel_hi:[1,0]
	v_pk_add_f32 v[74:75], v[74:75], 0 op_sel_hi:[1,0]
	v_pk_add_f32 v[68:69], v[68:69], 0 op_sel_hi:[1,0]
	v_pk_add_f32 v[70:71], v[70:71], 0 op_sel_hi:[1,0]
	v_pk_add_f32 v[64:65], v[64:65], 0 op_sel_hi:[1,0]
	v_pk_add_f32 v[66:67], v[66:67], 0 op_sel_hi:[1,0]
	v_pk_add_f32 v[60:61], v[60:61], 0 op_sel_hi:[1,0]
	v_pk_add_f32 v[62:63], v[62:63], 0 op_sel_hi:[1,0]
	v_pk_add_f32 v[56:57], v[56:57], 0 op_sel_hi:[1,0]
	v_pk_add_f32 v[58:59], v[58:59], 0 op_sel_hi:[1,0]
	v_pk_add_f32 v[52:53], v[52:53], 0 op_sel_hi:[1,0]
	v_pk_add_f32 v[54:55], v[54:55], 0 op_sel_hi:[1,0]
	v_pk_add_f32 v[44:45], v[44:45], 0 op_sel_hi:[1,0]
	v_pk_add_f32 v[46:47], v[46:47], 0 op_sel_hi:[1,0]
	v_pk_add_f32 v[48:49], v[48:49], 0 op_sel_hi:[1,0]
	v_pk_add_f32 v[50:51], v[50:51], 0 op_sel_hi:[1,0]
	v_pk_add_f32 v[40:41], v[40:41], 0 op_sel_hi:[1,0]
	v_pk_add_f32 v[42:43], v[42:43], 0 op_sel_hi:[1,0]
	v_pk_add_f32 v[36:37], v[36:37], 0 op_sel_hi:[1,0]
	v_pk_add_f32 v[38:39], v[38:39], 0 op_sel_hi:[1,0]
	v_pk_add_f32 v[32:33], v[32:33], 0 op_sel_hi:[1,0]
	v_pk_add_f32 v[34:35], v[34:35], 0 op_sel_hi:[1,0]
	v_pk_add_f32 v[28:29], v[28:29], 0 op_sel_hi:[1,0]
	v_pk_add_f32 v[30:31], v[30:31], 0 op_sel_hi:[1,0]
	v_pk_add_f32 v[24:25], v[24:25], 0 op_sel_hi:[1,0]
	v_pk_add_f32 v[26:27], v[26:27], 0 op_sel_hi:[1,0]
	v_pk_add_f32 v[20:21], v[20:21], 0 op_sel_hi:[1,0]
	v_pk_add_f32 v[22:23], v[22:23], 0 op_sel_hi:[1,0]
	v_pk_add_f32 v[12:13], v[12:13], 0 op_sel_hi:[1,0]
	v_pk_add_f32 v[14:15], v[14:15], 0 op_sel_hi:[1,0]
	v_pk_add_f32 v[16:17], v[16:17], 0 op_sel_hi:[1,0]
	v_pk_add_f32 v[18:19], v[18:19], 0 op_sel_hi:[1,0]
	v_pk_add_f32 v[8:9], v[8:9], 0 op_sel_hi:[1,0]
	v_pk_add_f32 v[10:11], v[10:11], 0 op_sel_hi:[1,0]
	v_pk_add_f32 v[4:5], v[4:5], 0 op_sel_hi:[1,0]
	v_pk_add_f32 v[6:7], v[6:7], 0 op_sel_hi:[1,0]
	v_pk_add_f32 v[0:1], v[0:1], 0 op_sel_hi:[1,0]
	v_pk_add_f32 v[2:3], v[2:3], 0 op_sel_hi:[1,0]
	s_waitcnt vmcnt(16)
	v_pk_add_f32 v[124:125], v[124:125], v[140:141]
	v_pk_add_f32 v[126:127], v[126:127], v[142:143]
	v_pk_add_f32 v[120:121], v[120:121], v[152:153]
	v_pk_add_f32 v[122:123], v[122:123], v[154:155]
	v_pk_add_f32 v[116:117], v[116:117], v[156:157]
	v_pk_add_f32 v[118:119], v[118:119], v[158:159]
	v_pk_add_f32 v[108:109], v[108:109], v[160:161]
	v_pk_add_f32 v[110:111], v[110:111], v[162:163]
	v_pk_add_f32 v[112:113], v[112:113], v[164:165]
	v_pk_add_f32 v[114:115], v[114:115], v[166:167]
	v_pk_add_f32 v[104:105], v[104:105], v[168:169]
	v_pk_add_f32 v[106:107], v[106:107], v[170:171]
	v_pk_add_f32 v[100:101], v[100:101], v[172:173]
	v_pk_add_f32 v[102:103], v[102:103], v[174:175]
	v_pk_add_f32 v[96:97], v[96:97], v[176:177]
	v_pk_add_f32 v[98:99], v[98:99], v[178:179]
	global_store_dwordx4 v145, v[124:127], s[52:53]
	global_store_dwordx4 v145, v[120:123], s[52:53] offset:64
	global_store_dwordx4 v145, v[116:119], s[52:53] offset:512
	global_store_dwordx4 v145, v[108:111], s[52:53] offset:576
	global_store_dwordx4 v216, v[112:115], s[52:53]
	global_store_dwordx4 v216, v[104:107], s[52:53] offset:64
	global_store_dwordx4 v216, v[100:103], s[52:53] offset:512
	global_store_dwordx4 v216, v[96:99], s[52:53] offset:576
	global_load_dwordx4 v[140:143], v235, s[52:53]
	global_load_dwordx4 v[152:155], v235, s[52:53] offset:64
	global_load_dwordx4 v[156:159], v235, s[52:53] offset:512
	global_load_dwordx4 v[160:163], v235, s[52:53] offset:576
	global_load_dwordx4 v[164:167], v253, s[52:53]
	global_load_dwordx4 v[168:171], v253, s[52:53] offset:64
	global_load_dwordx4 v[172:175], v253, s[52:53] offset:512
	global_load_dwordx4 v[176:179], v253, s[52:53] offset:576
	s_waitcnt vmcnt(24)
;     __device__ __forceinline__ void operator()(AccRef acc, const Unit& u, int wr, int wc, int fr, int fq) const {
;     ...
;                         for (int n = 0; n < 2; ++n) bs[m][bj][n] = *(const f32x4*)(base + (size_t)(row0 + ai * 128 + (2 * mh + m) * 16) * D + col0 + bj * 128 + n * 16);
; #pragma unroll
;                 for (int m = 0; m < 2; ++m)
; #pragma unroll
;                     for (int bj = 0; bj < 2; ++bj)
; #pragma unroll
;                         for (int n = 0; n < 2; ++n) *(f32x4*)(out + (size_t)(row0 + ai * 128 + (2 * mh + m) * 16) * D + col0 + bj * 128 + n * 16) = bs[m][bj][n] + sv[bj][n] * (acc[ai][bj][2 * mh + m][n] + bv[bj][n]);
;                 asm volatile("" ::: "memory"); }
	v_pk_add_f32 v[92:93], v[92:93], v[180:181]
	v_pk_add_f32 v[94:95], v[94:95], v[182:183]
	v_pk_add_f32 v[88:89], v[88:89], v[184:185]
	v_pk_add_f32 v[90:91], v[90:91], v[186:187]
	v_pk_add_f32 v[84:85], v[84:85], v[188:189]
	v_pk_add_f32 v[86:87], v[86:87], v[190:191]
	v_pk_add_f32 v[76:77], v[76:77], v[192:193]
	v_pk_add_f32 v[78:79], v[78:79], v[194:195]
	v_pk_add_f32 v[80:81], v[80:81], v[196:197]
	v_pk_add_f32 v[82:83], v[82:83], v[198:199]
	v_pk_add_f32 v[72:73], v[72:73], v[200:201]
	v_pk_add_f32 v[74:75], v[74:75], v[202:203]
	v_pk_add_f32 v[68:69], v[68:69], v[204:205]
	v_pk_add_f32 v[70:71], v[70:71], v[206:207]
	v_pk_add_f32 v[64:65], v[64:65], v[208:209]
	v_pk_add_f32 v[66:67], v[66:67], v[210:211]
	global_store_dwordx4 v217, v[92:95], s[52:53]
	global_store_dwordx4 v217, v[88:91], s[52:53] offset:64
	global_store_dwordx4 v217, v[84:87], s[52:53] offset:512
	global_store_dwordx4 v217, v[76:79], s[52:53] offset:576
	global_store_dwordx4 v218, v[80:83], s[52:53]
	global_store_dwordx4 v218, v[72:75], s[52:53] offset:64
	global_store_dwordx4 v218, v[68:71], s[52:53] offset:512
	global_store_dwordx4 v218, v[64:67], s[52:53] offset:576
	s_waitcnt vmcnt(24)
	v_pk_add_f32 v[60:61], v[60:61], v[212:213]
	v_pk_add_f32 v[62:63], v[62:63], v[214:215]
	v_pk_add_f32 v[56:57], v[56:57], v[220:221]
	v_pk_add_f32 v[58:59], v[58:59], v[222:223]
	v_pk_add_f32 v[52:53], v[52:53], v[224:225]
	v_pk_add_f32 v[54:55], v[54:55], v[226:227]
	v_pk_add_f32 v[44:45], v[44:45], v[228:229]
	v_pk_add_f32 v[46:47], v[46:47], v[230:231]
	v_pk_add_f32 v[48:49], v[48:49], v[236:237]
	v_pk_add_f32 v[50:51], v[50:51], v[238:239]
	v_pk_add_f32 v[40:41], v[40:41], v[240:241]
	v_pk_add_f32 v[42:43], v[42:43], v[242:243]
	v_pk_add_f32 v[36:37], v[36:37], v[244:245]
	v_pk_add_f32 v[38:39], v[38:39], v[246:247]
	v_pk_add_f32 v[32:33], v[32:33], v[248:249]
	v_pk_add_f32 v[34:35], v[34:35], v[250:251]
	global_store_dwordx4 v232, v[60:63], s[52:53]
	global_store_dwordx4 v232, v[56:59], s[52:53] offset:64
	global_store_dwordx4 v232, v[52:55], s[52:53] offset:512
	global_store_dwordx4 v232, v[44:47], s[52:53] offset:576
	global_store_dwordx4 v233, v[48:51], s[52:53]
	global_store_dwordx4 v233, v[40:43], s[52:53] offset:64
	global_store_dwordx4 v233, v[36:39], s[52:53] offset:512
	global_store_dwordx4 v233, v[32:35], s[52:53] offset:576
	s_waitcnt vmcnt(16)
	v_pk_add_f32 v[28:29], v[28:29], v[140:141]
	v_pk_add_f32 v[30:31], v[30:31], v[142:143]
	v_pk_add_f32 v[24:25], v[24:25], v[152:153]
	v_pk_add_f32 v[26:27], v[26:27], v[154:155]
	v_pk_add_f32 v[20:21], v[20:21], v[156:157]
	v_pk_add_f32 v[22:23], v[22:23], v[158:159]
	v_pk_add_f32 v[12:13], v[12:13], v[160:161]
	v_pk_add_f32 v[14:15], v[14:15], v[162:163]
	v_pk_add_f32 v[16:17], v[16:17], v[164:165]
	v_pk_add_f32 v[18:19], v[18:19], v[166:167]
	v_pk_add_f32 v[8:9], v[8:9], v[168:169]
	v_pk_add_f32 v[10:11], v[10:11], v[170:171]
	v_pk_add_f32 v[4:5], v[4:5], v[172:173]
	v_pk_add_f32 v[6:7], v[6:7], v[174:175]
	v_pk_add_f32 v[0:1], v[0:1], v[176:177]
	v_pk_add_f32 v[2:3], v[2:3], v[178:179]
	global_store_dwordx4 v235, v[28:31], s[52:53]
	global_store_dwordx4 v235, v[24:27], s[52:53] offset:64
	global_store_dwordx4 v235, v[20:23], s[52:53] offset:512
	global_store_dwordx4 v235, v[12:15], s[52:53] offset:576
	global_store_dwordx4 v253, v[16:19], s[52:53]
	global_store_dwordx4 v253, v[8:11], s[52:53] offset:64
	global_store_dwordx4 v253, v[4:7], s[52:53] offset:512
	global_store_dwordx4 v253, v[0:3], s[52:53] offset:576
	s_cbranch_vccz .LBB0_1450
	s_waitcnt vmcnt(0)
	s_cmpk_gt_u32 s4, 0xff
	s_cbranch_scc1 .LBB0_1465
	s_barrier

; #define PG8_STAGE(bufoff, gbase, voff) do { _Pragma("unroll") for (int _i = 0; _i < 2; ++_i) \
;         __builtin_amdgcn_global_load_lds((const unsigned*)((const char*)(gbase) + (voff)[_i]), (LAS unsigned*)(lds + (bufoff) + ldsw + _i * 8192), 16, 0, 0); } while (0)
; #define PG8_LDA(dst, b, h) do { _Pragma("unroll") for (int m = 0; m < 4; ++m) _Pragma("unroll") for (int k = 0; k < 2; ++k) dst[m][k] = *(const LAS bf16x8*)(lds + PG8_SA(b, h) + aoff + m * 2048 + k * 1024); } while (0)
; #define PG8_LDB(dst, b, h) do { _Pragma("unroll") for (int n = 0; n < 2; ++n) _Pragma("unroll") for (int k = 0; k < 2; ++k) dst[n][k] = *(const LAS bf16x8*)(lds + PG8_SB(b, h) + boff + n * 2048 + k * 1024); } while (0)
; #define PG8_MMA(ai, bj, At, Bt) do { __builtin_amdgcn_s_setprio(1); _Pragma("unroll") for (int m = 0; m < 4; ++m) _Pragma("unroll") for (int n = 0; n < 2; ++n) _Pragma("unroll") for (int k = 0; k < 2; ++k) \
;         acc[ai][bj][m][n] = __builtin_amdgcn_mfma_f32_16x16x32_bf16(Bt[n][k], At[m][k], acc[ai][bj][m][n], 0, 0, 0); __builtin_amdgcn_s_setprio(0); } while (0)
; #define PG8_WAIT_V(n) asm volatile("s_waitcnt vmcnt(" #n ")" ::: "memory")
; #define PG8_WAIT_L(n) asm volatile("s_waitcnt lgkmcnt(" #n ")" ::: "memory")
; template <class Epi>
; __device__ __forceinline__ void gemm_phase(LAS unsigned char* lds, const Gemm g, const StaticOrder& S, const Epi& E) {
;     ...
;         for (int t = 0; t < nt; t += 2) {
;             const bool last = (t == nt - 2);
;             const char* a1 = cA + (size_t)(t + 1) * kstep;
;             const char* a2 = last ? nA : cA + (size_t)(t + 2) * kstep; const char* b2 = last ? nB : cB + (size_t)(t + 2) * kstep;
;             const char* a3 = a2 + kstep; const char* b3 = b2 + kstep;
;             PG8_LDB(B0, 0, 0); PG8_SCHED; PG8_LDA(At, 0, 0); PG8_STAGE(PG8_SA(1, 1), a1 + hstepA, voffA);
;             PG8_WAIT_L(8); PG8_BAR; PG8_WAIT_L(0); PG8_MMA(0, 0, At, B0); PG8_BAR; PG8_SCHED;
;             PG8_LDB(B1, 0, 1); PG8_STAGE(PG8_SB(0, 0), b2, voffB);
;             PG8_BAR; PG8_WAIT_L(0); PG8_MMA(0, 1, At, B1); PG8_BAR;
;             PG8_LDA(At, 0, 1); PG8_STAGE(PG8_SA(0, 0), a2, voffA);
;             PG8_BAR; PG8_WAIT_L(0); PG8_MMA(1, 0, At, B0); PG8_BAR; PG8_SCHED;
;             PG8_STAGE(PG8_SB(0, 1), b2 + hstepB, voffB);
;             PG8_WAIT_V(6); PG8_BAR; PG8_MMA(1, 1, At, B1); PG8_BAR;
.LBB0_1820:
	ds_read_b128 v[140:143], v149
	ds_read_b128 v[152:155], v149 offset:1024
	ds_read_b128 v[156:159], v149 offset:2048
	ds_read_b128 v[160:163], v149 offset:3072
	s_add_u32 s36, s34, 0xfffc0080
	s_addc_u32 s37, s35, -1
	s_cmp_eq_u32 s70, 12
	s_cselect_b32 s39, s25, s37
	s_cselect_b32 s38, s47, s36
	s_cselect_b32 s37, s23, s63
	s_cselect_b32 s36, s48, s49
	v_lshl_add_u64 v[144:145], s[34:35], 0, v[132:133]
	s_add_i32 m0, s8, 0xc000
	ds_read_b128 v[164:167], v150
	ds_read_b128 v[168:171], v150 offset:1024
	ds_read_b128 v[172:175], v150 offset:2048
	ds_read_b128 v[176:179], v150 offset:3072
	ds_read_b128 v[180:183], v150 offset:4096
	ds_read_b128 v[184:187], v150 offset:5120
	ds_read_b128 v[188:191], v150 offset:6144
	ds_read_b128 v[192:195], v150 offset:7168
	global_load_lds_dwordx4 v[144:145], off
	v_lshl_add_u64 v[144:145], s[34:35], 0, v[134:135]
	s_add_i32 m0, s8, 0xe000
	s_nop 0
	global_load_lds_dwordx4 v[144:145], off
	ds_read_b128 v[196:199], v151
	ds_read_b128 v[200:203], v151 offset:1024
	ds_read_b128 v[204:207], v151 offset:2048
	ds_read_b128 v[208:211], v151 offset:3072
	s_waitcnt lgkmcnt(0)
	s_barrier
	s_setprio 1
	v_mfma_f32_16x16x32_bf16 v[124:127], v[140:143], v[164:167], v[124:127]
	v_mfma_f32_16x16x32_bf16 v[120:123], v[156:159], v[164:167], v[120:123]
	v_mfma_f32_16x16x32_bf16 v[112:115], v[140:143], v[172:175], v[112:115]
	v_mfma_f32_16x16x32_bf16 v[104:107], v[156:159], v[172:175], v[104:107]
	v_mfma_f32_16x16x32_bf16 v[92:95], v[140:143], v[180:183], v[92:95]
	v_mfma_f32_16x16x32_bf16 v[88:91], v[156:159], v[180:183], v[88:91]
	v_mfma_f32_16x16x32_bf16 v[80:83], v[140:143], v[188:191], v[80:83]
	v_mfma_f32_16x16x32_bf16 v[72:75], v[156:159], v[188:191], v[72:75]
	v_mfma_f32_16x16x32_bf16 v[124:127], v[152:155], v[168:171], v[124:127]
	v_mfma_f32_16x16x32_bf16 v[120:123], v[160:163], v[168:171], v[120:123]
	v_mfma_f32_16x16x32_bf16 v[112:115], v[152:155], v[176:179], v[112:115]
	v_mfma_f32_16x16x32_bf16 v[104:107], v[160:163], v[176:179], v[104:107]
	v_mfma_f32_16x16x32_bf16 v[92:95], v[152:155], v[184:187], v[92:95]
	v_mfma_f32_16x16x32_bf16 v[88:91], v[160:163], v[184:187], v[88:91]
	v_mfma_f32_16x16x32_bf16 v[80:83], v[152:155], v[192:195], v[80:83]
	v_mfma_f32_16x16x32_bf16 v[72:75], v[160:163], v[192:195], v[72:75]
	v_mfma_f32_16x16x32_bf16 v[116:119], v[196:199], v[164:167], v[116:119]
	v_mfma_f32_16x16x32_bf16 v[108:111], v[204:207], v[164:167], v[108:111]
	v_mfma_f32_16x16x32_bf16 v[100:103], v[196:199], v[172:175], v[100:103]
	v_mfma_f32_16x16x32_bf16 v[96:99], v[204:207], v[172:175], v[96:99]
	v_mfma_f32_16x16x32_bf16 v[84:87], v[196:199], v[180:183], v[84:87]
	v_mfma_f32_16x16x32_bf16 v[76:79], v[204:207], v[180:183], v[76:79]
	v_mfma_f32_16x16x32_bf16 v[68:71], v[196:199], v[188:191], v[68:71]
	v_mfma_f32_16x16x32_bf16 v[64:67], v[204:207], v[188:191], v[64:67]
	v_mfma_f32_16x16x32_bf16 v[116:119], v[200:203], v[168:171], v[116:119]
	v_mfma_f32_16x16x32_bf16 v[108:111], v[208:211], v[168:171], v[108:111]
	v_mfma_f32_16x16x32_bf16 v[100:103], v[200:203], v[176:179], v[100:103]
	v_mfma_f32_16x16x32_bf16 v[96:99], v[208:211], v[176:179], v[96:99]
	v_mfma_f32_16x16x32_bf16 v[84:87], v[200:203], v[184:187], v[84:87]
	v_mfma_f32_16x16x32_bf16 v[76:79], v[208:211], v[184:187], v[76:79]
	v_mfma_f32_16x16x32_bf16 v[68:71], v[200:203], v[192:195], v[68:71]
	v_mfma_f32_16x16x32_bf16 v[64:67], v[208:211], v[192:195], v[64:67]
	s_setprio 0
	s_barrier
	s_nop 1
	ds_read_b128 v[164:167], v150 offset:16384
	ds_read_b128 v[168:171], v150 offset:17408
	ds_read_b128 v[172:175], v150 offset:18432
	ds_read_b128 v[176:179], v150 offset:19456
	ds_read_b128 v[180:183], v150 offset:20480
	ds_read_b128 v[184:187], v150 offset:21504
	ds_read_b128 v[188:191], v150 offset:22528
	ds_read_b128 v[192:195], v150 offset:23552
	s_add_i32 s71, s44, s7
	v_lshl_add_u64 v[144:145], s[36:37], 0, v[128:129]
	s_mov_b32 m0, s71
	s_nop 0
	global_load_lds_dwordx4 v[144:145], off
	v_lshl_add_u64 v[212:213], s[36:37], 0, v[130:131]
	s_add_i32 m0, s71, 0x2000
	s_nop 0
	global_load_lds_dwordx4 v[212:213], off
	s_mov_b32 m0, s8
	v_lshl_add_u64 v[214:215], s[38:39], 0, v[128:129]
	global_load_lds_dwordx4 v[214:215], off
	v_lshl_add_u64 v[216:217], s[38:39], 0, v[130:131]
	s_mov_b32 m0, s9
	s_nop 0
	global_load_lds_dwordx4 v[216:217], off
	s_add_u32 s72, s36, 0x40000
	s_addc_u32 s73, s37, 0
	s_add_i32 s71, s45, s7
	v_lshl_add_u64 v[254:255], s[72:73], 0, v[128:129]
	s_mov_b32 m0, s71
	s_nop 0
	global_load_lds_dwordx4 v[254:255], off
	v_lshl_add_u64 v[254:255], s[72:73], 0, v[130:131]
	s_add_i32 m0, s71, 0x2000
	s_nop 0
	global_load_lds_dwordx4 v[254:255], off
	s_waitcnt vmcnt(6)
	s_waitcnt lgkmcnt(0)
	s_barrier
; #define PG8_STAGE(bufoff, gbase, voff) do { _Pragma("unroll") for (int _i = 0; _i < 2; ++_i) \
;         __builtin_amdgcn_global_load_lds((const unsigned*)((const char*)(gbase) + (voff)[_i]), (LAS unsigned*)(lds + (bufoff) + ldsw + _i * 8192), 16, 0, 0); } while (0)
; #define PG8_LDA(dst, b, h) do { _Pragma("unroll") for (int m = 0; m < 4; ++m) _Pragma("unroll") for (int k = 0; k < 2; ++k) dst[m][k] = *(const LAS bf16x8*)(lds + PG8_SA(b, h) + aoff + m * 2048 + k * 1024); } while (0)
; #define PG8_LDB(dst, b, h) do { _Pragma("unroll") for (int n = 0; n < 2; ++n) _Pragma("unroll") for (int k = 0; k < 2; ++k) dst[n][k] = *(const LAS bf16x8*)(lds + PG8_SB(b, h) + boff + n * 2048 + k * 1024); } while (0)
; #define PG8_MMA(ai, bj, At, Bt) do { __builtin_amdgcn_s_setprio(1); _Pragma("unroll") for (int m = 0; m < 4; ++m) _Pragma("unroll") for (int n = 0; n < 2; ++n) _Pragma("unroll") for (int k = 0; k < 2; ++k) \
;         acc[ai][bj][m][n] = __builtin_amdgcn_mfma_f32_16x16x32_bf16(Bt[n][k], At[m][k], acc[ai][bj][m][n], 0, 0, 0); __builtin_amdgcn_s_setprio(0); } while (0)
; #define PG8_WAIT_V(n) asm volatile("s_waitcnt vmcnt(" #n ")" ::: "memory")
; #define PG8_WAIT_L(n) asm volatile("s_waitcnt lgkmcnt(" #n ")" ::: "memory")
; #define PG8_BAR __builtin_amdgcn_s_barrier()
; #define PG8_SCHED __builtin_amdgcn_sched_barrier(0)
; template <class Epi>
; __device__ __forceinline__ void gemm_phase(LAS unsigned char* lds, const Gemm g, const StaticOrder& S, const Epi& E) {
;     ...
;             PG8_WAIT_L(8); PG8_BAR; PG8_WAIT_L(0); PG8_MMA(0, 0, At, B0); PG8_BAR; PG8_SCHED;
;             PG8_LDB(B1, 0, 1); PG8_STAGE(PG8_SB(0, 0), b2, voffB);
;             PG8_BAR; PG8_WAIT_L(0); PG8_MMA(0, 1, At, B1); PG8_BAR;
;             PG8_LDA(At, 0, 1); PG8_STAGE(PG8_SA(0, 0), a2, voffA);
;             PG8_BAR; PG8_WAIT_L(0); PG8_MMA(1, 0, At, B0); PG8_BAR; PG8_SCHED;
;             PG8_STAGE(PG8_SB(0, 1), b2 + hstepB, voffB);
;             PG8_WAIT_V(6); PG8_BAR; PG8_MMA(1, 1, At, B1); PG8_BAR;
;             PG8_LDB(B0, 1, 0); PG8_SCHED; PG8_LDA(At, 1, 0); PG8_STAGE(PG8_SA(0, 1), a2 + hstepA, voffA);
;             PG8_WAIT_L(8); PG8_BAR; PG8_WAIT_L(0); PG8_MMA(0, 0, At, B0); PG8_BAR; PG8_SCHED;
;             PG8_LDB(B1, 1, 1); PG8_STAGE(PG8_SB(1, 0), b3, voffB);
;             PG8_BAR; PG8_WAIT_L(0); PG8_MMA(0, 1, At, B1); PG8_BAR;
	s_setprio 1
	v_mfma_f32_16x16x32_bf16 v[60:63], v[140:143], v[164:167], v[60:63]
	v_mfma_f32_16x16x32_bf16 v[56:59], v[156:159], v[164:167], v[56:59]
	v_mfma_f32_16x16x32_bf16 v[48:51], v[140:143], v[172:175], v[48:51]
	v_mfma_f32_16x16x32_bf16 v[40:43], v[156:159], v[172:175], v[40:43]
	v_mfma_f32_16x16x32_bf16 v[28:31], v[140:143], v[180:183], v[28:31]
	v_mfma_f32_16x16x32_bf16 v[24:27], v[156:159], v[180:183], v[24:27]
	v_mfma_f32_16x16x32_bf16 v[16:19], v[140:143], v[188:191], v[16:19]
	v_mfma_f32_16x16x32_bf16 v[8:11], v[156:159], v[188:191], v[8:11]
	v_mfma_f32_16x16x32_bf16 v[60:63], v[152:155], v[168:171], v[60:63]
	v_mfma_f32_16x16x32_bf16 v[56:59], v[160:163], v[168:171], v[56:59]
	v_mfma_f32_16x16x32_bf16 v[48:51], v[152:155], v[176:179], v[48:51]
	v_mfma_f32_16x16x32_bf16 v[40:43], v[160:163], v[176:179], v[40:43]
	v_mfma_f32_16x16x32_bf16 v[28:31], v[152:155], v[184:187], v[28:31]
	v_mfma_f32_16x16x32_bf16 v[24:27], v[160:163], v[184:187], v[24:27]
	v_mfma_f32_16x16x32_bf16 v[16:19], v[152:155], v[192:195], v[16:19]
	v_mfma_f32_16x16x32_bf16 v[8:11], v[160:163], v[192:195], v[8:11]
	v_mfma_f32_16x16x32_bf16 v[52:55], v[196:199], v[164:167], v[52:55]
	v_mfma_f32_16x16x32_bf16 v[44:47], v[204:207], v[164:167], v[44:47]
	v_mfma_f32_16x16x32_bf16 v[36:39], v[196:199], v[172:175], v[36:39]
	v_mfma_f32_16x16x32_bf16 v[32:35], v[204:207], v[172:175], v[32:35]
	v_mfma_f32_16x16x32_bf16 v[20:23], v[196:199], v[180:183], v[20:23]
	v_mfma_f32_16x16x32_bf16 v[12:15], v[204:207], v[180:183], v[12:15]
	v_mfma_f32_16x16x32_bf16 v[4:7], v[196:199], v[188:191], v[4:7]
	v_mfma_f32_16x16x32_bf16 v[0:3], v[204:207], v[188:191], v[0:3]
	v_mfma_f32_16x16x32_bf16 v[52:55], v[200:203], v[168:171], v[52:55]
	v_mfma_f32_16x16x32_bf16 v[44:47], v[208:211], v[168:171], v[44:47]
	v_mfma_f32_16x16x32_bf16 v[36:39], v[200:203], v[176:179], v[36:39]
	v_mfma_f32_16x16x32_bf16 v[32:35], v[208:211], v[176:179], v[32:35]
	v_mfma_f32_16x16x32_bf16 v[20:23], v[200:203], v[184:187], v[20:23]
	v_mfma_f32_16x16x32_bf16 v[12:15], v[208:211], v[184:187], v[12:15]
	v_mfma_f32_16x16x32_bf16 v[4:7], v[200:203], v[192:195], v[4:7]
	v_mfma_f32_16x16x32_bf16 v[0:3], v[208:211], v[192:195], v[0:3]
	s_setprio 0
	s_add_i32 s71, 0, 0x18000
	v_add_u32_e32 v160, s71, v147
	s_barrier
	ds_read_b128 v[140:143], v160
	ds_read_b128 v[152:155], v160 offset:1024
	ds_read_b128 v[156:159], v160 offset:2048
	ds_read_b128 v[160:163], v160 offset:3072
	s_add_u32 s38, s38, 0x40000
	s_addc_u32 s39, s39, 0
	s_mov_b32 m0, s31
	v_lshl_add_u64 v[196:197], s[38:39], 0, v[128:129]
	ds_read_b128 v[164:167], v150 offset:32768
	ds_read_b128 v[168:171], v150 offset:33792
	ds_read_b128 v[172:175], v150 offset:34816
	ds_read_b128 v[176:179], v150 offset:35840
	ds_read_b128 v[180:183], v150 offset:36864
	ds_read_b128 v[184:187], v150 offset:37888
	ds_read_b128 v[188:191], v150 offset:38912
	ds_read_b128 v[192:195], v150 offset:39936
	global_load_lds_dwordx4 v[196:197], off
	v_lshl_add_u64 v[196:197], s[38:39], 0, v[130:131]
	s_mov_b32 m0, s40
	s_nop 0
	global_load_lds_dwordx4 v[196:197], off
	s_add_i32 s38, 0, 0x1c000
	v_add_u32_e32 v208, s38, v147
	ds_read_b128 v[196:199], v208
	ds_read_b128 v[200:203], v208 offset:1024
	ds_read_b128 v[204:207], v208 offset:2048
	ds_read_b128 v[208:211], v208 offset:3072
	s_waitcnt lgkmcnt(0)
	s_barrier
	s_setprio 1
	v_mfma_f32_16x16x32_bf16 v[124:127], v[140:143], v[164:167], v[124:127]
	v_mfma_f32_16x16x32_bf16 v[120:123], v[156:159], v[164:167], v[120:123]
	v_mfma_f32_16x16x32_bf16 v[112:115], v[140:143], v[172:175], v[112:115]
	v_mfma_f32_16x16x32_bf16 v[104:107], v[156:159], v[172:175], v[104:107]
	v_mfma_f32_16x16x32_bf16 v[92:95], v[140:143], v[180:183], v[92:95]
	v_mfma_f32_16x16x32_bf16 v[88:91], v[156:159], v[180:183], v[88:91]
	v_mfma_f32_16x16x32_bf16 v[80:83], v[140:143], v[188:191], v[80:83]
	v_mfma_f32_16x16x32_bf16 v[72:75], v[156:159], v[188:191], v[72:75]
	v_mfma_f32_16x16x32_bf16 v[124:127], v[152:155], v[168:171], v[124:127]
	v_mfma_f32_16x16x32_bf16 v[120:123], v[160:163], v[168:171], v[120:123]
	v_mfma_f32_16x16x32_bf16 v[112:115], v[152:155], v[176:179], v[112:115]
	v_mfma_f32_16x16x32_bf16 v[104:107], v[160:163], v[176:179], v[104:107]
	v_mfma_f32_16x16x32_bf16 v[92:95], v[152:155], v[184:187], v[92:95]
	v_mfma_f32_16x16x32_bf16 v[88:91], v[160:163], v[184:187], v[88:91]
	v_mfma_f32_16x16x32_bf16 v[80:83], v[152:155], v[192:195], v[80:83]
	v_mfma_f32_16x16x32_bf16 v[72:75], v[160:163], v[192:195], v[72:75]
	v_mfma_f32_16x16x32_bf16 v[116:119], v[196:199], v[164:167], v[116:119]
	v_mfma_f32_16x16x32_bf16 v[108:111], v[204:207], v[164:167], v[108:111]
	v_mfma_f32_16x16x32_bf16 v[100:103], v[196:199], v[172:175], v[100:103]
	v_mfma_f32_16x16x32_bf16 v[96:99], v[204:207], v[172:175], v[96:99]
	v_mfma_f32_16x16x32_bf16 v[84:87], v[196:199], v[180:183], v[84:87]
	v_mfma_f32_16x16x32_bf16 v[76:79], v[204:207], v[180:183], v[76:79]
	v_mfma_f32_16x16x32_bf16 v[68:71], v[196:199], v[188:191], v[68:71]
	v_mfma_f32_16x16x32_bf16 v[64:67], v[204:207], v[188:191], v[64:67]
	v_mfma_f32_16x16x32_bf16 v[116:119], v[200:203], v[168:171], v[116:119]
	v_mfma_f32_16x16x32_bf16 v[108:111], v[208:211], v[168:171], v[108:111]
	v_mfma_f32_16x16x32_bf16 v[100:103], v[200:203], v[176:179], v[100:103]
	v_mfma_f32_16x16x32_bf16 v[96:99], v[208:211], v[176:179], v[96:99]
	v_mfma_f32_16x16x32_bf16 v[84:87], v[200:203], v[184:187], v[84:87]
	v_mfma_f32_16x16x32_bf16 v[76:79], v[208:211], v[184:187], v[76:79]
	v_mfma_f32_16x16x32_bf16 v[68:71], v[200:203], v[192:195], v[68:71]
	v_mfma_f32_16x16x32_bf16 v[64:67], v[208:211], v[192:195], v[64:67]
	s_setprio 0
	s_barrier
; #define PG8_STAGE(bufoff, gbase, voff) do { _Pragma("unroll") for (int _i = 0; _i < 2; ++_i) \
;         __builtin_amdgcn_global_load_lds((const unsigned*)((const char*)(gbase) + (voff)[_i]), (LAS unsigned*)(lds + (bufoff) + ldsw + _i * 8192), 16, 0, 0); } while (0)
; #define PG8_LDA(dst, b, h) do { _Pragma("unroll") for (int m = 0; m < 4; ++m) _Pragma("unroll") for (int k = 0; k < 2; ++k) dst[m][k] = *(const LAS bf16x8*)(lds + PG8_SA(b, h) + aoff + m * 2048 + k * 1024); } while (0)
; #define PG8_BAR __builtin_amdgcn_s_barrier()
; template <class Epi>
; __device__ __forceinline__ void gemm_phase(LAS unsigned char* lds, const Gemm g, const StaticOrder& S, const Epi& E) {
;     ...
;             PG8_LDB(B0, 1, 0); PG8_SCHED; PG8_LDA(At, 1, 0); PG8_STAGE(PG8_SA(0, 1), a2 + hstepA, voffA);
;             PG8_WAIT_L(8); PG8_BAR; PG8_WAIT_L(0); PG8_MMA(0, 0, At, B0); PG8_BAR; PG8_SCHED;
;             PG8_LDB(B1, 1, 1); PG8_STAGE(PG8_SB(1, 0), b3, voffB);
;             PG8_BAR; PG8_WAIT_L(0); PG8_MMA(0, 1, At, B1); PG8_BAR;
;             PG8_LDA(At, 1, 1); PG8_STAGE(PG8_SA(1, 0), a3, voffA);
;             PG8_BAR; PG8_WAIT_L(0); PG8_MMA(1, 0, At, B0); PG8_BAR; PG8_SCHED;
;             PG8_STAGE(PG8_SB(1, 1), b3 + hstepB, voffB);
;             PG8_WAIT_V(6); PG8_BAR; PG8_MMA(1, 1, At, B1); PG8_BAR;
;     __device__ __forceinline__ void operator()(AccRef acc, const Unit& u, int wr, int wc, int fr, int fq) const {
;         const int row0 = u.pm * 256 + wr * 64 + fr, col0 = u.pn * 256 + wc * 32 + 4 * fq;
;         f32x4 sv[2][2], bv[2][2];
; #pragma unroll
;         for (int bj = 0; bj < 2; ++bj)
; #pragma unroll
;             for (int n = 0; n < 2; ++n) {
;                 sv[bj][n] = scale ? *(const f32x4*)(scale + col0 + bj * 128 + n * 16) : (f32x4){1.f, 1.f, 1.f, 1.f};
;                 bv[bj][n] = bias ? *(const f32x4*)(bias + col0 + bj * 128 + n * 16) : (f32x4){0.f, 0.f, 0.f, 0.f}; }
; #pragma unroll
;         for (int ai = 0; ai < 2; ++ai)
; #pragma unroll
;             for (int mh = 0; mh < 2; ++mh) {
;                 f32x4 bs[2][2][2];
; #pragma unroll
;                 for (int m = 0; m < 2; ++m)
; #pragma unroll
;                     for (int bj = 0; bj < 2; ++bj)
; #pragma unroll
;                         for (int n = 0; n < 2; ++n) bs[m][bj][n] = *(const f32x4*)(base + (size_t)(row0 + ai * 128 + (2 * mh + m) * 16) * D + col0 + bj * 128 + n * 16);
	s_nop 1
	ds_read_b128 v[164:167], v150 offset:49152
	ds_read_b128 v[168:171], v150 offset:50176
	ds_read_b128 v[172:175], v150 offset:51200
	ds_read_b128 v[176:179], v150 offset:52224
	ds_read_b128 v[180:183], v150 offset:53248
	ds_read_b128 v[184:187], v150 offset:54272
	ds_read_b128 v[188:191], v150 offset:55296
	ds_read_b128 v[192:195], v150 offset:56320
	s_add_i32 s39, s71, s7
	v_lshl_add_u64 v[254:255], v[144:145], 0, s[12:13]
	s_mov_b32 m0, s39
	s_nop 0
	global_load_lds_dwordx4 v[254:255], off
	v_lshl_add_u64 v[254:255], v[212:213], 0, s[12:13]
	s_add_i32 m0, s39, 0x2000
	s_nop 0
	global_load_lds_dwordx4 v[254:255], off
	s_mov_b32 m0, s42
	v_lshl_add_u64 v[254:255], v[214:215], 0, s[12:13]
	global_load_lds_dwordx4 v[254:255], off
	v_lshl_add_u64 v[144:145], v[216:217], 0, s[12:13]
	s_mov_b32 m0, s43
	s_nop 0
	global_load_lds_dwordx4 v[144:145], off
	s_add_u32 s36, s36, 0x40080
	s_addc_u32 s37, s37, 0
	s_add_i32 s38, s38, s7
	v_lshl_add_u64 v[254:255], s[36:37], 0, v[128:129]
	s_mov_b32 m0, s38
	s_nop 0
	global_load_lds_dwordx4 v[254:255], off
	v_lshl_add_u64 v[254:255], s[36:37], 0, v[130:131]
	s_add_i32 m0, s38, 0x2000
	s_nop 0
	global_load_lds_dwordx4 v[254:255], off
	s_waitcnt vmcnt(6)
	s_waitcnt lgkmcnt(0)
	s_barrier
	s_setprio 1
	v_mfma_f32_16x16x32_bf16 v[60:63], v[140:143], v[164:167], v[60:63]
	v_mfma_f32_16x16x32_bf16 v[56:59], v[156:159], v[164:167], v[56:59]
	v_mfma_f32_16x16x32_bf16 v[48:51], v[140:143], v[172:175], v[48:51]
	v_mfma_f32_16x16x32_bf16 v[40:43], v[156:159], v[172:175], v[40:43]
	v_mfma_f32_16x16x32_bf16 v[28:31], v[140:143], v[180:183], v[28:31]
	v_mfma_f32_16x16x32_bf16 v[24:27], v[156:159], v[180:183], v[24:27]
	v_mfma_f32_16x16x32_bf16 v[16:19], v[140:143], v[188:191], v[16:19]
	v_mfma_f32_16x16x32_bf16 v[8:11], v[156:159], v[188:191], v[8:11]
	v_mfma_f32_16x16x32_bf16 v[60:63], v[152:155], v[168:171], v[60:63]
	v_mfma_f32_16x16x32_bf16 v[56:59], v[160:163], v[168:171], v[56:59]
	v_mfma_f32_16x16x32_bf16 v[48:51], v[152:155], v[176:179], v[48:51]
	v_mfma_f32_16x16x32_bf16 v[40:43], v[160:163], v[176:179], v[40:43]
	v_mfma_f32_16x16x32_bf16 v[28:31], v[152:155], v[184:187], v[28:31]
	v_mfma_f32_16x16x32_bf16 v[24:27], v[160:163], v[184:187], v[24:27]
	v_mfma_f32_16x16x32_bf16 v[16:19], v[152:155], v[192:195], v[16:19]
	v_mfma_f32_16x16x32_bf16 v[8:11], v[160:163], v[192:195], v[8:11]
	v_mfma_f32_16x16x32_bf16 v[52:55], v[196:199], v[164:167], v[52:55]
	v_mfma_f32_16x16x32_bf16 v[44:47], v[204:207], v[164:167], v[44:47]
	v_mfma_f32_16x16x32_bf16 v[36:39], v[196:199], v[172:175], v[36:39]
	v_mfma_f32_16x16x32_bf16 v[32:35], v[204:207], v[172:175], v[32:35]
	v_mfma_f32_16x16x32_bf16 v[20:23], v[196:199], v[180:183], v[20:23]
	v_mfma_f32_16x16x32_bf16 v[12:15], v[204:207], v[180:183], v[12:15]
	v_mfma_f32_16x16x32_bf16 v[4:7], v[196:199], v[188:191], v[4:7]
	v_mfma_f32_16x16x32_bf16 v[0:3], v[204:207], v[188:191], v[0:3]
	v_mfma_f32_16x16x32_bf16 v[52:55], v[200:203], v[168:171], v[52:55]
	v_mfma_f32_16x16x32_bf16 v[44:47], v[208:211], v[168:171], v[44:47]
	v_mfma_f32_16x16x32_bf16 v[36:39], v[200:203], v[176:179], v[36:39]
	v_mfma_f32_16x16x32_bf16 v[32:35], v[208:211], v[176:179], v[32:35]
	v_mfma_f32_16x16x32_bf16 v[20:23], v[200:203], v[184:187], v[20:23]
	v_mfma_f32_16x16x32_bf16 v[12:15], v[208:211], v[184:187], v[12:15]
	v_mfma_f32_16x16x32_bf16 v[4:7], v[200:203], v[192:195], v[4:7]
	v_mfma_f32_16x16x32_bf16 v[0:3], v[208:211], v[192:195], v[0:3]
	s_setprio 0
	s_add_i32 s70, s70, 2
	s_add_u32 s34, s34, 0x100
	s_addc_u32 s35, s35, 0
	s_add_u32 s49, s49, 0x100
	s_addc_u32 s63, s63, 0
	s_cmp_gt_u32 s70, 13
	s_barrier
	s_cbranch_scc0 .LBB0_1820
	v_lshl_or_b32 v144, s46, 8, v148
	v_lshl_add_u32 v145, s30, 8, v146
	v_lshlrev_b32_e32 v144, 2, v144
	v_lshl_add_u32 v145, v145, 12, v144
	v_add_u32_e32 v216, 0x10000, v145
	v_add_u32_e32 v217, 0x20000, v145
	v_add_u32_e32 v218, 0x30000, v145
	v_add_u32_e32 v232, 0x80000, v145
	v_add_u32_e32 v233, 0x90000, v145
	v_add_u32_e32 v235, 0xa0000, v145
	v_add_u32_e32 v253, 0xb0000, v145
	s_and_b64 vcc, exec, s[10:11]
	s_mov_b32 s46, s22
	s_mov_b32 s30, s24
	s_mov_b64 s[36:37], s[28:29]
	s_mov_b64 s[34:35], s[26:27]
	global_load_dwordx4 v[140:143], v145, s[52:53]
	global_load_dwordx4 v[152:155], v145, s[52:53] offset:64
	global_load_dwordx4 v[156:159], v145, s[52:53] offset:512
	global_load_dwordx4 v[160:163], v145, s[52:53] offset:576
	global_load_dwordx4 v[164:167], v216, s[52:53]
	global_load_dwordx4 v[168:171], v216, s[52:53] offset:64
	global_load_dwordx4 v[172:175], v216, s[52:53] offset:512
	global_load_dwordx4 v[176:179], v216, s[52:53] offset:576
	global_load_dwordx4 v[180:183], v217, s[52:53]
	global_load_dwordx4 v[184:187], v217, s[52:53] offset:64
	global_load_dwordx4 v[188:191], v217, s[52:53] offset:512
	global_load_dwordx4 v[192:195], v217, s[52:53] offset:576
	global_load_dwordx4 v[196:199], v218, s[52:53]
	global_load_dwordx4 v[200:203], v218, s[52:53] offset:64
	global_load_dwordx4 v[204:207], v218, s[52:53] offset:512
	global_load_dwordx4 v[208:211], v218, s[52:53] offset:576
	global_load_dwordx4 v[212:215], v232, s[52:53]
	global_load_dwordx4 v[220:223], v232, s[52:53] offset:64
	global_load_dwordx4 v[224:227], v232, s[52:53] offset:512
	global_load_dwordx4 v[228:231], v232, s[52:53] offset:576
	global_load_dwordx4 v[236:239], v233, s[52:53]
	global_load_dwordx4 v[240:243], v233, s[52:53] offset:64
	global_load_dwordx4 v[244:247], v233, s[52:53] offset:512
	global_load_dwordx4 v[248:251], v233, s[52:53] offset:576
	v_pk_add_f32 v[124:125], v[124:125], 0 op_sel_hi:[1,0]
	v_pk_add_f32 v[126:127], v[126:127], 0 op_sel_hi:[1,0]
;     __device__ __forceinline__ void operator()(AccRef acc, const Unit& u, int wr, int wc, int fr, int fq) const {
;     ...
;                         for (int n = 0; n < 2; ++n) bs[m][bj][n] = *(const f32x4*)(base + (size_t)(row0 + ai * 128 + (2 * mh + m) * 16) * D + col0 + bj * 128 + n * 16);
; #pragma unroll
;                 for (int m = 0; m < 2; ++m)
; #pragma unroll
;                     for (int bj = 0; bj < 2; ++bj)
; #pragma unroll
;                         for (int n = 0; n < 2; ++n) *(f32x4*)(out + (size_t)(row0 + ai * 128 + (2 * mh + m) * 16) * D + col0 + bj * 128 + n * 16) = bs[m][bj][n] + sv[bj][n] * (acc[ai][bj][2 * mh + m][n] + bv[bj][n]);
;                 asm volatile("" ::: "memory"); }
	v_pk_add_f32 v[120:121], v[120:121], 0 op_sel_hi:[1,0]
	v_pk_add_f32 v[122:123], v[122:123], 0 op_sel_hi:[1,0]
	v_pk_add_f32 v[116:117], v[116:117], 0 op_sel_hi:[1,0]
	v_pk_add_f32 v[118:119], v[118:119], 0 op_sel_hi:[1,0]
	v_pk_add_f32 v[108:109], v[108:109], 0 op_sel_hi:[1,0]
	v_pk_add_f32 v[110:111], v[110:111], 0 op_sel_hi:[1,0]
	v_pk_add_f32 v[112:113], v[112:113], 0 op_sel_hi:[1,0]
	v_pk_add_f32 v[114:115], v[114:115], 0 op_sel_hi:[1,0]
	v_pk_add_f32 v[104:105], v[104:105], 0 op_sel_hi:[1,0]
	v_pk_add_f32 v[106:107], v[106:107], 0 op_sel_hi:[1,0]
	v_pk_add_f32 v[100:101], v[100:101], 0 op_sel_hi:[1,0]
	v_pk_add_f32 v[102:103], v[102:103], 0 op_sel_hi:[1,0]
	v_pk_add_f32 v[96:97], v[96:97], 0 op_sel_hi:[1,0]
	v_pk_add_f32 v[98:99], v[98:99], 0 op_sel_hi:[1,0]
	v_pk_add_f32 v[92:93], v[92:93], 0 op_sel_hi:[1,0]
	v_pk_add_f32 v[94:95], v[94:95], 0 op_sel_hi:[1,0]
	v_pk_add_f32 v[88:89], v[88:89], 0 op_sel_hi:[1,0]
	v_pk_add_f32 v[90:91], v[90:91], 0 op_sel_hi:[1,0]
	v_pk_add_f32 v[84:85], v[84:85], 0 op_sel_hi:[1,0]
	v_pk_add_f32 v[86:87], v[86:87], 0 op_sel_hi:[1,0]
	v_pk_add_f32 v[76:77], v[76:77], 0 op_sel_hi:[1,0]
	v_pk_add_f32 v[78:79], v[78:79], 0 op_sel_hi:[1,0]
	v_pk_add_f32 v[80:81], v[80:81], 0 op_sel_hi:[1,0]
	v_pk_add_f32 v[82:83], v[82:83], 0 op_sel_hi:[1,0]
	v_pk_add_f32 v[72:73], v[72:73], 0 op_sel_hi:[1,0]
	v_pk_add_f32 v[74:75], v[74:75], 0 op_sel_hi:[1,0]
	v_pk_add_f32 v[68:69], v[68:69], 0 op_sel_hi:[1,0]
	v_pk_add_f32 v[70:71], v[70:71], 0 op_sel_hi:[1,0]
	v_pk_add_f32 v[64:65], v[64:65], 0 op_sel_hi:[1,0]
	v_pk_add_f32 v[66:67], v[66:67], 0 op_sel_hi:[1,0]
	v_pk_add_f32 v[60:61], v[60:61], 0 op_sel_hi:[1,0]
	v_pk_add_f32 v[62:63], v[62:63], 0 op_sel_hi:[1,0]
	v_pk_add_f32 v[56:57], v[56:57], 0 op_sel_hi:[1,0]
	v_pk_add_f32 v[58:59], v[58:59], 0 op_sel_hi:[1,0]
	v_pk_add_f32 v[52:53], v[52:53], 0 op_sel_hi:[1,0]
	v_pk_add_f32 v[54:55], v[54:55], 0 op_sel_hi:[1,0]
	v_pk_add_f32 v[44:45], v[44:45], 0 op_sel_hi:[1,0]
	v_pk_add_f32 v[46:47], v[46:47], 0 op_sel_hi:[1,0]
	v_pk_add_f32 v[48:49], v[48:49], 0 op_sel_hi:[1,0]
	v_pk_add_f32 v[50:51], v[50:51], 0 op_sel_hi:[1,0]
	v_pk_add_f32 v[40:41], v[40:41], 0 op_sel_hi:[1,0]
	v_pk_add_f32 v[42:43], v[42:43], 0 op_sel_hi:[1,0]
	v_pk_add_f32 v[36:37], v[36:37], 0 op_sel_hi:[1,0]
	v_pk_add_f32 v[38:39], v[38:39], 0 op_sel_hi:[1,0]
	v_pk_add_f32 v[32:33], v[32:33], 0 op_sel_hi:[1,0]
	v_pk_add_f32 v[34:35], v[34:35], 0 op_sel_hi:[1,0]
	v_pk_add_f32 v[28:29], v[28:29], 0 op_sel_hi:[1,0]
	v_pk_add_f32 v[30:31], v[30:31], 0 op_sel_hi:[1,0]
	v_pk_add_f32 v[24:25], v[24:25], 0 op_sel_hi:[1,0]
	v_pk_add_f32 v[26:27], v[26:27], 0 op_sel_hi:[1,0]
	v_pk_add_f32 v[20:21], v[20:21], 0 op_sel_hi:[1,0]
	v_pk_add_f32 v[22:23], v[22:23], 0 op_sel_hi:[1,0]
	v_pk_add_f32 v[12:13], v[12:13], 0 op_sel_hi:[1,0]
	v_pk_add_f32 v[14:15], v[14:15], 0 op_sel_hi:[1,0]
	v_pk_add_f32 v[16:17], v[16:17], 0 op_sel_hi:[1,0]
	v_pk_add_f32 v[18:19], v[18:19], 0 op_sel_hi:[1,0]
	v_pk_add_f32 v[8:9], v[8:9], 0 op_sel_hi:[1,0]
	v_pk_add_f32 v[10:11], v[10:11], 0 op_sel_hi:[1,0]
	v_pk_add_f32 v[4:5], v[4:5], 0 op_sel_hi:[1,0]
	v_pk_add_f32 v[6:7], v[6:7], 0 op_sel_hi:[1,0]
	v_pk_add_f32 v[0:1], v[0:1], 0 op_sel_hi:[1,0]
	v_pk_add_f32 v[2:3], v[2:3], 0 op_sel_hi:[1,0]
	s_waitcnt vmcnt(16)
	v_pk_add_f32 v[124:125], v[124:125], v[140:141]
	v_pk_add_f32 v[126:127], v[126:127], v[142:143]
	v_pk_add_f32 v[120:121], v[120:121], v[152:153]
	v_pk_add_f32 v[122:123], v[122:123], v[154:155]
	v_pk_add_f32 v[116:117], v[116:117], v[156:157]
	v_pk_add_f32 v[118:119], v[118:119], v[158:159]
	v_pk_add_f32 v[108:109], v[108:109], v[160:161]
	v_pk_add_f32 v[110:111], v[110:111], v[162:163]
	v_pk_add_f32 v[112:113], v[112:113], v[164:165]
	v_pk_add_f32 v[114:115], v[114:115], v[166:167]
	v_pk_add_f32 v[104:105], v[104:105], v[168:169]
	v_pk_add_f32 v[106:107], v[106:107], v[170:171]
	v_pk_add_f32 v[100:101], v[100:101], v[172:173]
	v_pk_add_f32 v[102:103], v[102:103], v[174:175]
	v_pk_add_f32 v[96:97], v[96:97], v[176:177]
	v_pk_add_f32 v[98:99], v[98:99], v[178:179]
	global_store_dwordx4 v145, v[124:127], s[52:53]
	global_store_dwordx4 v145, v[120:123], s[52:53] offset:64
	global_store_dwordx4 v145, v[116:119], s[52:53] offset:512
	global_store_dwordx4 v145, v[108:111], s[52:53] offset:576
	global_store_dwordx4 v216, v[112:115], s[52:53]
	global_store_dwordx4 v216, v[104:107], s[52:53] offset:64
	global_store_dwordx4 v216, v[100:103], s[52:53] offset:512
	global_store_dwordx4 v216, v[96:99], s[52:53] offset:576
	global_load_dwordx4 v[140:143], v235, s[52:53]
	global_load_dwordx4 v[152:155], v235, s[52:53] offset:64
	global_load_dwordx4 v[156:159], v235, s[52:53] offset:512
	global_load_dwordx4 v[160:163], v235, s[52:53] offset:576
	global_load_dwordx4 v[164:167], v253, s[52:53]
	global_load_dwordx4 v[168:171], v253, s[52:53] offset:64
	global_load_dwordx4 v[172:175], v253, s[52:53] offset:512
	global_load_dwordx4 v[176:179], v253, s[52:53] offset:576
	s_waitcnt vmcnt(24)
;     __device__ __forceinline__ void operator()(AccRef acc, const Unit& u, int wr, int wc, int fr, int fq) const {
;     ...
;                         for (int n = 0; n < 2; ++n) bs[m][bj][n] = *(const f32x4*)(base + (size_t)(row0 + ai * 128 + (2 * mh + m) * 16) * D + col0 + bj * 128 + n * 16);
; #pragma unroll
;                 for (int m = 0; m < 2; ++m)
; #pragma unroll
;                     for (int bj = 0; bj < 2; ++bj)
; #pragma unroll
;                         for (int n = 0; n < 2; ++n) *(f32x4*)(out + (size_t)(row0 + ai * 128 + (2 * mh + m) * 16) * D + col0 + bj * 128 + n * 16) = bs[m][bj][n] + sv[bj][n] * (acc[ai][bj][2 * mh + m][n] + bv[bj][n]);
;                 asm volatile("" ::: "memory"); }
	v_pk_add_f32 v[92:93], v[92:93], v[180:181]
	v_pk_add_f32 v[94:95], v[94:95], v[182:183]
	v_pk_add_f32 v[88:89], v[88:89], v[184:185]
	v_pk_add_f32 v[90:91], v[90:91], v[186:187]
	v_pk_add_f32 v[84:85], v[84:85], v[188:189]
	v_pk_add_f32 v[86:87], v[86:87], v[190:191]
	v_pk_add_f32 v[76:77], v[76:77], v[192:193]
	v_pk_add_f32 v[78:79], v[78:79], v[194:195]
	v_pk_add_f32 v[80:81], v[80:81], v[196:197]
	v_pk_add_f32 v[82:83], v[82:83], v[198:199]
	v_pk_add_f32 v[72:73], v[72:73], v[200:201]
	v_pk_add_f32 v[74:75], v[74:75], v[202:203]
	v_pk_add_f32 v[68:69], v[68:69], v[204:205]
	v_pk_add_f32 v[70:71], v[70:71], v[206:207]
	v_pk_add_f32 v[64:65], v[64:65], v[208:209]
	v_pk_add_f32 v[66:67], v[66:67], v[210:211]
	global_store_dwordx4 v217, v[92:95], s[52:53]
	global_store_dwordx4 v217, v[88:91], s[52:53] offset:64
	global_store_dwordx4 v217, v[84:87], s[52:53] offset:512
	global_store_dwordx4 v217, v[76:79], s[52:53] offset:576
	global_store_dwordx4 v218, v[80:83], s[52:53]
	global_store_dwordx4 v218, v[72:75], s[52:53] offset:64
	global_store_dwordx4 v218, v[68:71], s[52:53] offset:512
	global_store_dwordx4 v218, v[64:67], s[52:53] offset:576
	s_waitcnt vmcnt(24)
	v_pk_add_f32 v[60:61], v[60:61], v[212:213]
	v_pk_add_f32 v[62:63], v[62:63], v[214:215]
	v_pk_add_f32 v[56:57], v[56:57], v[220:221]
	v_pk_add_f32 v[58:59], v[58:59], v[222:223]
	v_pk_add_f32 v[52:53], v[52:53], v[224:225]
	v_pk_add_f32 v[54:55], v[54:55], v[226:227]
	v_pk_add_f32 v[44:45], v[44:45], v[228:229]
	v_pk_add_f32 v[46:47], v[46:47], v[230:231]
	v_pk_add_f32 v[48:49], v[48:49], v[236:237]
	v_pk_add_f32 v[50:51], v[50:51], v[238:239]
	v_pk_add_f32 v[40:41], v[40:41], v[240:241]
	v_pk_add_f32 v[42:43], v[42:43], v[242:243]
	v_pk_add_f32 v[36:37], v[36:37], v[244:245]
	v_pk_add_f32 v[38:39], v[38:39], v[246:247]
	v_pk_add_f32 v[32:33], v[32:33], v[248:249]
	v_pk_add_f32 v[34:35], v[34:35], v[250:251]
	global_store_dwordx4 v232, v[60:63], s[52:53]
	global_store_dwordx4 v232, v[56:59], s[52:53] offset:64
	global_store_dwordx4 v232, v[52:55], s[52:53] offset:512
	global_store_dwordx4 v232, v[44:47], s[52:53] offset:576
	global_store_dwordx4 v233, v[48:51], s[52:53]
	global_store_dwordx4 v233, v[40:43], s[52:53] offset:64
	global_store_dwordx4 v233, v[36:39], s[52:53] offset:512
	global_store_dwordx4 v233, v[32:35], s[52:53] offset:576
	s_waitcnt vmcnt(16)
	v_pk_add_f32 v[28:29], v[28:29], v[140:141]
	v_pk_add_f32 v[30:31], v[30:31], v[142:143]
	v_pk_add_f32 v[24:25], v[24:25], v[152:153]
	v_pk_add_f32 v[26:27], v[26:27], v[154:155]
	v_pk_add_f32 v[20:21], v[20:21], v[156:157]
	v_pk_add_f32 v[22:23], v[22:23], v[158:159]
	v_pk_add_f32 v[12:13], v[12:13], v[160:161]
	v_pk_add_f32 v[14:15], v[14:15], v[162:163]
	v_pk_add_f32 v[16:17], v[16:17], v[164:165]
	v_pk_add_f32 v[18:19], v[18:19], v[166:167]
	v_pk_add_f32 v[8:9], v[8:9], v[168:169]
	v_pk_add_f32 v[10:11], v[10:11], v[170:171]
	v_pk_add_f32 v[4:5], v[4:5], v[172:173]
	v_pk_add_f32 v[6:7], v[6:7], v[174:175]
	v_pk_add_f32 v[0:1], v[0:1], v[176:177]
	v_pk_add_f32 v[2:3], v[2:3], v[178:179]
	global_store_dwordx4 v235, v[28:31], s[52:53]
	global_store_dwordx4 v235, v[24:27], s[52:53] offset:64
	global_store_dwordx4 v235, v[20:23], s[52:53] offset:512
	global_store_dwordx4 v235, v[12:15], s[52:53] offset:576
	global_store_dwordx4 v253, v[16:19], s[52:53]
	global_store_dwordx4 v253, v[8:11], s[52:53] offset:64
	global_store_dwordx4 v253, v[4:7], s[52:53] offset:512
	global_store_dwordx4 v253, v[0:3], s[52:53] offset:576
	s_cbranch_vccz .LBB0_1813
	s_waitcnt vmcnt(0)
	s_cmpk_gt_u32 s4, 0xff
	s_cbranch_scc1 .LBB0_1824
	s_barrier

; #define PG8_STAGE(bufoff, gbase, voff) do { _Pragma("unroll") for (int _i = 0; _i < 2; ++_i) \
;         __builtin_amdgcn_global_load_lds((const unsigned*)((const char*)(gbase) + (voff)[_i]), (LAS unsigned*)(lds + (bufoff) + ldsw + _i * 8192), 16, 0, 0); } while (0)
; #define PG8_LDA(dst, b, h) do { _Pragma("unroll") for (int m = 0; m < 4; ++m) _Pragma("unroll") for (int k = 0; k < 2; ++k) dst[m][k] = *(const LAS bf16x8*)(lds + PG8_SA(b, h) + aoff + m * 2048 + k * 1024); } while (0)
; #define PG8_LDB(dst, b, h) do { _Pragma("unroll") for (int n = 0; n < 2; ++n) _Pragma("unroll") for (int k = 0; k < 2; ++k) dst[n][k] = *(const LAS bf16x8*)(lds + PG8_SB(b, h) + boff + n * 2048 + k * 1024); } while (0)
; #define PG8_MMA(ai, bj, At, Bt) do { __builtin_amdgcn_s_setprio(1); _Pragma("unroll") for (int m = 0; m < 4; ++m) _Pragma("unroll") for (int n = 0; n < 2; ++n) _Pragma("unroll") for (int k = 0; k < 2; ++k) \
;         acc[ai][bj][m][n] = __builtin_amdgcn_mfma_f32_16x16x32_bf16(Bt[n][k], At[m][k], acc[ai][bj][m][n], 0, 0, 0); __builtin_amdgcn_s_setprio(0); } while (0)
; #define PG8_WAIT_V(n) asm volatile("s_waitcnt vmcnt(" #n ")" ::: "memory")
; #define PG8_WAIT_L(n) asm volatile("s_waitcnt lgkmcnt(" #n ")" ::: "memory")
; template <class Epi>
; __device__ __forceinline__ void gemm_phase(LAS unsigned char* lds, const Gemm g, const StaticOrder& S, const Epi& E) {
;     ...
;         for (int t = 0; t < nt; t += 2) {
;             const bool last = (t == nt - 2);
;             const char* a1 = cA + (size_t)(t + 1) * kstep;
;             const char* a2 = last ? nA : cA + (size_t)(t + 2) * kstep; const char* b2 = last ? nB : cB + (size_t)(t + 2) * kstep;
;             const char* a3 = a2 + kstep; const char* b3 = b2 + kstep;
;             PG8_LDB(B0, 0, 0); PG8_SCHED; PG8_LDA(At, 0, 0); PG8_STAGE(PG8_SA(1, 1), a1 + hstepA, voffA);
;             PG8_WAIT_L(8); PG8_BAR; PG8_WAIT_L(0); PG8_MMA(0, 0, At, B0); PG8_BAR; PG8_SCHED;
;             PG8_LDB(B1, 0, 1); PG8_STAGE(PG8_SB(0, 0), b2, voffB);
;             PG8_BAR; PG8_WAIT_L(0); PG8_MMA(0, 1, At, B1); PG8_BAR;
;             PG8_LDA(At, 0, 1); PG8_STAGE(PG8_SA(0, 0), a2, voffA);
;             PG8_BAR; PG8_WAIT_L(0); PG8_MMA(1, 0, At, B0); PG8_BAR; PG8_SCHED;
;             PG8_STAGE(PG8_SB(0, 1), b2 + hstepB, voffB);
;             PG8_WAIT_V(6); PG8_BAR; PG8_MMA(1, 1, At, B1); PG8_BAR;
.LBB0_2042:
	ds_read_b128 v[140:143], v149
	ds_read_b128 v[152:155], v149 offset:1024
	ds_read_b128 v[156:159], v149 offset:2048
	ds_read_b128 v[160:163], v149 offset:3072
	s_add_u32 s20, s18, 0x100
	s_addc_u32 s21, s19, 0
	s_cmp_eq_u32 s46, 40
	s_cselect_b32 s25, s5, s21
	s_cselect_b32 s24, s4, s20
	s_cselect_b32 s23, s7, s45
	s_cselect_b32 s22, s6, s44
	v_lshl_add_u64 v[144:145], s[18:19], 0, v[132:133]
	s_add_i32 m0, s30, 0xc000
	ds_read_b128 v[164:167], v150
	ds_read_b128 v[168:171], v150 offset:1024
	ds_read_b128 v[172:175], v150 offset:2048
	ds_read_b128 v[176:179], v150 offset:3072
	ds_read_b128 v[180:183], v150 offset:4096
	ds_read_b128 v[184:187], v150 offset:5120
	ds_read_b128 v[188:191], v150 offset:6144
	ds_read_b128 v[192:195], v150 offset:7168
	global_load_lds_dwordx4 v[144:145], off
	v_lshl_add_u64 v[144:145], s[18:19], 0, v[134:135]
	s_add_i32 m0, s30, 0xe000
	s_nop 0
	global_load_lds_dwordx4 v[144:145], off
	ds_read_b128 v[196:199], v151
	ds_read_b128 v[200:203], v151 offset:1024
	ds_read_b128 v[204:207], v151 offset:2048
	ds_read_b128 v[208:211], v151 offset:3072
	s_waitcnt lgkmcnt(0)
	s_barrier
	s_setprio 1
	v_mfma_f32_16x16x32_bf16 v[124:127], v[140:143], v[164:167], v[124:127]
	v_mfma_f32_16x16x32_bf16 v[120:123], v[156:159], v[164:167], v[120:123]
	v_mfma_f32_16x16x32_bf16 v[112:115], v[140:143], v[172:175], v[112:115]
	v_mfma_f32_16x16x32_bf16 v[104:107], v[156:159], v[172:175], v[104:107]
	v_mfma_f32_16x16x32_bf16 v[92:95], v[140:143], v[180:183], v[92:95]
	v_mfma_f32_16x16x32_bf16 v[88:91], v[156:159], v[180:183], v[88:91]
	v_mfma_f32_16x16x32_bf16 v[80:83], v[140:143], v[188:191], v[80:83]
	v_mfma_f32_16x16x32_bf16 v[72:75], v[156:159], v[188:191], v[72:75]
	v_mfma_f32_16x16x32_bf16 v[124:127], v[152:155], v[168:171], v[124:127]
	v_mfma_f32_16x16x32_bf16 v[120:123], v[160:163], v[168:171], v[120:123]
	v_mfma_f32_16x16x32_bf16 v[112:115], v[152:155], v[176:179], v[112:115]
	v_mfma_f32_16x16x32_bf16 v[104:107], v[160:163], v[176:179], v[104:107]
	v_mfma_f32_16x16x32_bf16 v[92:95], v[152:155], v[184:187], v[92:95]
	v_mfma_f32_16x16x32_bf16 v[88:91], v[160:163], v[184:187], v[88:91]
	v_mfma_f32_16x16x32_bf16 v[80:83], v[152:155], v[192:195], v[80:83]
	v_mfma_f32_16x16x32_bf16 v[72:75], v[160:163], v[192:195], v[72:75]
	v_mfma_f32_16x16x32_bf16 v[116:119], v[196:199], v[164:167], v[116:119]
	v_mfma_f32_16x16x32_bf16 v[108:111], v[204:207], v[164:167], v[108:111]
	v_mfma_f32_16x16x32_bf16 v[100:103], v[196:199], v[172:175], v[100:103]
	v_mfma_f32_16x16x32_bf16 v[96:99], v[204:207], v[172:175], v[96:99]
	v_mfma_f32_16x16x32_bf16 v[84:87], v[196:199], v[180:183], v[84:87]
	v_mfma_f32_16x16x32_bf16 v[76:79], v[204:207], v[180:183], v[76:79]
	v_mfma_f32_16x16x32_bf16 v[68:71], v[196:199], v[188:191], v[68:71]
	v_mfma_f32_16x16x32_bf16 v[64:67], v[204:207], v[188:191], v[64:67]
	v_mfma_f32_16x16x32_bf16 v[116:119], v[200:203], v[168:171], v[116:119]
	v_mfma_f32_16x16x32_bf16 v[108:111], v[208:211], v[168:171], v[108:111]
	v_mfma_f32_16x16x32_bf16 v[100:103], v[200:203], v[176:179], v[100:103]
	v_mfma_f32_16x16x32_bf16 v[96:99], v[208:211], v[176:179], v[96:99]
	v_mfma_f32_16x16x32_bf16 v[84:87], v[200:203], v[184:187], v[84:87]
	v_mfma_f32_16x16x32_bf16 v[76:79], v[208:211], v[184:187], v[76:79]
	v_mfma_f32_16x16x32_bf16 v[68:71], v[200:203], v[192:195], v[68:71]
	v_mfma_f32_16x16x32_bf16 v[64:67], v[208:211], v[192:195], v[64:67]
	s_setprio 0
	s_barrier
	s_nop 1
	ds_read_b128 v[164:167], v150 offset:16384
	ds_read_b128 v[168:171], v150 offset:17408
	ds_read_b128 v[172:175], v150 offset:18432
	ds_read_b128 v[176:179], v150 offset:19456
	ds_read_b128 v[180:183], v150 offset:20480
	ds_read_b128 v[184:187], v150 offset:21504
	ds_read_b128 v[188:191], v150 offset:22528
	ds_read_b128 v[192:195], v150 offset:23552
	s_add_i32 s18, s38, s29
	v_lshl_add_u64 v[144:145], s[22:23], 0, v[128:129]
	s_mov_b32 m0, s18
	s_nop 0
	global_load_lds_dwordx4 v[144:145], off
	v_lshl_add_u64 v[212:213], s[22:23], 0, v[130:131]
	s_add_i32 m0, s18, 0x2000
	s_nop 0
	global_load_lds_dwordx4 v[212:213], off
	s_mov_b32 m0, s30
	v_lshl_add_u64 v[214:215], s[24:25], 0, v[128:129]
	global_load_lds_dwordx4 v[214:215], off
	v_lshl_add_u64 v[216:217], s[24:25], 0, v[130:131]
	s_mov_b32 m0, s31
	s_nop 0
	global_load_lds_dwordx4 v[216:217], off
	s_add_u32 s18, s22, 0xb0000
	s_addc_u32 s19, s23, 0
	s_add_i32 s47, s39, s29
	v_lshl_add_u64 v[254:255], s[18:19], 0, v[128:129]
	s_mov_b32 m0, s47
	s_nop 0
	global_load_lds_dwordx4 v[254:255], off
	v_lshl_add_u64 v[254:255], s[18:19], 0, v[130:131]
	s_add_i32 m0, s47, 0x2000
	s_nop 0
	global_load_lds_dwordx4 v[254:255], off
	s_waitcnt vmcnt(6)
	s_waitcnt lgkmcnt(0)
	s_barrier
; #define PG8_STAGE(bufoff, gbase, voff) do { _Pragma("unroll") for (int _i = 0; _i < 2; ++_i) \
;         __builtin_amdgcn_global_load_lds((const unsigned*)((const char*)(gbase) + (voff)[_i]), (LAS unsigned*)(lds + (bufoff) + ldsw + _i * 8192), 16, 0, 0); } while (0)
; #define PG8_LDA(dst, b, h) do { _Pragma("unroll") for (int m = 0; m < 4; ++m) _Pragma("unroll") for (int k = 0; k < 2; ++k) dst[m][k] = *(const LAS bf16x8*)(lds + PG8_SA(b, h) + aoff + m * 2048 + k * 1024); } while (0)
; #define PG8_LDB(dst, b, h) do { _Pragma("unroll") for (int n = 0; n < 2; ++n) _Pragma("unroll") for (int k = 0; k < 2; ++k) dst[n][k] = *(const LAS bf16x8*)(lds + PG8_SB(b, h) + boff + n * 2048 + k * 1024); } while (0)
; #define PG8_MMA(ai, bj, At, Bt) do { __builtin_amdgcn_s_setprio(1); _Pragma("unroll") for (int m = 0; m < 4; ++m) _Pragma("unroll") for (int n = 0; n < 2; ++n) _Pragma("unroll") for (int k = 0; k < 2; ++k) \
;         acc[ai][bj][m][n] = __builtin_amdgcn_mfma_f32_16x16x32_bf16(Bt[n][k], At[m][k], acc[ai][bj][m][n], 0, 0, 0); __builtin_amdgcn_s_setprio(0); } while (0)
; #define PG8_WAIT_V(n) asm volatile("s_waitcnt vmcnt(" #n ")" ::: "memory")
; #define PG8_WAIT_L(n) asm volatile("s_waitcnt lgkmcnt(" #n ")" ::: "memory")
; #define PG8_BAR __builtin_amdgcn_s_barrier()
; #define PG8_SCHED __builtin_amdgcn_sched_barrier(0)
; template <class Epi>
; __device__ __forceinline__ void gemm_phase(LAS unsigned char* lds, const Gemm g, const StaticOrder& S, const Epi& E) {
;     ...
;             PG8_WAIT_L(8); PG8_BAR; PG8_WAIT_L(0); PG8_MMA(0, 0, At, B0); PG8_BAR; PG8_SCHED;
;             PG8_LDB(B1, 0, 1); PG8_STAGE(PG8_SB(0, 0), b2, voffB);
;             PG8_BAR; PG8_WAIT_L(0); PG8_MMA(0, 1, At, B1); PG8_BAR;
;             PG8_LDA(At, 0, 1); PG8_STAGE(PG8_SA(0, 0), a2, voffA);
;             PG8_BAR; PG8_WAIT_L(0); PG8_MMA(1, 0, At, B0); PG8_BAR; PG8_SCHED;
;             PG8_STAGE(PG8_SB(0, 1), b2 + hstepB, voffB);
;             PG8_WAIT_V(6); PG8_BAR; PG8_MMA(1, 1, At, B1); PG8_BAR;
;             PG8_LDB(B0, 1, 0); PG8_SCHED; PG8_LDA(At, 1, 0); PG8_STAGE(PG8_SA(0, 1), a2 + hstepA, voffA);
;             PG8_WAIT_L(8); PG8_BAR; PG8_WAIT_L(0); PG8_MMA(0, 0, At, B0); PG8_BAR; PG8_SCHED;
;             PG8_LDB(B1, 1, 1); PG8_STAGE(PG8_SB(1, 0), b3, voffB);
;             PG8_BAR; PG8_WAIT_L(0); PG8_MMA(0, 1, At, B1); PG8_BAR;
	s_setprio 1
	v_mfma_f32_16x16x32_bf16 v[60:63], v[140:143], v[164:167], v[60:63]
	v_mfma_f32_16x16x32_bf16 v[56:59], v[156:159], v[164:167], v[56:59]
	v_mfma_f32_16x16x32_bf16 v[48:51], v[140:143], v[172:175], v[48:51]
	v_mfma_f32_16x16x32_bf16 v[40:43], v[156:159], v[172:175], v[40:43]
	v_mfma_f32_16x16x32_bf16 v[28:31], v[140:143], v[180:183], v[28:31]
	v_mfma_f32_16x16x32_bf16 v[24:27], v[156:159], v[180:183], v[24:27]
	v_mfma_f32_16x16x32_bf16 v[16:19], v[140:143], v[188:191], v[16:19]
	v_mfma_f32_16x16x32_bf16 v[8:11], v[156:159], v[188:191], v[8:11]
	v_mfma_f32_16x16x32_bf16 v[60:63], v[152:155], v[168:171], v[60:63]
	v_mfma_f32_16x16x32_bf16 v[56:59], v[160:163], v[168:171], v[56:59]
	v_mfma_f32_16x16x32_bf16 v[48:51], v[152:155], v[176:179], v[48:51]
	v_mfma_f32_16x16x32_bf16 v[40:43], v[160:163], v[176:179], v[40:43]
	v_mfma_f32_16x16x32_bf16 v[28:31], v[152:155], v[184:187], v[28:31]
	v_mfma_f32_16x16x32_bf16 v[24:27], v[160:163], v[184:187], v[24:27]
	v_mfma_f32_16x16x32_bf16 v[16:19], v[152:155], v[192:195], v[16:19]
	v_mfma_f32_16x16x32_bf16 v[8:11], v[160:163], v[192:195], v[8:11]
	v_mfma_f32_16x16x32_bf16 v[52:55], v[196:199], v[164:167], v[52:55]
	v_mfma_f32_16x16x32_bf16 v[44:47], v[204:207], v[164:167], v[44:47]
	v_mfma_f32_16x16x32_bf16 v[36:39], v[196:199], v[172:175], v[36:39]
	v_mfma_f32_16x16x32_bf16 v[32:35], v[204:207], v[172:175], v[32:35]
	v_mfma_f32_16x16x32_bf16 v[20:23], v[196:199], v[180:183], v[20:23]
	v_mfma_f32_16x16x32_bf16 v[12:15], v[204:207], v[180:183], v[12:15]
	v_mfma_f32_16x16x32_bf16 v[4:7], v[196:199], v[188:191], v[4:7]
	v_mfma_f32_16x16x32_bf16 v[0:3], v[204:207], v[188:191], v[0:3]
	v_mfma_f32_16x16x32_bf16 v[52:55], v[200:203], v[168:171], v[52:55]
	v_mfma_f32_16x16x32_bf16 v[44:47], v[208:211], v[168:171], v[44:47]
	v_mfma_f32_16x16x32_bf16 v[36:39], v[200:203], v[176:179], v[36:39]
	v_mfma_f32_16x16x32_bf16 v[32:35], v[208:211], v[176:179], v[32:35]
	v_mfma_f32_16x16x32_bf16 v[20:23], v[200:203], v[184:187], v[20:23]
	v_mfma_f32_16x16x32_bf16 v[12:15], v[208:211], v[184:187], v[12:15]
	v_mfma_f32_16x16x32_bf16 v[4:7], v[200:203], v[192:195], v[4:7]
	v_mfma_f32_16x16x32_bf16 v[0:3], v[208:211], v[192:195], v[0:3]
	s_setprio 0
	s_add_i32 s47, 0, 0x18000
	v_add_u32_e32 v160, s47, v147
	s_barrier
	ds_read_b128 v[140:143], v160
	ds_read_b128 v[152:155], v160 offset:1024
	ds_read_b128 v[156:159], v160 offset:2048
	ds_read_b128 v[160:163], v160 offset:3072
	s_add_u32 s18, s24, 0xb0000
	s_addc_u32 s19, s25, 0
	s_mov_b32 m0, s33
	v_lshl_add_u64 v[196:197], s[18:19], 0, v[128:129]
	ds_read_b128 v[164:167], v150 offset:32768
	ds_read_b128 v[168:171], v150 offset:33792
	ds_read_b128 v[172:175], v150 offset:34816
	ds_read_b128 v[176:179], v150 offset:35840
	ds_read_b128 v[180:183], v150 offset:36864
	ds_read_b128 v[184:187], v150 offset:37888
	ds_read_b128 v[188:191], v150 offset:38912
	ds_read_b128 v[192:195], v150 offset:39936
	global_load_lds_dwordx4 v[196:197], off
	v_lshl_add_u64 v[196:197], s[18:19], 0, v[130:131]
	s_mov_b32 m0, s34
	s_nop 0
	global_load_lds_dwordx4 v[196:197], off
	s_add_i32 s24, 0, 0x1c000
	v_add_u32_e32 v208, s24, v147
	ds_read_b128 v[196:199], v208
	ds_read_b128 v[200:203], v208 offset:1024
	ds_read_b128 v[204:207], v208 offset:2048
	ds_read_b128 v[208:211], v208 offset:3072
	s_waitcnt lgkmcnt(0)
	s_barrier
	s_setprio 1
	v_mfma_f32_16x16x32_bf16 v[124:127], v[140:143], v[164:167], v[124:127]
	v_mfma_f32_16x16x32_bf16 v[120:123], v[156:159], v[164:167], v[120:123]
	v_mfma_f32_16x16x32_bf16 v[112:115], v[140:143], v[172:175], v[112:115]
	v_mfma_f32_16x16x32_bf16 v[104:107], v[156:159], v[172:175], v[104:107]
	v_mfma_f32_16x16x32_bf16 v[92:95], v[140:143], v[180:183], v[92:95]
	v_mfma_f32_16x16x32_bf16 v[88:91], v[156:159], v[180:183], v[88:91]
	v_mfma_f32_16x16x32_bf16 v[80:83], v[140:143], v[188:191], v[80:83]
	v_mfma_f32_16x16x32_bf16 v[72:75], v[156:159], v[188:191], v[72:75]
	v_mfma_f32_16x16x32_bf16 v[124:127], v[152:155], v[168:171], v[124:127]
	v_mfma_f32_16x16x32_bf16 v[120:123], v[160:163], v[168:171], v[120:123]
	v_mfma_f32_16x16x32_bf16 v[112:115], v[152:155], v[176:179], v[112:115]
	v_mfma_f32_16x16x32_bf16 v[104:107], v[160:163], v[176:179], v[104:107]
	v_mfma_f32_16x16x32_bf16 v[92:95], v[152:155], v[184:187], v[92:95]
	v_mfma_f32_16x16x32_bf16 v[88:91], v[160:163], v[184:187], v[88:91]
	v_mfma_f32_16x16x32_bf16 v[80:83], v[152:155], v[192:195], v[80:83]
	v_mfma_f32_16x16x32_bf16 v[72:75], v[160:163], v[192:195], v[72:75]
	v_mfma_f32_16x16x32_bf16 v[116:119], v[196:199], v[164:167], v[116:119]
	v_mfma_f32_16x16x32_bf16 v[108:111], v[204:207], v[164:167], v[108:111]
	v_mfma_f32_16x16x32_bf16 v[100:103], v[196:199], v[172:175], v[100:103]
	v_mfma_f32_16x16x32_bf16 v[96:99], v[204:207], v[172:175], v[96:99]
	v_mfma_f32_16x16x32_bf16 v[84:87], v[196:199], v[180:183], v[84:87]
	v_mfma_f32_16x16x32_bf16 v[76:79], v[204:207], v[180:183], v[76:79]
	v_mfma_f32_16x16x32_bf16 v[68:71], v[196:199], v[188:191], v[68:71]
	v_mfma_f32_16x16x32_bf16 v[64:67], v[204:207], v[188:191], v[64:67]
	v_mfma_f32_16x16x32_bf16 v[116:119], v[200:203], v[168:171], v[116:119]
	v_mfma_f32_16x16x32_bf16 v[108:111], v[208:211], v[168:171], v[108:111]
	v_mfma_f32_16x16x32_bf16 v[100:103], v[200:203], v[176:179], v[100:103]
	v_mfma_f32_16x16x32_bf16 v[96:99], v[208:211], v[176:179], v[96:99]
	v_mfma_f32_16x16x32_bf16 v[84:87], v[200:203], v[184:187], v[84:87]
	v_mfma_f32_16x16x32_bf16 v[76:79], v[208:211], v[184:187], v[76:79]
	v_mfma_f32_16x16x32_bf16 v[68:71], v[200:203], v[192:195], v[68:71]
	v_mfma_f32_16x16x32_bf16 v[64:67], v[208:211], v[192:195], v[64:67]
	s_setprio 0
	s_barrier
; #define PG8_STAGE(bufoff, gbase, voff) do { _Pragma("unroll") for (int _i = 0; _i < 2; ++_i) \
;         __builtin_amdgcn_global_load_lds((const unsigned*)((const char*)(gbase) + (voff)[_i]), (LAS unsigned*)(lds + (bufoff) + ldsw + _i * 8192), 16, 0, 0); } while (0)
; #define PG8_LDA(dst, b, h) do { _Pragma("unroll") for (int m = 0; m < 4; ++m) _Pragma("unroll") for (int k = 0; k < 2; ++k) dst[m][k] = *(const LAS bf16x8*)(lds + PG8_SA(b, h) + aoff + m * 2048 + k * 1024); } while (0)
; #define PG8_BAR __builtin_amdgcn_s_barrier()
; template <class Epi>
; __device__ __forceinline__ void gemm_phase(LAS unsigned char* lds, const Gemm g, const StaticOrder& S, const Epi& E) {
;     ...
;             PG8_LDB(B0, 1, 0); PG8_SCHED; PG8_LDA(At, 1, 0); PG8_STAGE(PG8_SA(0, 1), a2 + hstepA, voffA);
;             PG8_WAIT_L(8); PG8_BAR; PG8_WAIT_L(0); PG8_MMA(0, 0, At, B0); PG8_BAR; PG8_SCHED;
;             PG8_LDB(B1, 1, 1); PG8_STAGE(PG8_SB(1, 0), b3, voffB);
;             PG8_BAR; PG8_WAIT_L(0); PG8_MMA(0, 1, At, B1); PG8_BAR;
;             PG8_LDA(At, 1, 1); PG8_STAGE(PG8_SA(1, 0), a3, voffA);
;             PG8_BAR; PG8_WAIT_L(0); PG8_MMA(1, 0, At, B0); PG8_BAR; PG8_SCHED;
;             PG8_STAGE(PG8_SB(1, 1), b3 + hstepB, voffB);
;             PG8_WAIT_V(6); PG8_BAR; PG8_MMA(1, 1, At, B1); PG8_BAR;
;     __device__ __forceinline__ void operator()(AccRef acc, const Unit& u, int wr, int wc, int fr, int fq) const {
;         const int row0 = u.pm * 256 + wr * 64 + fr, col0 = u.pn * 256 + wc * 32 + 4 * fq;
;         f32x4 sv[2][2], bv[2][2];
; #pragma unroll
;         for (int bj = 0; bj < 2; ++bj)
; #pragma unroll
;             for (int n = 0; n < 2; ++n) {
;                 sv[bj][n] = scale ? *(const f32x4*)(scale + col0 + bj * 128 + n * 16) : (f32x4){1.f, 1.f, 1.f, 1.f};
;                 bv[bj][n] = bias ? *(const f32x4*)(bias + col0 + bj * 128 + n * 16) : (f32x4){0.f, 0.f, 0.f, 0.f}; }
; #pragma unroll
;         for (int ai = 0; ai < 2; ++ai)
; #pragma unroll
;             for (int mh = 0; mh < 2; ++mh) {
;                 f32x4 bs[2][2][2];
; #pragma unroll
;                 for (int m = 0; m < 2; ++m)
; #pragma unroll
;                     for (int bj = 0; bj < 2; ++bj)
; #pragma unroll
;                         for (int n = 0; n < 2; ++n) bs[m][bj][n] = *(const f32x4*)(base + (size_t)(row0 + ai * 128 + (2 * mh + m) * 16) * D + col0 + bj * 128 + n * 16);
	s_nop 1
	ds_read_b128 v[164:167], v150 offset:49152
	ds_read_b128 v[168:171], v150 offset:50176
	ds_read_b128 v[172:175], v150 offset:51200
	ds_read_b128 v[176:179], v150 offset:52224
	ds_read_b128 v[180:183], v150 offset:53248
	ds_read_b128 v[184:187], v150 offset:54272
	ds_read_b128 v[188:191], v150 offset:55296
	ds_read_b128 v[192:195], v150 offset:56320
	s_add_i32 s18, s47, s29
	v_lshl_add_u64 v[254:255], v[144:145], 0, s[10:11]
	s_mov_b32 m0, s18
	s_nop 0
	global_load_lds_dwordx4 v[254:255], off
	v_lshl_add_u64 v[254:255], v[212:213], 0, s[10:11]
	s_add_i32 m0, s18, 0x2000
	s_nop 0
	global_load_lds_dwordx4 v[254:255], off
	s_mov_b32 m0, s36
	v_lshl_add_u64 v[254:255], v[214:215], 0, s[10:11]
	global_load_lds_dwordx4 v[254:255], off
	v_lshl_add_u64 v[144:145], v[216:217], 0, s[10:11]
	s_mov_b32 m0, s37
	s_nop 0
	global_load_lds_dwordx4 v[144:145], off
	s_add_u32 s18, s22, 0xb0080
	s_addc_u32 s19, s23, 0
	s_add_i32 s22, s24, s29
	v_lshl_add_u64 v[254:255], s[18:19], 0, v[128:129]
	s_mov_b32 m0, s22
	s_nop 0
	global_load_lds_dwordx4 v[254:255], off
	v_lshl_add_u64 v[254:255], s[18:19], 0, v[130:131]
	s_add_i32 m0, s22, 0x2000
	s_nop 0
	global_load_lds_dwordx4 v[254:255], off
	s_waitcnt vmcnt(6)
	s_waitcnt lgkmcnt(0)
	s_barrier
	s_setprio 1
	v_mfma_f32_16x16x32_bf16 v[60:63], v[140:143], v[164:167], v[60:63]
	v_mfma_f32_16x16x32_bf16 v[56:59], v[156:159], v[164:167], v[56:59]
	v_mfma_f32_16x16x32_bf16 v[48:51], v[140:143], v[172:175], v[48:51]
	v_mfma_f32_16x16x32_bf16 v[40:43], v[156:159], v[172:175], v[40:43]
	v_mfma_f32_16x16x32_bf16 v[28:31], v[140:143], v[180:183], v[28:31]
	v_mfma_f32_16x16x32_bf16 v[24:27], v[156:159], v[180:183], v[24:27]
	v_mfma_f32_16x16x32_bf16 v[16:19], v[140:143], v[188:191], v[16:19]
	v_mfma_f32_16x16x32_bf16 v[8:11], v[156:159], v[188:191], v[8:11]
	v_mfma_f32_16x16x32_bf16 v[60:63], v[152:155], v[168:171], v[60:63]
	v_mfma_f32_16x16x32_bf16 v[56:59], v[160:163], v[168:171], v[56:59]
	v_mfma_f32_16x16x32_bf16 v[48:51], v[152:155], v[176:179], v[48:51]
	v_mfma_f32_16x16x32_bf16 v[40:43], v[160:163], v[176:179], v[40:43]
	v_mfma_f32_16x16x32_bf16 v[28:31], v[152:155], v[184:187], v[28:31]
	v_mfma_f32_16x16x32_bf16 v[24:27], v[160:163], v[184:187], v[24:27]
	v_mfma_f32_16x16x32_bf16 v[16:19], v[152:155], v[192:195], v[16:19]
	v_mfma_f32_16x16x32_bf16 v[8:11], v[160:163], v[192:195], v[8:11]
	v_mfma_f32_16x16x32_bf16 v[52:55], v[196:199], v[164:167], v[52:55]
	v_mfma_f32_16x16x32_bf16 v[44:47], v[204:207], v[164:167], v[44:47]
	v_mfma_f32_16x16x32_bf16 v[36:39], v[196:199], v[172:175], v[36:39]
	v_mfma_f32_16x16x32_bf16 v[32:35], v[204:207], v[172:175], v[32:35]
	v_mfma_f32_16x16x32_bf16 v[20:23], v[196:199], v[180:183], v[20:23]
	v_mfma_f32_16x16x32_bf16 v[12:15], v[204:207], v[180:183], v[12:15]
	v_mfma_f32_16x16x32_bf16 v[4:7], v[196:199], v[188:191], v[4:7]
	v_mfma_f32_16x16x32_bf16 v[0:3], v[204:207], v[188:191], v[0:3]
	v_mfma_f32_16x16x32_bf16 v[52:55], v[200:203], v[168:171], v[52:55]
	v_mfma_f32_16x16x32_bf16 v[44:47], v[208:211], v[168:171], v[44:47]
	v_mfma_f32_16x16x32_bf16 v[36:39], v[200:203], v[176:179], v[36:39]
	v_mfma_f32_16x16x32_bf16 v[32:35], v[208:211], v[176:179], v[32:35]
	v_mfma_f32_16x16x32_bf16 v[20:23], v[200:203], v[184:187], v[20:23]
	v_mfma_f32_16x16x32_bf16 v[12:15], v[208:211], v[184:187], v[12:15]
	v_mfma_f32_16x16x32_bf16 v[4:7], v[200:203], v[192:195], v[4:7]
	v_mfma_f32_16x16x32_bf16 v[0:3], v[208:211], v[192:195], v[0:3]
	s_setprio 0
	s_add_i32 s46, s46, 2
	s_add_u32 s44, s44, 0x100
	s_addc_u32 s45, s45, 0
	s_cmp_gt_u32 s46, 41
	s_mov_b64 s[18:19], s[20:21]
	s_barrier
	s_cbranch_scc0 .LBB0_2042
	v_lshl_or_b32 v144, s42, 8, v148
	v_lshl_add_u32 v145, s43, 8, v146
	v_lshlrev_b32_e32 v144, 2, v144
	v_lshl_add_u32 v145, v145, 12, v144
	v_add_u32_e32 v216, 0x10000, v145
	v_add_u32_e32 v217, 0x20000, v145
	v_add_u32_e32 v218, 0x30000, v145
	v_add_u32_e32 v232, 0x80000, v145
	v_add_u32_e32 v233, 0x90000, v145
	v_add_u32_e32 v235, 0xa0000, v145
	v_add_u32_e32 v253, 0xb0000, v145
	s_and_b64 vcc, exec, s[0:1]
	s_mov_b32 s42, s40
	s_mov_b32 s43, s41
	s_mov_b64 s[20:21], s[6:7]
	s_mov_b64 s[18:19], s[4:5]
	global_load_dwordx4 v[140:143], v145, s[52:53]
	global_load_dwordx4 v[152:155], v145, s[52:53] offset:64
	global_load_dwordx4 v[156:159], v145, s[52:53] offset:512
	global_load_dwordx4 v[160:163], v145, s[52:53] offset:576
	global_load_dwordx4 v[164:167], v216, s[52:53]
	global_load_dwordx4 v[168:171], v216, s[52:53] offset:64
	global_load_dwordx4 v[172:175], v216, s[52:53] offset:512
	global_load_dwordx4 v[176:179], v216, s[52:53] offset:576
	global_load_dwordx4 v[180:183], v217, s[52:53]
	global_load_dwordx4 v[184:187], v217, s[52:53] offset:64
	global_load_dwordx4 v[188:191], v217, s[52:53] offset:512
	global_load_dwordx4 v[192:195], v217, s[52:53] offset:576
	global_load_dwordx4 v[196:199], v218, s[52:53]
	global_load_dwordx4 v[200:203], v218, s[52:53] offset:64
	global_load_dwordx4 v[204:207], v218, s[52:53] offset:512
	global_load_dwordx4 v[208:211], v218, s[52:53] offset:576
	global_load_dwordx4 v[212:215], v232, s[52:53]
	global_load_dwordx4 v[220:223], v232, s[52:53] offset:64
	global_load_dwordx4 v[224:227], v232, s[52:53] offset:512
	global_load_dwordx4 v[228:231], v232, s[52:53] offset:576
	global_load_dwordx4 v[236:239], v233, s[52:53]
	global_load_dwordx4 v[240:243], v233, s[52:53] offset:64
	global_load_dwordx4 v[244:247], v233, s[52:53] offset:512
	global_load_dwordx4 v[248:251], v233, s[52:53] offset:576
	v_pk_add_f32 v[124:125], v[124:125], 0 op_sel_hi:[1,0]
	v_pk_add_f32 v[126:127], v[126:127], 0 op_sel_hi:[1,0]
	v_pk_add_f32 v[120:121], v[120:121], 0 op_sel_hi:[1,0]
;     __device__ __forceinline__ void operator()(AccRef acc, const Unit& u, int wr, int wc, int fr, int fq) const {
;     ...
;                         for (int n = 0; n < 2; ++n) bs[m][bj][n] = *(const f32x4*)(base + (size_t)(row0 + ai * 128 + (2 * mh + m) * 16) * D + col0 + bj * 128 + n * 16);
; #pragma unroll
;                 for (int m = 0; m < 2; ++m)
; #pragma unroll
;                     for (int bj = 0; bj < 2; ++bj)
; #pragma unroll
;                         for (int n = 0; n < 2; ++n) *(f32x4*)(out + (size_t)(row0 + ai * 128 + (2 * mh + m) * 16) * D + col0 + bj * 128 + n * 16) = bs[m][bj][n] + sv[bj][n] * (acc[ai][bj][2 * mh + m][n] + bv[bj][n]);
;                 asm volatile("" ::: "memory"); }
	v_pk_add_f32 v[122:123], v[122:123], 0 op_sel_hi:[1,0]
	v_pk_add_f32 v[116:117], v[116:117], 0 op_sel_hi:[1,0]
	v_pk_add_f32 v[118:119], v[118:119], 0 op_sel_hi:[1,0]
	v_pk_add_f32 v[108:109], v[108:109], 0 op_sel_hi:[1,0]
	v_pk_add_f32 v[110:111], v[110:111], 0 op_sel_hi:[1,0]
	v_pk_add_f32 v[112:113], v[112:113], 0 op_sel_hi:[1,0]
	v_pk_add_f32 v[114:115], v[114:115], 0 op_sel_hi:[1,0]
	v_pk_add_f32 v[104:105], v[104:105], 0 op_sel_hi:[1,0]
	v_pk_add_f32 v[106:107], v[106:107], 0 op_sel_hi:[1,0]
	v_pk_add_f32 v[100:101], v[100:101], 0 op_sel_hi:[1,0]
	v_pk_add_f32 v[102:103], v[102:103], 0 op_sel_hi:[1,0]
	v_pk_add_f32 v[96:97], v[96:97], 0 op_sel_hi:[1,0]
	v_pk_add_f32 v[98:99], v[98:99], 0 op_sel_hi:[1,0]
	v_pk_add_f32 v[92:93], v[92:93], 0 op_sel_hi:[1,0]
	v_pk_add_f32 v[94:95], v[94:95], 0 op_sel_hi:[1,0]
	v_pk_add_f32 v[88:89], v[88:89], 0 op_sel_hi:[1,0]
	v_pk_add_f32 v[90:91], v[90:91], 0 op_sel_hi:[1,0]
	v_pk_add_f32 v[84:85], v[84:85], 0 op_sel_hi:[1,0]
	v_pk_add_f32 v[86:87], v[86:87], 0 op_sel_hi:[1,0]
	v_pk_add_f32 v[76:77], v[76:77], 0 op_sel_hi:[1,0]
	v_pk_add_f32 v[78:79], v[78:79], 0 op_sel_hi:[1,0]
	v_pk_add_f32 v[80:81], v[80:81], 0 op_sel_hi:[1,0]
	v_pk_add_f32 v[82:83], v[82:83], 0 op_sel_hi:[1,0]
	v_pk_add_f32 v[72:73], v[72:73], 0 op_sel_hi:[1,0]
	v_pk_add_f32 v[74:75], v[74:75], 0 op_sel_hi:[1,0]
	v_pk_add_f32 v[68:69], v[68:69], 0 op_sel_hi:[1,0]
	v_pk_add_f32 v[70:71], v[70:71], 0 op_sel_hi:[1,0]
	v_pk_add_f32 v[64:65], v[64:65], 0 op_sel_hi:[1,0]
	v_pk_add_f32 v[66:67], v[66:67], 0 op_sel_hi:[1,0]
	v_pk_add_f32 v[60:61], v[60:61], 0 op_sel_hi:[1,0]
	v_pk_add_f32 v[62:63], v[62:63], 0 op_sel_hi:[1,0]
	v_pk_add_f32 v[56:57], v[56:57], 0 op_sel_hi:[1,0]
	v_pk_add_f32 v[58:59], v[58:59], 0 op_sel_hi:[1,0]
	v_pk_add_f32 v[52:53], v[52:53], 0 op_sel_hi:[1,0]
	v_pk_add_f32 v[54:55], v[54:55], 0 op_sel_hi:[1,0]
	v_pk_add_f32 v[44:45], v[44:45], 0 op_sel_hi:[1,0]
	v_pk_add_f32 v[46:47], v[46:47], 0 op_sel_hi:[1,0]
	v_pk_add_f32 v[48:49], v[48:49], 0 op_sel_hi:[1,0]
	v_pk_add_f32 v[50:51], v[50:51], 0 op_sel_hi:[1,0]
	v_pk_add_f32 v[40:41], v[40:41], 0 op_sel_hi:[1,0]
	v_pk_add_f32 v[42:43], v[42:43], 0 op_sel_hi:[1,0]
	v_pk_add_f32 v[36:37], v[36:37], 0 op_sel_hi:[1,0]
	v_pk_add_f32 v[38:39], v[38:39], 0 op_sel_hi:[1,0]
	v_pk_add_f32 v[32:33], v[32:33], 0 op_sel_hi:[1,0]
	v_pk_add_f32 v[34:35], v[34:35], 0 op_sel_hi:[1,0]
	v_pk_add_f32 v[28:29], v[28:29], 0 op_sel_hi:[1,0]
	v_pk_add_f32 v[30:31], v[30:31], 0 op_sel_hi:[1,0]
	v_pk_add_f32 v[24:25], v[24:25], 0 op_sel_hi:[1,0]
	v_pk_add_f32 v[26:27], v[26:27], 0 op_sel_hi:[1,0]
	v_pk_add_f32 v[20:21], v[20:21], 0 op_sel_hi:[1,0]
	v_pk_add_f32 v[22:23], v[22:23], 0 op_sel_hi:[1,0]
	v_pk_add_f32 v[12:13], v[12:13], 0 op_sel_hi:[1,0]
	v_pk_add_f32 v[14:15], v[14:15], 0 op_sel_hi:[1,0]
	v_pk_add_f32 v[16:17], v[16:17], 0 op_sel_hi:[1,0]
	v_pk_add_f32 v[18:19], v[18:19], 0 op_sel_hi:[1,0]
	v_pk_add_f32 v[8:9], v[8:9], 0 op_sel_hi:[1,0]
	v_pk_add_f32 v[10:11], v[10:11], 0 op_sel_hi:[1,0]
	v_pk_add_f32 v[4:5], v[4:5], 0 op_sel_hi:[1,0]
	v_pk_add_f32 v[6:7], v[6:7], 0 op_sel_hi:[1,0]
	v_pk_add_f32 v[0:1], v[0:1], 0 op_sel_hi:[1,0]
	v_pk_add_f32 v[2:3], v[2:3], 0 op_sel_hi:[1,0]
	s_waitcnt vmcnt(16)
	v_pk_add_f32 v[124:125], v[124:125], v[140:141]
	v_pk_add_f32 v[126:127], v[126:127], v[142:143]
	v_pk_add_f32 v[120:121], v[120:121], v[152:153]
	v_pk_add_f32 v[122:123], v[122:123], v[154:155]
	v_pk_add_f32 v[116:117], v[116:117], v[156:157]
	v_pk_add_f32 v[118:119], v[118:119], v[158:159]
	v_pk_add_f32 v[108:109], v[108:109], v[160:161]
	v_pk_add_f32 v[110:111], v[110:111], v[162:163]
	v_pk_add_f32 v[112:113], v[112:113], v[164:165]
	v_pk_add_f32 v[114:115], v[114:115], v[166:167]
	v_pk_add_f32 v[104:105], v[104:105], v[168:169]
	v_pk_add_f32 v[106:107], v[106:107], v[170:171]
	v_pk_add_f32 v[100:101], v[100:101], v[172:173]
	v_pk_add_f32 v[102:103], v[102:103], v[174:175]
	v_pk_add_f32 v[96:97], v[96:97], v[176:177]
	v_pk_add_f32 v[98:99], v[98:99], v[178:179]
	global_store_dwordx4 v145, v[124:127], s[52:53]
	global_store_dwordx4 v145, v[120:123], s[52:53] offset:64
	global_store_dwordx4 v145, v[116:119], s[52:53] offset:512
	global_store_dwordx4 v145, v[108:111], s[52:53] offset:576
	global_store_dwordx4 v216, v[112:115], s[52:53]
	global_store_dwordx4 v216, v[104:107], s[52:53] offset:64
	global_store_dwordx4 v216, v[100:103], s[52:53] offset:512
	global_store_dwordx4 v216, v[96:99], s[52:53] offset:576
	global_load_dwordx4 v[140:143], v235, s[52:53]
	global_load_dwordx4 v[152:155], v235, s[52:53] offset:64
	global_load_dwordx4 v[156:159], v235, s[52:53] offset:512
	global_load_dwordx4 v[160:163], v235, s[52:53] offset:576
	global_load_dwordx4 v[164:167], v253, s[52:53]
	global_load_dwordx4 v[168:171], v253, s[52:53] offset:64
	global_load_dwordx4 v[172:175], v253, s[52:53] offset:512
	global_load_dwordx4 v[176:179], v253, s[52:53] offset:576
	s_waitcnt vmcnt(24)
;     __device__ __forceinline__ void operator()(AccRef acc, const Unit& u, int wr, int wc, int fr, int fq) const {
;     ...
;                         for (int n = 0; n < 2; ++n) bs[m][bj][n] = *(const f32x4*)(base + (size_t)(row0 + ai * 128 + (2 * mh + m) * 16) * D + col0 + bj * 128 + n * 16);
; #pragma unroll
;                 for (int m = 0; m < 2; ++m)
; #pragma unroll
;                     for (int bj = 0; bj < 2; ++bj)
; #pragma unroll
;                         for (int n = 0; n < 2; ++n) *(f32x4*)(out + (size_t)(row0 + ai * 128 + (2 * mh + m) * 16) * D + col0 + bj * 128 + n * 16) = bs[m][bj][n] + sv[bj][n] * (acc[ai][bj][2 * mh + m][n] + bv[bj][n]);
;                 asm volatile("" ::: "memory"); }
	v_pk_add_f32 v[92:93], v[92:93], v[180:181]
	v_pk_add_f32 v[94:95], v[94:95], v[182:183]
	v_pk_add_f32 v[88:89], v[88:89], v[184:185]
	v_pk_add_f32 v[90:91], v[90:91], v[186:187]
	v_pk_add_f32 v[84:85], v[84:85], v[188:189]
	v_pk_add_f32 v[86:87], v[86:87], v[190:191]
	v_pk_add_f32 v[76:77], v[76:77], v[192:193]
	v_pk_add_f32 v[78:79], v[78:79], v[194:195]
	v_pk_add_f32 v[80:81], v[80:81], v[196:197]
	v_pk_add_f32 v[82:83], v[82:83], v[198:199]
	v_pk_add_f32 v[72:73], v[72:73], v[200:201]
	v_pk_add_f32 v[74:75], v[74:75], v[202:203]
	v_pk_add_f32 v[68:69], v[68:69], v[204:205]
	v_pk_add_f32 v[70:71], v[70:71], v[206:207]
	v_pk_add_f32 v[64:65], v[64:65], v[208:209]
	v_pk_add_f32 v[66:67], v[66:67], v[210:211]
	global_store_dwordx4 v217, v[92:95], s[52:53]
	global_store_dwordx4 v217, v[88:91], s[52:53] offset:64
	global_store_dwordx4 v217, v[84:87], s[52:53] offset:512
	global_store_dwordx4 v217, v[76:79], s[52:53] offset:576
	global_store_dwordx4 v218, v[80:83], s[52:53]
	global_store_dwordx4 v218, v[72:75], s[52:53] offset:64
	global_store_dwordx4 v218, v[68:71], s[52:53] offset:512
	global_store_dwordx4 v218, v[64:67], s[52:53] offset:576
	s_waitcnt vmcnt(24)
	v_pk_add_f32 v[60:61], v[60:61], v[212:213]
	v_pk_add_f32 v[62:63], v[62:63], v[214:215]
	v_pk_add_f32 v[56:57], v[56:57], v[220:221]
	v_pk_add_f32 v[58:59], v[58:59], v[222:223]
	v_pk_add_f32 v[52:53], v[52:53], v[224:225]
	v_pk_add_f32 v[54:55], v[54:55], v[226:227]
	v_pk_add_f32 v[44:45], v[44:45], v[228:229]
	v_pk_add_f32 v[46:47], v[46:47], v[230:231]
	v_pk_add_f32 v[48:49], v[48:49], v[236:237]
	v_pk_add_f32 v[50:51], v[50:51], v[238:239]
	v_pk_add_f32 v[40:41], v[40:41], v[240:241]
	v_pk_add_f32 v[42:43], v[42:43], v[242:243]
	v_pk_add_f32 v[36:37], v[36:37], v[244:245]
	v_pk_add_f32 v[38:39], v[38:39], v[246:247]
	v_pk_add_f32 v[32:33], v[32:33], v[248:249]
	v_pk_add_f32 v[34:35], v[34:35], v[250:251]
	global_store_dwordx4 v232, v[60:63], s[52:53]
	global_store_dwordx4 v232, v[56:59], s[52:53] offset:64
	global_store_dwordx4 v232, v[52:55], s[52:53] offset:512
	global_store_dwordx4 v232, v[44:47], s[52:53] offset:576
	global_store_dwordx4 v233, v[48:51], s[52:53]
	global_store_dwordx4 v233, v[40:43], s[52:53] offset:64
	global_store_dwordx4 v233, v[36:39], s[52:53] offset:512
	global_store_dwordx4 v233, v[32:35], s[52:53] offset:576
	s_waitcnt vmcnt(16)
	v_pk_add_f32 v[28:29], v[28:29], v[140:141]
	v_pk_add_f32 v[30:31], v[30:31], v[142:143]
	v_pk_add_f32 v[24:25], v[24:25], v[152:153]
	v_pk_add_f32 v[26:27], v[26:27], v[154:155]
	v_pk_add_f32 v[20:21], v[20:21], v[156:157]
	v_pk_add_f32 v[22:23], v[22:23], v[158:159]
	v_pk_add_f32 v[12:13], v[12:13], v[160:161]
	v_pk_add_f32 v[14:15], v[14:15], v[162:163]
	v_pk_add_f32 v[16:17], v[16:17], v[164:165]
	v_pk_add_f32 v[18:19], v[18:19], v[166:167]
	v_pk_add_f32 v[8:9], v[8:9], v[168:169]
	v_pk_add_f32 v[10:11], v[10:11], v[170:171]
	v_pk_add_f32 v[4:5], v[4:5], v[172:173]
	v_pk_add_f32 v[6:7], v[6:7], v[174:175]
	v_pk_add_f32 v[0:1], v[0:1], v[176:177]
	v_pk_add_f32 v[2:3], v[2:3], v[178:179]
	global_store_dwordx4 v235, v[28:31], s[52:53]
	global_store_dwordx4 v235, v[24:27], s[52:53] offset:64
	global_store_dwordx4 v235, v[20:23], s[52:53] offset:512
	global_store_dwordx4 v235, v[12:15], s[52:53] offset:576
	global_store_dwordx4 v253, v[16:19], s[52:53]
	global_store_dwordx4 v253, v[8:11], s[52:53] offset:64
	global_store_dwordx4 v253, v[4:7], s[52:53] offset:512
	global_store_dwordx4 v253, v[0:3], s[52:53] offset:576
	s_cbranch_vccz .LBB0_2031
	s_waitcnt vmcnt(0)
	s_cmpk_gt_u32 s26, 0xff
	s_cbranch_scc1 .LBB0_2046
	s_barrier
